# MLA loop: grouped V-fragment waits; GEMM K-loops: loop-carried SALU moved in front of the loop-back barrier
# baseline (speedup 1.0000x reference)
; #define PG8_STAGE(bufoff, gbase, voff) do { _Pragma("unroll") for (int _i = 0; _i < 2; ++_i) \
;         __builtin_amdgcn_global_load_lds((const unsigned*)((const char*)(gbase) + (voff)[_i]), (PG8_LAS unsigned*)(lds + (bufoff) + ldsw + _i * 8192), 16, 0, 0); } while (0)
; #define PG8_LDA(dst, b, h) do { _Pragma("unroll") for (int m = 0; m < 4; ++m) _Pragma("unroll") for (int k = 0; k < 2; ++k) dst[m][k] = *(const PG8_LAS bf16x8*)(lds + PG8_SA(b, h) + aoff + m * 2048 + k * 1024); } while (0)
; #define PG8_LDB(dst, b, h) do { _Pragma("unroll") for (int n = 0; n < 2; ++n) _Pragma("unroll") for (int k = 0; k < 2; ++k) dst[n][k] = *(const PG8_LAS bf16x8*)(lds + PG8_SB(b, h) + boff + n * 2048 + k * 1024); } while (0)
; #define PG8_MMA(ai, bj, At, Bt) do { __builtin_amdgcn_s_setprio(1); _Pragma("unroll") for (int m = 0; m < 4; ++m) _Pragma("unroll") for (int n = 0; n < 2; ++n) _Pragma("unroll") for (int k = 0; k < 2; ++k) \
;         acc[ai][bj][m][n] = __builtin_amdgcn_mfma_f32_16x16x32_bf16(Bt[n][k], At[m][k], acc[ai][bj][m][n], 0, 0, 0); __builtin_amdgcn_s_setprio(0); } while (0)
; #define PG8_WAIT_V(n) asm volatile("s_waitcnt vmcnt(" #n ")" ::: "memory")
; #define PG8_WAIT_L(n) asm volatile("s_waitcnt lgkmcnt(" #n ")" ::: "memory")
; #define PG8_BAR __builtin_amdgcn_s_barrier()
; #define PG8_SCHED __builtin_amdgcn_sched_barrier(0)
; template <class Epi, class Sched, bool ALIGN_EPI = false, bool SP2 = false>
; __device__ __forceinline__ void gemm_phase(PG8_LAS unsigned char* lds, const Gemm g, const Sched& S, const Epi& E) {
;     ...
;             PG8_LDB(B0, 0, 0); PG8_LDB(B1, 0, 1); PG8_SCHED; PG8_LDA(At, 0, 0); PG8_STAGE(PG8_SA(1, 1), a1 + hstep, voffA);
;             PG8_WAIT_V(8); PG8_WAIT_L(0); PG8_BAR; PG8_MMA(0, 0, At, B0); PG8_MMA(0, 1, At, B1); PG8_BAR; PG8_SCHED;
;             PG8_LDA(At, 0, 1); PG8_STAGE(PG8_SB(0, 0), b2, voffB); PG8_STAGE(PG8_SB(0, 1), b2 + hstep, voffB); PG8_STAGE(PG8_SA(0, 0), a2, voffA);
.LBB0_291:
	ds_read_b128 v[170:173], v166
	ds_read_b128 v[174:177], v166 offset:1024
	ds_read_b128 v[182:185], v166 offset:2048
	ds_read_b128 v[186:189], v166 offset:3072
	ds_read_b128 v[190:193], v167
	ds_read_b128 v[194:197], v167 offset:1024
	ds_read_b128 v[198:201], v167 offset:2048
	ds_read_b128 v[202:205], v167 offset:3072
	s_add_i32 s73, s46, 2
	s_add_u32 s74, s44, 0x80
	s_addc_u32 s47, s45, 0
	s_cmp_eq_u32 s61, s46
	s_cselect_b32 s46, s6, s74
	s_cselect_b32 s47, s7, s47
	s_cselect_b32 s75, s43, s72
	s_cselect_b32 s74, s42, s71
	v_lshl_add_u64 v[156:157], s[44:45], 0, v[138:139]
	s_add_i32 m0, s53, 0xc000
	ds_read_b128 v[206:209], v168
	ds_read_b128 v[210:213], v168 offset:1024
	ds_read_b128 v[214:217], v168 offset:2048
	ds_read_b128 v[218:221], v168 offset:3072
	ds_read_b128 v[222:225], v168 offset:4096
	ds_read_b128 v[226:229], v168 offset:5120
	ds_read_b128 v[230:233], v168 offset:6144
	ds_read_b128 v[234:237], v168 offset:7168
	global_load_lds_dwordx4 v[156:157], off
	v_lshl_add_u64 v[156:157], s[44:45], 0, v[136:137]
	s_add_i32 m0, s53, 0xe000
	s_nop 0
	global_load_lds_dwordx4 v[156:157], off
	s_waitcnt vmcnt(8)
	s_waitcnt lgkmcnt(0)
	s_barrier
	s_setprio 1
	s_waitcnt lgkmcnt(0)
	v_mfma_f32_16x16x32_bf16 v[124:127], v[170:173], v[206:209], v[124:127]
	v_mfma_f32_16x16x32_bf16 v[116:119], v[182:185], v[206:209], v[116:119]
	v_mfma_f32_16x16x32_bf16 v[108:111], v[170:173], v[214:217], v[108:111]
	v_mfma_f32_16x16x32_bf16 v[100:103], v[182:185], v[214:217], v[100:103]
	v_mfma_f32_16x16x32_bf16 v[92:95], v[170:173], v[222:225], v[92:95]
	v_mfma_f32_16x16x32_bf16 v[84:87], v[182:185], v[222:225], v[84:87]
	v_mfma_f32_16x16x32_bf16 v[76:79], v[170:173], v[230:233], v[76:79]
	v_mfma_f32_16x16x32_bf16 v[68:71], v[182:185], v[230:233], v[68:71]
	v_mfma_f32_16x16x32_bf16 v[124:127], v[174:177], v[210:213], v[124:127]
	v_mfma_f32_16x16x32_bf16 v[116:119], v[186:189], v[210:213], v[116:119]
	v_mfma_f32_16x16x32_bf16 v[108:111], v[174:177], v[218:221], v[108:111]
	v_mfma_f32_16x16x32_bf16 v[100:103], v[186:189], v[218:221], v[100:103]
	v_mfma_f32_16x16x32_bf16 v[92:95], v[174:177], v[226:229], v[92:95]
	v_mfma_f32_16x16x32_bf16 v[84:87], v[186:189], v[226:229], v[84:87]
	v_mfma_f32_16x16x32_bf16 v[76:79], v[174:177], v[234:237], v[76:79]
	v_mfma_f32_16x16x32_bf16 v[68:71], v[186:189], v[234:237], v[68:71]
	s_setprio 0
	s_setprio 1
	v_mfma_f32_16x16x32_bf16 v[120:123], v[190:193], v[206:209], v[120:123]
	v_mfma_f32_16x16x32_bf16 v[112:115], v[198:201], v[206:209], v[112:115]
	v_mfma_f32_16x16x32_bf16 v[104:107], v[190:193], v[214:217], v[104:107]
	v_mfma_f32_16x16x32_bf16 v[96:99], v[198:201], v[214:217], v[96:99]
	v_mfma_f32_16x16x32_bf16 v[88:91], v[190:193], v[222:225], v[88:91]
	v_mfma_f32_16x16x32_bf16 v[80:83], v[198:201], v[222:225], v[80:83]
	v_mfma_f32_16x16x32_bf16 v[72:75], v[190:193], v[230:233], v[72:75]
	v_mfma_f32_16x16x32_bf16 v[64:67], v[198:201], v[230:233], v[64:67]
	v_mfma_f32_16x16x32_bf16 v[120:123], v[194:197], v[210:213], v[120:123]
	v_mfma_f32_16x16x32_bf16 v[112:115], v[202:205], v[210:213], v[112:115]
	v_mfma_f32_16x16x32_bf16 v[104:107], v[194:197], v[218:221], v[104:107]
	v_mfma_f32_16x16x32_bf16 v[96:99], v[202:205], v[218:221], v[96:99]
	v_mfma_f32_16x16x32_bf16 v[88:91], v[194:197], v[226:229], v[88:91]
	v_mfma_f32_16x16x32_bf16 v[80:83], v[202:205], v[226:229], v[80:83]
	v_mfma_f32_16x16x32_bf16 v[72:75], v[194:197], v[234:237], v[72:75]
	v_mfma_f32_16x16x32_bf16 v[64:67], v[202:205], v[234:237], v[64:67]
	s_setprio 0
	s_barrier
	s_add_i32 s76, s64, s50
	v_lshl_add_u64 v[156:157], s[74:75], 0, v[132:133]
	s_mov_b32 m0, s76
	ds_read_b128 v[206:209], v168 offset:16384
	ds_read_b128 v[210:213], v168 offset:17408
	ds_read_b128 v[214:217], v168 offset:18432
	ds_read_b128 v[218:221], v168 offset:19456
	ds_read_b128 v[222:225], v168 offset:20480
	ds_read_b128 v[226:229], v168 offset:21504
	ds_read_b128 v[230:233], v168 offset:22528
	ds_read_b128 v[234:237], v168 offset:23552
	global_load_lds_dwordx4 v[156:157], off
	s_add_i32 m0, s76, 0x2000
	v_lshl_add_u64 v[238:239], s[74:75], 0, v[128:129]
	s_add_u32 s74, s74, s12
	s_addc_u32 s75, s75, s13
	s_add_i32 s76, s65, s50
	global_load_lds_dwordx4 v[238:239], off
	v_lshl_add_u64 v[240:241], s[74:75], 0, v[132:133]
	s_mov_b32 m0, s76
	v_lshl_add_u64 v[242:243], s[74:75], 0, v[128:129]
	global_load_lds_dwordx4 v[240:241], off
	s_add_i32 m0, s76, 0x2000
	v_lshl_add_u64 v[244:245], s[46:47], 0, v[134:135]
	global_load_lds_dwordx4 v[242:243], off
	s_mov_b32 m0, s53
	v_lshl_add_u64 v[246:247], s[46:47], 0, v[130:131]
	global_load_lds_dwordx4 v[244:245], off
	s_mov_b32 m0, s54
	s_nop 0
	global_load_lds_dwordx4 v[246:247], off
	s_waitcnt vmcnt(8)
	s_waitcnt lgkmcnt(0)
	s_barrier
; #define PG8_STAGE(bufoff, gbase, voff) do { _Pragma("unroll") for (int _i = 0; _i < 2; ++_i) \
;         __builtin_amdgcn_global_load_lds((const unsigned*)((const char*)(gbase) + (voff)[_i]), (PG8_LAS unsigned*)(lds + (bufoff) + ldsw + _i * 8192), 16, 0, 0); } while (0)
; #define PG8_LDA(dst, b, h) do { _Pragma("unroll") for (int m = 0; m < 4; ++m) _Pragma("unroll") for (int k = 0; k < 2; ++k) dst[m][k] = *(const PG8_LAS bf16x8*)(lds + PG8_SA(b, h) + aoff + m * 2048 + k * 1024); } while (0)
; #define PG8_LDB(dst, b, h) do { _Pragma("unroll") for (int n = 0; n < 2; ++n) _Pragma("unroll") for (int k = 0; k < 2; ++k) dst[n][k] = *(const PG8_LAS bf16x8*)(lds + PG8_SB(b, h) + boff + n * 2048 + k * 1024); } while (0)
; #define PG8_MMA(ai, bj, At, Bt) do { __builtin_amdgcn_s_setprio(1); _Pragma("unroll") for (int m = 0; m < 4; ++m) _Pragma("unroll") for (int n = 0; n < 2; ++n) _Pragma("unroll") for (int k = 0; k < 2; ++k) \
;         acc[ai][bj][m][n] = __builtin_amdgcn_mfma_f32_16x16x32_bf16(Bt[n][k], At[m][k], acc[ai][bj][m][n], 0, 0, 0); __builtin_amdgcn_s_setprio(0); } while (0)
; #define PG8_WAIT_V(n) asm volatile("s_waitcnt vmcnt(" #n ")" ::: "memory")
; #define PG8_WAIT_L(n) asm volatile("s_waitcnt lgkmcnt(" #n ")" ::: "memory")
; #define PG8_BAR __builtin_amdgcn_s_barrier()
; #define PG8_SCHED __builtin_amdgcn_sched_barrier(0)
; template <class Epi, class Sched, bool ALIGN_EPI = false, bool SP2 = false>
; __device__ __forceinline__ void gemm_phase(PG8_LAS unsigned char* lds, const Gemm g, const Sched& S, const Epi& E) {
;     ...
;             PG8_WAIT_V(8); PG8_WAIT_L(0); PG8_BAR; PG8_MMA(1, 0, At, B0); PG8_MMA(1, 1, At, B1); PG8_BAR; PG8_SCHED;
;             PG8_LDB(B0, 1, 0); PG8_LDB(B1, 1, 1); PG8_SCHED; PG8_LDA(At, 1, 0); PG8_STAGE(PG8_SA(0, 1), a2 + hstep, voffA);
;             PG8_WAIT_V(8); PG8_WAIT_L(0); PG8_BAR; PG8_MMA(0, 0, At, B0); PG8_MMA(0, 1, At, B1); PG8_BAR; PG8_SCHED;
	s_setprio 1
	s_waitcnt lgkmcnt(0)
	v_mfma_f32_16x16x32_bf16 v[60:63], v[170:173], v[206:209], v[60:63]
	v_mfma_f32_16x16x32_bf16 v[52:55], v[182:185], v[206:209], v[52:55]
	v_mfma_f32_16x16x32_bf16 v[44:47], v[170:173], v[214:217], v[44:47]
	v_mfma_f32_16x16x32_bf16 v[36:39], v[182:185], v[214:217], v[36:39]
	v_mfma_f32_16x16x32_bf16 v[28:31], v[170:173], v[222:225], v[28:31]
	v_mfma_f32_16x16x32_bf16 v[20:23], v[182:185], v[222:225], v[20:23]
	v_mfma_f32_16x16x32_bf16 v[12:15], v[170:173], v[230:233], v[12:15]
	v_mfma_f32_16x16x32_bf16 v[4:7], v[182:185], v[230:233], v[4:7]
	v_mfma_f32_16x16x32_bf16 v[60:63], v[174:177], v[210:213], v[60:63]
	v_mfma_f32_16x16x32_bf16 v[52:55], v[186:189], v[210:213], v[52:55]
	v_mfma_f32_16x16x32_bf16 v[44:47], v[174:177], v[218:221], v[44:47]
	v_mfma_f32_16x16x32_bf16 v[36:39], v[186:189], v[218:221], v[36:39]
	v_mfma_f32_16x16x32_bf16 v[28:31], v[174:177], v[226:229], v[28:31]
	v_mfma_f32_16x16x32_bf16 v[20:23], v[186:189], v[226:229], v[20:23]
	v_mfma_f32_16x16x32_bf16 v[12:15], v[174:177], v[234:237], v[12:15]
	v_mfma_f32_16x16x32_bf16 v[4:7], v[186:189], v[234:237], v[4:7]
	s_setprio 0
	s_setprio 1
	v_mfma_f32_16x16x32_bf16 v[56:59], v[190:193], v[206:209], v[56:59]
	v_mfma_f32_16x16x32_bf16 v[48:51], v[198:201], v[206:209], v[48:51]
	v_mfma_f32_16x16x32_bf16 v[40:43], v[190:193], v[214:217], v[40:43]
	v_mfma_f32_16x16x32_bf16 v[32:35], v[198:201], v[214:217], v[32:35]
	v_mfma_f32_16x16x32_bf16 v[24:27], v[190:193], v[222:225], v[24:27]
	v_mfma_f32_16x16x32_bf16 v[16:19], v[198:201], v[222:225], v[16:19]
	v_mfma_f32_16x16x32_bf16 v[8:11], v[190:193], v[230:233], v[8:11]
	v_mfma_f32_16x16x32_bf16 v[0:3], v[198:201], v[230:233], v[0:3]
	v_mfma_f32_16x16x32_bf16 v[56:59], v[194:197], v[210:213], v[56:59]
	v_mfma_f32_16x16x32_bf16 v[48:51], v[202:205], v[210:213], v[48:51]
	v_mfma_f32_16x16x32_bf16 v[40:43], v[194:197], v[218:221], v[40:43]
	v_mfma_f32_16x16x32_bf16 v[32:35], v[202:205], v[218:221], v[32:35]
	v_mfma_f32_16x16x32_bf16 v[24:27], v[194:197], v[226:229], v[24:27]
	v_mfma_f32_16x16x32_bf16 v[16:19], v[202:205], v[226:229], v[16:19]
	v_mfma_f32_16x16x32_bf16 v[8:11], v[194:197], v[234:237], v[8:11]
	v_mfma_f32_16x16x32_bf16 v[0:3], v[202:205], v[234:237], v[0:3]
	s_setprio 0
	s_barrier
	s_add_i32 s74, 0, 0x18000
	v_add_u32_e32 v169, s74, v149
	s_add_i32 s75, 0, 0x1c000
	ds_read_b128 v[170:173], v169
	ds_read_b128 v[174:177], v169 offset:1024
	ds_read_b128 v[182:185], v169 offset:2048
	ds_read_b128 v[186:189], v169 offset:3072
	v_add_u32_e32 v169, s75, v149
	ds_read_b128 v[190:193], v169
	ds_read_b128 v[194:197], v169 offset:1024
	ds_read_b128 v[198:201], v169 offset:2048
	ds_read_b128 v[202:205], v169 offset:3072
	s_add_u32 s46, s46, s12
	s_addc_u32 s47, s47, s13
	s_mov_b32 m0, s55
	v_lshl_add_u64 v[248:249], s[46:47], 0, v[134:135]
	ds_read_b128 v[206:209], v168 offset:32768
	ds_read_b128 v[210:213], v168 offset:33792
	ds_read_b128 v[214:217], v168 offset:34816
	ds_read_b128 v[218:221], v168 offset:35840
	ds_read_b128 v[222:225], v168 offset:36864
	ds_read_b128 v[226:229], v168 offset:37888
	ds_read_b128 v[230:233], v168 offset:38912
	ds_read_b128 v[234:237], v168 offset:39936
	global_load_lds_dwordx4 v[248:249], off
	v_lshl_add_u64 v[248:249], s[46:47], 0, v[130:131]
	s_mov_b32 m0, s56
	s_nop 0
	global_load_lds_dwordx4 v[248:249], off
	s_waitcnt vmcnt(8)
	s_waitcnt lgkmcnt(0)
	s_barrier
	s_setprio 1
	s_waitcnt lgkmcnt(0)
	v_mfma_f32_16x16x32_bf16 v[124:127], v[170:173], v[206:209], v[124:127]
	v_mfma_f32_16x16x32_bf16 v[116:119], v[182:185], v[206:209], v[116:119]
	v_mfma_f32_16x16x32_bf16 v[108:111], v[170:173], v[214:217], v[108:111]
	v_mfma_f32_16x16x32_bf16 v[100:103], v[182:185], v[214:217], v[100:103]
	v_mfma_f32_16x16x32_bf16 v[92:95], v[170:173], v[222:225], v[92:95]
	v_mfma_f32_16x16x32_bf16 v[84:87], v[182:185], v[222:225], v[84:87]
	v_mfma_f32_16x16x32_bf16 v[76:79], v[170:173], v[230:233], v[76:79]
	v_mfma_f32_16x16x32_bf16 v[68:71], v[182:185], v[230:233], v[68:71]
	v_mfma_f32_16x16x32_bf16 v[124:127], v[174:177], v[210:213], v[124:127]
	v_mfma_f32_16x16x32_bf16 v[116:119], v[186:189], v[210:213], v[116:119]
	v_mfma_f32_16x16x32_bf16 v[108:111], v[174:177], v[218:221], v[108:111]
	v_mfma_f32_16x16x32_bf16 v[100:103], v[186:189], v[218:221], v[100:103]
	v_mfma_f32_16x16x32_bf16 v[92:95], v[174:177], v[226:229], v[92:95]
	v_mfma_f32_16x16x32_bf16 v[84:87], v[186:189], v[226:229], v[84:87]
	v_mfma_f32_16x16x32_bf16 v[76:79], v[174:177], v[234:237], v[76:79]
	v_mfma_f32_16x16x32_bf16 v[68:71], v[186:189], v[234:237], v[68:71]
	s_setprio 0
	s_setprio 1
	v_mfma_f32_16x16x32_bf16 v[120:123], v[190:193], v[206:209], v[120:123]
	v_mfma_f32_16x16x32_bf16 v[112:115], v[198:201], v[206:209], v[112:115]
	v_mfma_f32_16x16x32_bf16 v[104:107], v[190:193], v[214:217], v[104:107]
	v_mfma_f32_16x16x32_bf16 v[96:99], v[198:201], v[214:217], v[96:99]
	v_mfma_f32_16x16x32_bf16 v[88:91], v[190:193], v[222:225], v[88:91]
	v_mfma_f32_16x16x32_bf16 v[80:83], v[198:201], v[222:225], v[80:83]
	v_mfma_f32_16x16x32_bf16 v[72:75], v[190:193], v[230:233], v[72:75]
	v_mfma_f32_16x16x32_bf16 v[64:67], v[198:201], v[230:233], v[64:67]
	v_mfma_f32_16x16x32_bf16 v[120:123], v[194:197], v[210:213], v[120:123]
	v_mfma_f32_16x16x32_bf16 v[112:115], v[202:205], v[210:213], v[112:115]
	v_mfma_f32_16x16x32_bf16 v[104:107], v[194:197], v[218:221], v[104:107]
	v_mfma_f32_16x16x32_bf16 v[96:99], v[202:205], v[218:221], v[96:99]
	v_mfma_f32_16x16x32_bf16 v[88:91], v[194:197], v[226:229], v[88:91]
	v_mfma_f32_16x16x32_bf16 v[80:83], v[202:205], v[226:229], v[80:83]
	v_mfma_f32_16x16x32_bf16 v[72:75], v[194:197], v[234:237], v[72:75]
	v_mfma_f32_16x16x32_bf16 v[64:67], v[202:205], v[234:237], v[64:67]
	s_setprio 0
	s_barrier
; #define PG8_STAGE(bufoff, gbase, voff) do { _Pragma("unroll") for (int _i = 0; _i < 2; ++_i) \
;         __builtin_amdgcn_global_load_lds((const unsigned*)((const char*)(gbase) + (voff)[_i]), (PG8_LAS unsigned*)(lds + (bufoff) + ldsw + _i * 8192), 16, 0, 0); } while (0)
; #define PG8_LDA(dst, b, h) do { _Pragma("unroll") for (int m = 0; m < 4; ++m) _Pragma("unroll") for (int k = 0; k < 2; ++k) dst[m][k] = *(const PG8_LAS bf16x8*)(lds + PG8_SA(b, h) + aoff + m * 2048 + k * 1024); } while (0)
; #define PG8_MMA(ai, bj, At, Bt) do { __builtin_amdgcn_s_setprio(1); _Pragma("unroll") for (int m = 0; m < 4; ++m) _Pragma("unroll") for (int n = 0; n < 2; ++n) _Pragma("unroll") for (int k = 0; k < 2; ++k) \
;         acc[ai][bj][m][n] = __builtin_amdgcn_mfma_f32_16x16x32_bf16(Bt[n][k], At[m][k], acc[ai][bj][m][n], 0, 0, 0); __builtin_amdgcn_s_setprio(0); } while (0)
; #define PG8_WAIT_V(n) asm volatile("s_waitcnt vmcnt(" #n ")" ::: "memory")
; #define PG8_WAIT_L(n) asm volatile("s_waitcnt lgkmcnt(" #n ")" ::: "memory")
; #define PG8_BAR __builtin_amdgcn_s_barrier()
; #define PG8_SCHED __builtin_amdgcn_sched_barrier(0)
; template <class Epi, class Sched, bool ALIGN_EPI = false, bool SP2 = false>
; __device__ __forceinline__ void gemm_phase(PG8_LAS unsigned char* lds, const Gemm g, const Sched& S, const Epi& E) {
;     ...
;         for (int t = 0; t < nt; t += 2) {
;             const bool last = (t == nt - 2);
;             const char* a1 = cA + (size_t)(t + 1) * kstep;
;             const char* a2 = last ? nA : cA + (size_t)(t + 2) * kstep; const char* b2 = last ? nB : cB + (size_t)(t + 2) * kstep;
;             const char* a3 = a2 + kstep; const char* b3 = b2 + kstep;
;     ...
;             PG8_LDA(At, 1, 1); PG8_STAGE(PG8_SB(1, 0), b3, voffB); PG8_STAGE(PG8_SB(1, 1), b3 + hstep, voffB); PG8_STAGE(PG8_SA(1, 0), a3, voffA);
;             PG8_WAIT_V(8); PG8_WAIT_L(0); PG8_BAR; PG8_MMA(1, 0, At, B0); PG8_MMA(1, 1, At, B1); PG8_BAR; PG8_SCHED;
	s_add_i32 s46, s74, s50
	v_lshl_add_u64 v[156:157], v[156:157], 0, s[30:31]
	s_mov_b32 m0, s46
	ds_read_b128 v[206:209], v168 offset:49152
	ds_read_b128 v[210:213], v168 offset:50176
	ds_read_b128 v[214:217], v168 offset:51200
	ds_read_b128 v[218:221], v168 offset:52224
	ds_read_b128 v[222:225], v168 offset:53248
	ds_read_b128 v[226:229], v168 offset:54272
	ds_read_b128 v[230:233], v168 offset:55296
	ds_read_b128 v[234:237], v168 offset:56320
	global_load_lds_dwordx4 v[156:157], off
	v_lshl_add_u64 v[156:157], v[238:239], 0, s[30:31]
	s_add_i32 m0, s46, 0x2000
	s_add_i32 s46, s75, s50
	global_load_lds_dwordx4 v[156:157], off
	v_lshl_add_u64 v[156:157], v[240:241], 0, s[30:31]
	s_mov_b32 m0, s46
	s_nop 0
	global_load_lds_dwordx4 v[156:157], off
	v_lshl_add_u64 v[156:157], v[242:243], 0, s[30:31]
	s_add_i32 m0, s46, 0x2000
	s_nop 0
	global_load_lds_dwordx4 v[156:157], off
	v_lshl_add_u64 v[156:157], v[244:245], 0, s[30:31]
	s_mov_b32 m0, s58
	s_nop 0
	global_load_lds_dwordx4 v[156:157], off
	v_lshl_add_u64 v[156:157], v[246:247], 0, s[30:31]
	s_mov_b32 m0, s59
	s_nop 0
	global_load_lds_dwordx4 v[156:157], off
	s_waitcnt vmcnt(8)
	s_waitcnt lgkmcnt(0)
	s_barrier
	s_setprio 1
	s_waitcnt lgkmcnt(0)
	v_mfma_f32_16x16x32_bf16 v[60:63], v[170:173], v[206:209], v[60:63]
	v_mfma_f32_16x16x32_bf16 v[52:55], v[182:185], v[206:209], v[52:55]
	v_mfma_f32_16x16x32_bf16 v[44:47], v[170:173], v[214:217], v[44:47]
	v_mfma_f32_16x16x32_bf16 v[36:39], v[182:185], v[214:217], v[36:39]
	v_mfma_f32_16x16x32_bf16 v[28:31], v[170:173], v[222:225], v[28:31]
	v_mfma_f32_16x16x32_bf16 v[20:23], v[182:185], v[222:225], v[20:23]
	v_mfma_f32_16x16x32_bf16 v[12:15], v[170:173], v[230:233], v[12:15]
	v_mfma_f32_16x16x32_bf16 v[4:7], v[182:185], v[230:233], v[4:7]
	v_mfma_f32_16x16x32_bf16 v[60:63], v[174:177], v[210:213], v[60:63]
	v_mfma_f32_16x16x32_bf16 v[52:55], v[186:189], v[210:213], v[52:55]
	v_mfma_f32_16x16x32_bf16 v[44:47], v[174:177], v[218:221], v[44:47]
	v_mfma_f32_16x16x32_bf16 v[36:39], v[186:189], v[218:221], v[36:39]
	v_mfma_f32_16x16x32_bf16 v[28:31], v[174:177], v[226:229], v[28:31]
	v_mfma_f32_16x16x32_bf16 v[20:23], v[186:189], v[226:229], v[20:23]
	v_mfma_f32_16x16x32_bf16 v[12:15], v[174:177], v[234:237], v[12:15]
	v_mfma_f32_16x16x32_bf16 v[4:7], v[186:189], v[234:237], v[4:7]
	s_setprio 0
	s_setprio 1
	v_mfma_f32_16x16x32_bf16 v[56:59], v[190:193], v[206:209], v[56:59]
	v_mfma_f32_16x16x32_bf16 v[48:51], v[198:201], v[206:209], v[48:51]
	v_mfma_f32_16x16x32_bf16 v[40:43], v[190:193], v[214:217], v[40:43]
	v_mfma_f32_16x16x32_bf16 v[32:35], v[198:201], v[214:217], v[32:35]
	v_mfma_f32_16x16x32_bf16 v[24:27], v[190:193], v[222:225], v[24:27]
	v_mfma_f32_16x16x32_bf16 v[16:19], v[198:201], v[222:225], v[16:19]
	v_mfma_f32_16x16x32_bf16 v[8:11], v[190:193], v[230:233], v[8:11]
	v_mfma_f32_16x16x32_bf16 v[0:3], v[198:201], v[230:233], v[0:3]
	v_mfma_f32_16x16x32_bf16 v[56:59], v[194:197], v[210:213], v[56:59]
	v_mfma_f32_16x16x32_bf16 v[48:51], v[202:205], v[210:213], v[48:51]
	v_mfma_f32_16x16x32_bf16 v[40:43], v[194:197], v[218:221], v[40:43]
	v_mfma_f32_16x16x32_bf16 v[32:35], v[202:205], v[218:221], v[32:35]
	v_mfma_f32_16x16x32_bf16 v[24:27], v[194:197], v[226:229], v[24:27]
	v_mfma_f32_16x16x32_bf16 v[16:19], v[202:205], v[226:229], v[16:19]
	v_mfma_f32_16x16x32_bf16 v[8:11], v[194:197], v[234:237], v[8:11]
	v_mfma_f32_16x16x32_bf16 v[0:3], v[202:205], v[234:237], v[0:3]
	s_setprio 0
	s_add_u32 s71, s71, 0x100
	s_addc_u32 s72, s72, 0
	s_add_u32 s44, s44, 0x100
	s_addc_u32 s45, s45, 0
	s_cmp_ge_i32 s73, s60
	s_mov_b32 s46, s73
	s_barrier
	s_cbranch_scc0 .LBB0_291

; #define PG8_STAGE(bufoff, gbase, voff) do { _Pragma("unroll") for (int _i = 0; _i < 2; ++_i) \
;         __builtin_amdgcn_global_load_lds((const unsigned*)((const char*)(gbase) + (voff)[_i]), (PG8_LAS unsigned*)(lds + (bufoff) + ldsw + _i * 8192), 16, 0, 0); } while (0)
; #define PG8_LDA(dst, b, h) do { _Pragma("unroll") for (int m = 0; m < 4; ++m) _Pragma("unroll") for (int k = 0; k < 2; ++k) dst[m][k] = *(const PG8_LAS bf16x8*)(lds + PG8_SA(b, h) + aoff + m * 2048 + k * 1024); } while (0)
; #define PG8_LDB(dst, b, h) do { _Pragma("unroll") for (int n = 0; n < 2; ++n) _Pragma("unroll") for (int k = 0; k < 2; ++k) dst[n][k] = *(const PG8_LAS bf16x8*)(lds + PG8_SB(b, h) + boff + n * 2048 + k * 1024); } while (0)
; #define PG8_MMA(ai, bj, At, Bt) do { __builtin_amdgcn_s_setprio(1); _Pragma("unroll") for (int m = 0; m < 4; ++m) _Pragma("unroll") for (int n = 0; n < 2; ++n) _Pragma("unroll") for (int k = 0; k < 2; ++k) \
;         acc[ai][bj][m][n] = __builtin_amdgcn_mfma_f32_16x16x32_bf16(Bt[n][k], At[m][k], acc[ai][bj][m][n], 0, 0, 0); __builtin_amdgcn_s_setprio(0); } while (0)
; #define PG8_WAIT_V(n) asm volatile("s_waitcnt vmcnt(" #n ")" ::: "memory")
; #define PG8_WAIT_L(n) asm volatile("s_waitcnt lgkmcnt(" #n ")" ::: "memory")
; #define PG8_BAR __builtin_amdgcn_s_barrier()
; #define PG8_SCHED __builtin_amdgcn_sched_barrier(0)
; template <class Epi, class Sched, bool ALIGN_EPI = false, bool SP2 = false>
; __device__ __forceinline__ void gemm_phase(PG8_LAS unsigned char* lds, const Gemm g, const Sched& S, const Epi& E) {
;     ...
;             PG8_LDB(B0, 0, 0); PG8_LDB(B1, 0, 1); PG8_SCHED; PG8_LDA(At, 0, 0); PG8_STAGE(PG8_SA(1, 1), a1 + hstep, voffA);
;             PG8_WAIT_V(8); PG8_WAIT_L(0); PG8_BAR; PG8_MMA(0, 0, At, B0); PG8_MMA(0, 1, At, B1); PG8_BAR; PG8_SCHED;
;             PG8_LDA(At, 0, 1); PG8_STAGE(PG8_SB(0, 0), b2, voffB); PG8_STAGE(PG8_SB(0, 1), b2 + hstep, voffB); PG8_STAGE(PG8_SA(0, 0), a2, voffA);
.LBB0_387:
	v_add_u32_e32 v5, s66, v164
	ds_read_b128 v[166:169], v5
	ds_read_b128 v[170:173], v5 offset:1024
	ds_read_b128 v[174:177], v5 offset:2048
	ds_read_b128 v[182:185], v5 offset:3072
	v_add_u32_e32 v5, s67, v164
	ds_read_b128 v[186:189], v5
	ds_read_b128 v[190:193], v5 offset:1024
	ds_read_b128 v[194:197], v5 offset:2048
	ds_read_b128 v[198:201], v5 offset:3072
	s_add_i32 s74, s48, 2
	s_add_u32 s75, s46, 0x80
	s_addc_u32 s49, s47, 0
	s_cmp_eq_u32 s65, s48
	s_cselect_b32 s48, s10, s75
	s_cselect_b32 s49, s11, s49
	s_cselect_b32 s77, s45, s73
	s_cselect_b32 s76, s44, s72
	v_lshl_add_u64 v[6:7], s[46:47], 0, v[158:159]
	s_add_i32 m0, s57, 0xc000
	ds_read_b128 v[202:205], v165
	ds_read_b128 v[206:209], v165 offset:1024
	ds_read_b128 v[210:213], v165 offset:2048
	ds_read_b128 v[214:217], v165 offset:3072
	ds_read_b128 v[218:221], v165 offset:4096
	ds_read_b128 v[222:225], v165 offset:5120
	ds_read_b128 v[226:229], v165 offset:6144
	ds_read_b128 v[230:233], v165 offset:7168
	global_load_lds_dwordx4 v[6:7], off
	v_lshl_add_u64 v[6:7], s[46:47], 0, v[156:157]
	s_add_i32 m0, s57, 0xe000
	s_nop 0
	global_load_lds_dwordx4 v[6:7], off
	s_waitcnt vmcnt(8)
	s_waitcnt lgkmcnt(0)
	s_barrier
	s_setprio 1
	s_waitcnt lgkmcnt(0)
	v_mfma_f32_16x16x32_bf16 v[92:95], v[166:169], v[202:205], v[92:95]
	v_mfma_f32_16x16x32_bf16 v[60:63], v[174:177], v[202:205], v[60:63]
	v_mfma_f32_16x16x32_bf16 v[100:103], v[166:169], v[210:213], v[100:103]
	v_mfma_f32_16x16x32_bf16 v[68:71], v[174:177], v[210:213], v[68:71]
	v_mfma_f32_16x16x32_bf16 v[108:111], v[166:169], v[218:221], v[108:111]
	v_mfma_f32_16x16x32_bf16 v[72:75], v[174:177], v[218:221], v[72:75]
	v_mfma_f32_16x16x32_bf16 v[112:115], v[166:169], v[226:229], v[112:115]
	v_mfma_f32_16x16x32_bf16 v[80:83], v[174:177], v[226:229], v[80:83]
	v_mfma_f32_16x16x32_bf16 v[92:95], v[170:173], v[206:209], v[92:95]
	v_mfma_f32_16x16x32_bf16 v[60:63], v[182:185], v[206:209], v[60:63]
	v_mfma_f32_16x16x32_bf16 v[100:103], v[170:173], v[214:217], v[100:103]
	v_mfma_f32_16x16x32_bf16 v[68:71], v[182:185], v[214:217], v[68:71]
	v_mfma_f32_16x16x32_bf16 v[108:111], v[170:173], v[222:225], v[108:111]
	v_mfma_f32_16x16x32_bf16 v[72:75], v[182:185], v[222:225], v[72:75]
	v_mfma_f32_16x16x32_bf16 v[112:115], v[170:173], v[230:233], v[112:115]
	v_mfma_f32_16x16x32_bf16 v[80:83], v[182:185], v[230:233], v[80:83]
	s_setprio 0
	s_setprio 1
	v_mfma_f32_16x16x32_bf16 v[28:31], v[186:189], v[202:205], v[28:31]
	v_mfma_f32_16x16x32_bf16 v[132:135], v[194:197], v[202:205], v[132:135]
	v_mfma_f32_16x16x32_bf16 v[36:39], v[186:189], v[210:213], v[36:39]
	v_mfma_f32_16x16x32_bf16 v[6:9], v[194:197], v[210:213], v[8:11]
	v_mfma_f32_16x16x32_bf16 v[40:43], v[186:189], v[218:221], v[40:43]
	v_mfma_f32_16x16x32_bf16 v[10:13], v[194:197], v[218:221], v[12:15]
	v_mfma_f32_16x16x32_bf16 v[48:51], v[186:189], v[226:229], v[48:51]
	v_mfma_f32_16x16x32_bf16 v[16:19], v[194:197], v[226:229], v[16:19]
	v_mfma_f32_16x16x32_bf16 v[28:31], v[190:193], v[206:209], v[28:31]
	v_mfma_f32_16x16x32_bf16 v[132:135], v[198:201], v[206:209], v[132:135]
	v_mfma_f32_16x16x32_bf16 v[36:39], v[190:193], v[214:217], v[36:39]
	v_mfma_f32_16x16x32_bf16 v[6:9], v[198:201], v[214:217], v[6:9]
	v_mfma_f32_16x16x32_bf16 v[40:43], v[190:193], v[222:225], v[40:43]
	v_mfma_f32_16x16x32_bf16 v[12:15], v[198:201], v[222:225], v[10:13]
	v_mfma_f32_16x16x32_bf16 v[48:51], v[190:193], v[230:233], v[48:51]
	v_mfma_f32_16x16x32_bf16 v[16:19], v[198:201], v[230:233], v[16:19]
	s_setprio 0
	s_barrier
	s_add_i32 s75, s66, s56
	v_lshl_add_u64 v[234:235], s[76:77], 0, v[136:137]
	s_mov_b32 m0, s75
	ds_read_b128 v[202:205], v165 offset:16384
	ds_read_b128 v[206:209], v165 offset:17408
	ds_read_b128 v[210:213], v165 offset:18432
	ds_read_b128 v[214:217], v165 offset:19456
	ds_read_b128 v[218:221], v165 offset:20480
	ds_read_b128 v[222:225], v165 offset:21504
	ds_read_b128 v[226:229], v165 offset:22528
	ds_read_b128 v[230:233], v165 offset:23552
	global_load_lds_dwordx4 v[234:235], off
	s_add_i32 m0, s75, 0x2000
	v_lshl_add_u64 v[236:237], s[76:77], 0, v[154:155]
	s_add_u32 s76, s76, s16
	s_addc_u32 s77, s77, s17
	s_add_i32 s75, s67, s56
	global_load_lds_dwordx4 v[236:237], off
	v_lshl_add_u64 v[238:239], s[76:77], 0, v[136:137]
	s_mov_b32 m0, s75
	v_lshl_add_u64 v[240:241], s[76:77], 0, v[154:155]
	global_load_lds_dwordx4 v[238:239], off
	s_add_i32 m0, s75, 0x2000
	v_lshl_add_u64 v[242:243], s[48:49], 0, v[136:137]
	global_load_lds_dwordx4 v[240:241], off
	s_mov_b32 m0, s57
	v_lshl_add_u64 v[244:245], s[48:49], 0, v[154:155]
	global_load_lds_dwordx4 v[242:243], off
	s_mov_b32 m0, s58
	s_nop 0
	global_load_lds_dwordx4 v[244:245], off
	s_waitcnt vmcnt(8)
	s_waitcnt lgkmcnt(0)
	s_barrier
; #define PG8_STAGE(bufoff, gbase, voff) do { _Pragma("unroll") for (int _i = 0; _i < 2; ++_i) \
;         __builtin_amdgcn_global_load_lds((const unsigned*)((const char*)(gbase) + (voff)[_i]), (PG8_LAS unsigned*)(lds + (bufoff) + ldsw + _i * 8192), 16, 0, 0); } while (0)
; #define PG8_LDA(dst, b, h) do { _Pragma("unroll") for (int m = 0; m < 4; ++m) _Pragma("unroll") for (int k = 0; k < 2; ++k) dst[m][k] = *(const PG8_LAS bf16x8*)(lds + PG8_SA(b, h) + aoff + m * 2048 + k * 1024); } while (0)
; #define PG8_LDB(dst, b, h) do { _Pragma("unroll") for (int n = 0; n < 2; ++n) _Pragma("unroll") for (int k = 0; k < 2; ++k) dst[n][k] = *(const PG8_LAS bf16x8*)(lds + PG8_SB(b, h) + boff + n * 2048 + k * 1024); } while (0)
; #define PG8_MMA(ai, bj, At, Bt) do { __builtin_amdgcn_s_setprio(1); _Pragma("unroll") for (int m = 0; m < 4; ++m) _Pragma("unroll") for (int n = 0; n < 2; ++n) _Pragma("unroll") for (int k = 0; k < 2; ++k) \
;         acc[ai][bj][m][n] = __builtin_amdgcn_mfma_f32_16x16x32_bf16(Bt[n][k], At[m][k], acc[ai][bj][m][n], 0, 0, 0); __builtin_amdgcn_s_setprio(0); } while (0)
; #define PG8_WAIT_V(n) asm volatile("s_waitcnt vmcnt(" #n ")" ::: "memory")
; #define PG8_WAIT_L(n) asm volatile("s_waitcnt lgkmcnt(" #n ")" ::: "memory")
; #define PG8_BAR __builtin_amdgcn_s_barrier()
; #define PG8_SCHED __builtin_amdgcn_sched_barrier(0)
; template <class Epi, class Sched, bool ALIGN_EPI = false, bool SP2 = false>
; __device__ __forceinline__ void gemm_phase(PG8_LAS unsigned char* lds, const Gemm g, const Sched& S, const Epi& E) {
;     ...
;             PG8_WAIT_V(8); PG8_WAIT_L(0); PG8_BAR; PG8_MMA(1, 0, At, B0); PG8_MMA(1, 1, At, B1); PG8_BAR; PG8_SCHED;
;             PG8_LDB(B0, 1, 0); PG8_LDB(B1, 1, 1); PG8_SCHED; PG8_LDA(At, 1, 0); PG8_STAGE(PG8_SA(0, 1), a2 + hstep, voffA);
;             PG8_WAIT_V(8); PG8_WAIT_L(0); PG8_BAR; PG8_MMA(0, 0, At, B0); PG8_MMA(0, 1, At, B1); PG8_BAR; PG8_SCHED;
	s_setprio 1
	s_waitcnt lgkmcnt(0)
	v_mfma_f32_16x16x32_bf16 v[116:119], v[166:169], v[202:205], v[116:119]
	v_mfma_f32_16x16x32_bf16 v[84:87], v[174:177], v[202:205], v[84:87]
	v_mfma_f32_16x16x32_bf16 v[120:123], v[166:169], v[210:213], v[120:123]
	v_mfma_f32_16x16x32_bf16 v[88:91], v[174:177], v[210:213], v[88:91]
	v_mfma_f32_16x16x32_bf16 v[128:131], v[166:169], v[218:221], v[128:131]
	v_mfma_f32_16x16x32_bf16 v[96:99], v[174:177], v[218:221], v[96:99]
	v_mfma_f32_16x16x32_bf16 v[124:127], v[166:169], v[226:229], v[124:127]
	v_mfma_f32_16x16x32_bf16 v[104:107], v[174:177], v[226:229], v[104:107]
	v_mfma_f32_16x16x32_bf16 v[116:119], v[170:173], v[206:209], v[116:119]
	v_mfma_f32_16x16x32_bf16 v[84:87], v[182:185], v[206:209], v[84:87]
	v_mfma_f32_16x16x32_bf16 v[120:123], v[170:173], v[214:217], v[120:123]
	v_mfma_f32_16x16x32_bf16 v[88:91], v[182:185], v[214:217], v[88:91]
	v_mfma_f32_16x16x32_bf16 v[128:131], v[170:173], v[222:225], v[128:131]
	v_mfma_f32_16x16x32_bf16 v[96:99], v[182:185], v[222:225], v[96:99]
	v_mfma_f32_16x16x32_bf16 v[124:127], v[170:173], v[230:233], v[124:127]
	v_mfma_f32_16x16x32_bf16 v[104:107], v[182:185], v[230:233], v[104:107]
	s_setprio 0
	s_setprio 1
	v_mfma_f32_16x16x32_bf16 v[52:55], v[186:189], v[202:205], v[52:55]
	v_mfma_f32_16x16x32_bf16 v[20:23], v[194:197], v[202:205], v[20:23]
	v_mfma_f32_16x16x32_bf16 v[56:59], v[186:189], v[210:213], v[56:59]
	v_mfma_f32_16x16x32_bf16 v[24:27], v[194:197], v[210:213], v[24:27]
	v_mfma_f32_16x16x32_bf16 v[64:67], v[186:189], v[218:221], v[64:67]
	v_mfma_f32_16x16x32_bf16 v[32:35], v[194:197], v[218:221], v[32:35]
	v_mfma_f32_16x16x32_bf16 v[76:79], v[186:189], v[226:229], v[76:79]
	v_mfma_f32_16x16x32_bf16 v[44:47], v[194:197], v[226:229], v[44:47]
	v_mfma_f32_16x16x32_bf16 v[52:55], v[190:193], v[206:209], v[52:55]
	v_mfma_f32_16x16x32_bf16 v[20:23], v[198:201], v[206:209], v[20:23]
	v_mfma_f32_16x16x32_bf16 v[56:59], v[190:193], v[214:217], v[56:59]
	v_mfma_f32_16x16x32_bf16 v[24:27], v[198:201], v[214:217], v[24:27]
	v_mfma_f32_16x16x32_bf16 v[64:67], v[190:193], v[222:225], v[64:67]
	v_mfma_f32_16x16x32_bf16 v[32:35], v[198:201], v[222:225], v[32:35]
	v_mfma_f32_16x16x32_bf16 v[76:79], v[190:193], v[230:233], v[76:79]
	v_mfma_f32_16x16x32_bf16 v[44:47], v[198:201], v[230:233], v[44:47]
	s_setprio 0
	s_barrier
	s_add_i32 s75, 0, 0x18000
	v_add_u32_e32 v5, s75, v164
	s_add_i32 s76, 0, 0x1c000
	ds_read_b128 v[166:169], v5
	ds_read_b128 v[170:173], v5 offset:1024
	ds_read_b128 v[174:177], v5 offset:2048
	ds_read_b128 v[182:185], v5 offset:3072
	v_add_u32_e32 v5, s76, v164
	ds_read_b128 v[186:189], v5
	ds_read_b128 v[190:193], v5 offset:1024
	ds_read_b128 v[194:197], v5 offset:2048
	ds_read_b128 v[198:201], v5 offset:3072
	s_add_u32 s48, s48, s16
	s_addc_u32 s49, s49, s17
	s_mov_b32 m0, s59
	v_lshl_add_u64 v[10:11], s[48:49], 0, v[136:137]
	ds_read_b128 v[202:205], v165 offset:32768
	ds_read_b128 v[206:209], v165 offset:33792
	ds_read_b128 v[210:213], v165 offset:34816
	ds_read_b128 v[214:217], v165 offset:35840
	ds_read_b128 v[218:221], v165 offset:36864
	ds_read_b128 v[222:225], v165 offset:37888
	ds_read_b128 v[226:229], v165 offset:38912
	ds_read_b128 v[230:233], v165 offset:39936
	global_load_lds_dwordx4 v[10:11], off
	v_lshl_add_u64 v[10:11], s[48:49], 0, v[154:155]
	s_mov_b32 m0, s61
	s_nop 0
	global_load_lds_dwordx4 v[10:11], off
	s_waitcnt vmcnt(8)
	s_waitcnt lgkmcnt(0)
	s_barrier
	s_setprio 1
	s_waitcnt lgkmcnt(0)
	v_mfma_f32_16x16x32_bf16 v[92:95], v[166:169], v[202:205], v[92:95]
	v_mfma_f32_16x16x32_bf16 v[60:63], v[174:177], v[202:205], v[60:63]
	v_mfma_f32_16x16x32_bf16 v[100:103], v[166:169], v[210:213], v[100:103]
	v_mfma_f32_16x16x32_bf16 v[68:71], v[174:177], v[210:213], v[68:71]
	v_mfma_f32_16x16x32_bf16 v[108:111], v[166:169], v[218:221], v[108:111]
	v_mfma_f32_16x16x32_bf16 v[72:75], v[174:177], v[218:221], v[72:75]
	v_mfma_f32_16x16x32_bf16 v[112:115], v[166:169], v[226:229], v[112:115]
	v_mfma_f32_16x16x32_bf16 v[80:83], v[174:177], v[226:229], v[80:83]
	v_mfma_f32_16x16x32_bf16 v[92:95], v[170:173], v[206:209], v[92:95]
	v_mfma_f32_16x16x32_bf16 v[60:63], v[182:185], v[206:209], v[60:63]
	v_mfma_f32_16x16x32_bf16 v[100:103], v[170:173], v[214:217], v[100:103]
	v_mfma_f32_16x16x32_bf16 v[68:71], v[182:185], v[214:217], v[68:71]
	v_mfma_f32_16x16x32_bf16 v[108:111], v[170:173], v[222:225], v[108:111]
	v_mfma_f32_16x16x32_bf16 v[72:75], v[182:185], v[222:225], v[72:75]
	v_mfma_f32_16x16x32_bf16 v[112:115], v[170:173], v[230:233], v[112:115]
	v_mfma_f32_16x16x32_bf16 v[80:83], v[182:185], v[230:233], v[80:83]
	s_setprio 0
	s_setprio 1
	v_mfma_f32_16x16x32_bf16 v[28:31], v[186:189], v[202:205], v[28:31]
	v_mfma_f32_16x16x32_bf16 v[132:135], v[194:197], v[202:205], v[132:135]
	v_mfma_f32_16x16x32_bf16 v[36:39], v[186:189], v[210:213], v[36:39]
	v_mfma_f32_16x16x32_bf16 v[6:9], v[194:197], v[210:213], v[6:9]
	v_mfma_f32_16x16x32_bf16 v[40:43], v[186:189], v[218:221], v[40:43]
	v_mfma_f32_16x16x32_bf16 v[12:15], v[194:197], v[218:221], v[12:15]
	v_mfma_f32_16x16x32_bf16 v[48:51], v[186:189], v[226:229], v[48:51]
	v_mfma_f32_16x16x32_bf16 v[16:19], v[194:197], v[226:229], v[16:19]
	v_mfma_f32_16x16x32_bf16 v[28:31], v[190:193], v[206:209], v[28:31]
	v_mfma_f32_16x16x32_bf16 v[132:135], v[198:201], v[206:209], v[132:135]
	v_mfma_f32_16x16x32_bf16 v[36:39], v[190:193], v[214:217], v[36:39]
	v_mfma_f32_16x16x32_bf16 v[8:11], v[198:201], v[214:217], v[6:9]
	v_mfma_f32_16x16x32_bf16 v[40:43], v[190:193], v[222:225], v[40:43]
	v_mfma_f32_16x16x32_bf16 v[12:15], v[198:201], v[222:225], v[12:15]
	v_mfma_f32_16x16x32_bf16 v[48:51], v[190:193], v[230:233], v[48:51]
	v_mfma_f32_16x16x32_bf16 v[16:19], v[198:201], v[230:233], v[16:19]
	s_setprio 0
	s_barrier
; #define PG8_STAGE(bufoff, gbase, voff) do { _Pragma("unroll") for (int _i = 0; _i < 2; ++_i) \
;         __builtin_amdgcn_global_load_lds((const unsigned*)((const char*)(gbase) + (voff)[_i]), (PG8_LAS unsigned*)(lds + (bufoff) + ldsw + _i * 8192), 16, 0, 0); } while (0)
; #define PG8_LDA(dst, b, h) do { _Pragma("unroll") for (int m = 0; m < 4; ++m) _Pragma("unroll") for (int k = 0; k < 2; ++k) dst[m][k] = *(const PG8_LAS bf16x8*)(lds + PG8_SA(b, h) + aoff + m * 2048 + k * 1024); } while (0)
; #define PG8_MMA(ai, bj, At, Bt) do { __builtin_amdgcn_s_setprio(1); _Pragma("unroll") for (int m = 0; m < 4; ++m) _Pragma("unroll") for (int n = 0; n < 2; ++n) _Pragma("unroll") for (int k = 0; k < 2; ++k) \
;         acc[ai][bj][m][n] = __builtin_amdgcn_mfma_f32_16x16x32_bf16(Bt[n][k], At[m][k], acc[ai][bj][m][n], 0, 0, 0); __builtin_amdgcn_s_setprio(0); } while (0)
; #define PG8_WAIT_V(n) asm volatile("s_waitcnt vmcnt(" #n ")" ::: "memory")
; #define PG8_WAIT_L(n) asm volatile("s_waitcnt lgkmcnt(" #n ")" ::: "memory")
; #define PG8_BAR __builtin_amdgcn_s_barrier()
; #define PG8_SCHED __builtin_amdgcn_sched_barrier(0)
; template <class Epi, class Sched, bool ALIGN_EPI = false, bool SP2 = false>
; __device__ __forceinline__ void gemm_phase(PG8_LAS unsigned char* lds, const Gemm g, const Sched& S, const Epi& E) {
;     ...
;         for (int t = 0; t < nt; t += 2) {
;             const bool last = (t == nt - 2);
;             const char* a1 = cA + (size_t)(t + 1) * kstep;
;             const char* a2 = last ? nA : cA + (size_t)(t + 2) * kstep; const char* b2 = last ? nB : cB + (size_t)(t + 2) * kstep;
;             const char* a3 = a2 + kstep; const char* b3 = b2 + kstep;
;     ...
;             PG8_LDA(At, 1, 1); PG8_STAGE(PG8_SB(1, 0), b3, voffB); PG8_STAGE(PG8_SB(1, 1), b3 + hstep, voffB); PG8_STAGE(PG8_SA(1, 0), a3, voffA);
;             PG8_WAIT_V(8); PG8_WAIT_L(0); PG8_BAR; PG8_MMA(1, 0, At, B0); PG8_MMA(1, 1, At, B1); PG8_BAR; PG8_SCHED;
	s_add_i32 s48, s75, s56
	v_lshl_add_u64 v[6:7], v[234:235], 0, s[40:41]
	s_mov_b32 m0, s48
	ds_read_b128 v[202:205], v165 offset:49152
	ds_read_b128 v[206:209], v165 offset:50176
	ds_read_b128 v[210:213], v165 offset:51200
	ds_read_b128 v[214:217], v165 offset:52224
	ds_read_b128 v[218:221], v165 offset:53248
	ds_read_b128 v[222:225], v165 offset:54272
	ds_read_b128 v[226:229], v165 offset:55296
	ds_read_b128 v[230:233], v165 offset:56320
	global_load_lds_dwordx4 v[6:7], off
	v_lshl_add_u64 v[6:7], v[236:237], 0, s[40:41]
	s_add_i32 m0, s48, 0x2000
	s_add_i32 s48, s76, s56
	global_load_lds_dwordx4 v[6:7], off
	v_lshl_add_u64 v[6:7], v[238:239], 0, s[40:41]
	s_mov_b32 m0, s48
	s_nop 0
	global_load_lds_dwordx4 v[6:7], off
	v_lshl_add_u64 v[6:7], v[240:241], 0, s[40:41]
	s_add_i32 m0, s48, 0x2000
	s_nop 0
	global_load_lds_dwordx4 v[6:7], off
	v_lshl_add_u64 v[6:7], v[242:243], 0, s[40:41]
	s_mov_b32 m0, s62
	s_nop 0
	global_load_lds_dwordx4 v[6:7], off
	v_lshl_add_u64 v[6:7], v[244:245], 0, s[40:41]
	s_mov_b32 m0, s63
	s_nop 0
	global_load_lds_dwordx4 v[6:7], off
	s_waitcnt vmcnt(8)
	s_waitcnt lgkmcnt(0)
	s_barrier
	s_setprio 1
	s_waitcnt lgkmcnt(0)
	v_mfma_f32_16x16x32_bf16 v[116:119], v[166:169], v[202:205], v[116:119]
	v_mfma_f32_16x16x32_bf16 v[84:87], v[174:177], v[202:205], v[84:87]
	v_mfma_f32_16x16x32_bf16 v[120:123], v[166:169], v[210:213], v[120:123]
	v_mfma_f32_16x16x32_bf16 v[88:91], v[174:177], v[210:213], v[88:91]
	v_mfma_f32_16x16x32_bf16 v[128:131], v[166:169], v[218:221], v[128:131]
	v_mfma_f32_16x16x32_bf16 v[96:99], v[174:177], v[218:221], v[96:99]
	v_mfma_f32_16x16x32_bf16 v[124:127], v[166:169], v[226:229], v[124:127]
	v_mfma_f32_16x16x32_bf16 v[104:107], v[174:177], v[226:229], v[104:107]
	v_mfma_f32_16x16x32_bf16 v[116:119], v[170:173], v[206:209], v[116:119]
	v_mfma_f32_16x16x32_bf16 v[84:87], v[182:185], v[206:209], v[84:87]
	v_mfma_f32_16x16x32_bf16 v[120:123], v[170:173], v[214:217], v[120:123]
	v_mfma_f32_16x16x32_bf16 v[88:91], v[182:185], v[214:217], v[88:91]
	v_mfma_f32_16x16x32_bf16 v[128:131], v[170:173], v[222:225], v[128:131]
	v_mfma_f32_16x16x32_bf16 v[96:99], v[182:185], v[222:225], v[96:99]
	v_mfma_f32_16x16x32_bf16 v[124:127], v[170:173], v[230:233], v[124:127]
	v_mfma_f32_16x16x32_bf16 v[104:107], v[182:185], v[230:233], v[104:107]
	s_setprio 0
	s_setprio 1
	v_mfma_f32_16x16x32_bf16 v[52:55], v[186:189], v[202:205], v[52:55]
	v_mfma_f32_16x16x32_bf16 v[20:23], v[194:197], v[202:205], v[20:23]
	v_mfma_f32_16x16x32_bf16 v[56:59], v[186:189], v[210:213], v[56:59]
	v_mfma_f32_16x16x32_bf16 v[24:27], v[194:197], v[210:213], v[24:27]
	v_mfma_f32_16x16x32_bf16 v[64:67], v[186:189], v[218:221], v[64:67]
	v_mfma_f32_16x16x32_bf16 v[32:35], v[194:197], v[218:221], v[32:35]
	v_mfma_f32_16x16x32_bf16 v[76:79], v[186:189], v[226:229], v[76:79]
	v_mfma_f32_16x16x32_bf16 v[44:47], v[194:197], v[226:229], v[44:47]
	v_mfma_f32_16x16x32_bf16 v[52:55], v[190:193], v[206:209], v[52:55]
	v_mfma_f32_16x16x32_bf16 v[20:23], v[198:201], v[206:209], v[20:23]
	v_mfma_f32_16x16x32_bf16 v[56:59], v[190:193], v[214:217], v[56:59]
	v_mfma_f32_16x16x32_bf16 v[24:27], v[198:201], v[214:217], v[24:27]
	v_mfma_f32_16x16x32_bf16 v[64:67], v[190:193], v[222:225], v[64:67]
	v_mfma_f32_16x16x32_bf16 v[32:35], v[198:201], v[222:225], v[32:35]
	v_mfma_f32_16x16x32_bf16 v[76:79], v[190:193], v[230:233], v[76:79]
	v_mfma_f32_16x16x32_bf16 v[44:47], v[198:201], v[230:233], v[44:47]
	s_setprio 0
	s_add_u32 s72, s72, 0x100
	s_addc_u32 s73, s73, 0
	s_add_u32 s46, s46, 0x100
	s_addc_u32 s47, s47, 0
	s_cmp_ge_i32 s74, s64
	s_mov_b32 s48, s74
	s_barrier
	s_cbranch_scc0 .LBB0_387

; #define PG8_STAGE(bufoff, gbase, voff) do { _Pragma("unroll") for (int _i = 0; _i < 2; ++_i) \
;         __builtin_amdgcn_global_load_lds((const unsigned*)((const char*)(gbase) + (voff)[_i]), (PG8_LAS unsigned*)(lds + (bufoff) + ldsw + _i * 8192), 16, 0, 0); } while (0)
; #define PG8_LDA(dst, b, h) do { _Pragma("unroll") for (int m = 0; m < 4; ++m) _Pragma("unroll") for (int k = 0; k < 2; ++k) dst[m][k] = *(const PG8_LAS bf16x8*)(lds + PG8_SA(b, h) + aoff + m * 2048 + k * 1024); } while (0)
; #define PG8_LDB(dst, b, h) do { _Pragma("unroll") for (int n = 0; n < 2; ++n) _Pragma("unroll") for (int k = 0; k < 2; ++k) dst[n][k] = *(const PG8_LAS bf16x8*)(lds + PG8_SB(b, h) + boff + n * 2048 + k * 1024); } while (0)
; #define PG8_MMA(ai, bj, At, Bt) do { __builtin_amdgcn_s_setprio(1); _Pragma("unroll") for (int m = 0; m < 4; ++m) _Pragma("unroll") for (int n = 0; n < 2; ++n) _Pragma("unroll") for (int k = 0; k < 2; ++k) \
;         acc[ai][bj][m][n] = __builtin_amdgcn_mfma_f32_16x16x32_bf16(Bt[n][k], At[m][k], acc[ai][bj][m][n], 0, 0, 0); __builtin_amdgcn_s_setprio(0); } while (0)
; #define PG8_WAIT_V(n) asm volatile("s_waitcnt vmcnt(" #n ")" ::: "memory")
; #define PG8_WAIT_L(n) asm volatile("s_waitcnt lgkmcnt(" #n ")" ::: "memory")
; #define PG8_BAR __builtin_amdgcn_s_barrier()
; #define PG8_SCHED __builtin_amdgcn_sched_barrier(0)
; template <class Epi, class Sched, bool ALIGN_EPI = false, bool SP2 = false>
; __device__ __forceinline__ void gemm_phase(PG8_LAS unsigned char* lds, const Gemm g, const Sched& S, const Epi& E) {
;     ...
;             PG8_LDB(B0, 0, 0); PG8_LDB(B1, 0, 1); PG8_SCHED; PG8_LDA(At, 0, 0); PG8_STAGE(PG8_SA(1, 1), a1 + hstep, voffA);
;             PG8_WAIT_V(8); PG8_WAIT_L(0); PG8_BAR; PG8_MMA(0, 0, At, B0); PG8_MMA(0, 1, At, B1); PG8_BAR; PG8_SCHED;
;             PG8_LDA(At, 0, 1); PG8_STAGE(PG8_SB(0, 0), b2, voffB); PG8_STAGE(PG8_SB(0, 1), b2 + hstep, voffB); PG8_STAGE(PG8_SA(0, 0), a2, voffA);
.LBB0_506:
	ds_read_b128 v[156:159], v164
	ds_read_b128 v[160:163], v164 offset:1024
	ds_read_b128 v[168:171], v164 offset:2048
	ds_read_b128 v[172:175], v164 offset:3072
	ds_read_b128 v[182:185], v165
	ds_read_b128 v[186:189], v165 offset:1024
	ds_read_b128 v[190:193], v165 offset:2048
	ds_read_b128 v[194:197], v165 offset:3072
	s_add_i32 s79, s52, 2
	s_add_u32 s80, s50, 0x80
	s_addc_u32 s53, s51, 0
	s_cmp_eq_u32 s65, s52
	s_cselect_b32 s52, s8, s80
	s_cselect_b32 s53, s9, s53
	s_cselect_b32 s81, s49, s78
	s_cselect_b32 s80, s48, s77
	v_lshl_add_u64 v[176:177], s[50:51], 0, v[138:139]
	s_add_i32 m0, s57, 0xc000
	ds_read_b128 v[198:201], v166
	ds_read_b128 v[202:205], v166 offset:1024
	ds_read_b128 v[206:209], v166 offset:2048
	ds_read_b128 v[210:213], v166 offset:3072
	ds_read_b128 v[214:217], v166 offset:4096
	ds_read_b128 v[218:221], v166 offset:5120
	ds_read_b128 v[222:225], v166 offset:6144
	ds_read_b128 v[226:229], v166 offset:7168
	global_load_lds_dwordx4 v[176:177], off
	v_lshl_add_u64 v[176:177], s[50:51], 0, v[136:137]
	s_add_i32 m0, s57, 0xe000
	s_nop 0
	global_load_lds_dwordx4 v[176:177], off
	s_waitcnt vmcnt(8)
	s_waitcnt lgkmcnt(0)
	s_barrier
	s_setprio 1
	s_waitcnt lgkmcnt(0)
	v_mfma_f32_16x16x32_bf16 v[124:127], v[156:159], v[198:201], v[124:127]
	v_mfma_f32_16x16x32_bf16 v[120:123], v[168:171], v[198:201], v[120:123]
	v_mfma_f32_16x16x32_bf16 v[116:119], v[156:159], v[206:209], v[116:119]
	v_mfma_f32_16x16x32_bf16 v[112:115], v[168:171], v[206:209], v[112:115]
	v_mfma_f32_16x16x32_bf16 v[104:107], v[156:159], v[214:217], v[104:107]
	v_mfma_f32_16x16x32_bf16 v[96:99], v[168:171], v[214:217], v[96:99]
	v_mfma_f32_16x16x32_bf16 v[88:91], v[156:159], v[222:225], v[88:91]
	v_mfma_f32_16x16x32_bf16 v[80:83], v[168:171], v[222:225], v[80:83]
	v_mfma_f32_16x16x32_bf16 v[124:127], v[160:163], v[202:205], v[124:127]
	v_mfma_f32_16x16x32_bf16 v[120:123], v[172:175], v[202:205], v[120:123]
	v_mfma_f32_16x16x32_bf16 v[116:119], v[160:163], v[210:213], v[116:119]
	v_mfma_f32_16x16x32_bf16 v[112:115], v[172:175], v[210:213], v[112:115]
	v_mfma_f32_16x16x32_bf16 v[104:107], v[160:163], v[218:221], v[104:107]
	v_mfma_f32_16x16x32_bf16 v[96:99], v[172:175], v[218:221], v[96:99]
	v_mfma_f32_16x16x32_bf16 v[88:91], v[160:163], v[226:229], v[88:91]
	v_mfma_f32_16x16x32_bf16 v[80:83], v[172:175], v[226:229], v[80:83]
	s_setprio 0
	s_setprio 1
	v_mfma_f32_16x16x32_bf16 v[108:111], v[182:185], v[198:201], v[108:111]
	v_mfma_f32_16x16x32_bf16 v[100:103], v[190:193], v[198:201], v[100:103]
	v_mfma_f32_16x16x32_bf16 v[92:95], v[182:185], v[206:209], v[92:95]
	v_mfma_f32_16x16x32_bf16 v[84:87], v[190:193], v[206:209], v[84:87]
	v_mfma_f32_16x16x32_bf16 v[76:79], v[182:185], v[214:217], v[76:79]
	v_mfma_f32_16x16x32_bf16 v[72:75], v[190:193], v[214:217], v[72:75]
	v_mfma_f32_16x16x32_bf16 v[68:71], v[182:185], v[222:225], v[68:71]
	v_mfma_f32_16x16x32_bf16 v[64:67], v[190:193], v[222:225], v[64:67]
	v_mfma_f32_16x16x32_bf16 v[108:111], v[186:189], v[202:205], v[108:111]
	v_mfma_f32_16x16x32_bf16 v[100:103], v[194:197], v[202:205], v[100:103]
	v_mfma_f32_16x16x32_bf16 v[92:95], v[186:189], v[210:213], v[92:95]
	v_mfma_f32_16x16x32_bf16 v[84:87], v[194:197], v[210:213], v[84:87]
	v_mfma_f32_16x16x32_bf16 v[76:79], v[186:189], v[218:221], v[76:79]
	v_mfma_f32_16x16x32_bf16 v[72:75], v[194:197], v[218:221], v[72:75]
	v_mfma_f32_16x16x32_bf16 v[68:71], v[186:189], v[226:229], v[68:71]
	v_mfma_f32_16x16x32_bf16 v[64:67], v[194:197], v[226:229], v[64:67]
	s_setprio 0
	s_barrier
	s_add_i32 s82, s68, s56
	v_lshl_add_u64 v[176:177], s[80:81], 0, v[130:131]
	s_mov_b32 m0, s82
	ds_read_b128 v[198:201], v166 offset:16384
	ds_read_b128 v[202:205], v166 offset:17408
	ds_read_b128 v[206:209], v166 offset:18432
	ds_read_b128 v[210:213], v166 offset:19456
	ds_read_b128 v[214:217], v166 offset:20480
	ds_read_b128 v[218:221], v166 offset:21504
	ds_read_b128 v[222:225], v166 offset:22528
	ds_read_b128 v[226:229], v166 offset:23552
	global_load_lds_dwordx4 v[176:177], off
	s_add_i32 m0, s82, 0x2000
	v_lshl_add_u64 v[230:231], s[80:81], 0, v[134:135]
	s_add_u32 s80, s80, s10
	s_addc_u32 s81, s81, s11
	s_add_i32 s82, s69, s56
	global_load_lds_dwordx4 v[230:231], off
	v_lshl_add_u64 v[232:233], s[80:81], 0, v[130:131]
	s_mov_b32 m0, s82
	v_lshl_add_u64 v[234:235], s[80:81], 0, v[134:135]
	global_load_lds_dwordx4 v[232:233], off
	s_add_i32 m0, s82, 0x2000
	v_lshl_add_u64 v[236:237], s[52:53], 0, v[128:129]
	global_load_lds_dwordx4 v[234:235], off
	s_mov_b32 m0, s57
	v_lshl_add_u64 v[238:239], s[52:53], 0, v[132:133]
	global_load_lds_dwordx4 v[236:237], off
	s_mov_b32 m0, s58
	s_nop 0
	global_load_lds_dwordx4 v[238:239], off
	s_waitcnt vmcnt(8)
	s_waitcnt lgkmcnt(0)
	s_barrier
; #define PG8_STAGE(bufoff, gbase, voff) do { _Pragma("unroll") for (int _i = 0; _i < 2; ++_i) \
;         __builtin_amdgcn_global_load_lds((const unsigned*)((const char*)(gbase) + (voff)[_i]), (PG8_LAS unsigned*)(lds + (bufoff) + ldsw + _i * 8192), 16, 0, 0); } while (0)
; #define PG8_LDA(dst, b, h) do { _Pragma("unroll") for (int m = 0; m < 4; ++m) _Pragma("unroll") for (int k = 0; k < 2; ++k) dst[m][k] = *(const PG8_LAS bf16x8*)(lds + PG8_SA(b, h) + aoff + m * 2048 + k * 1024); } while (0)
; #define PG8_LDB(dst, b, h) do { _Pragma("unroll") for (int n = 0; n < 2; ++n) _Pragma("unroll") for (int k = 0; k < 2; ++k) dst[n][k] = *(const PG8_LAS bf16x8*)(lds + PG8_SB(b, h) + boff + n * 2048 + k * 1024); } while (0)
; #define PG8_MMA(ai, bj, At, Bt) do { __builtin_amdgcn_s_setprio(1); _Pragma("unroll") for (int m = 0; m < 4; ++m) _Pragma("unroll") for (int n = 0; n < 2; ++n) _Pragma("unroll") for (int k = 0; k < 2; ++k) \
;         acc[ai][bj][m][n] = __builtin_amdgcn_mfma_f32_16x16x32_bf16(Bt[n][k], At[m][k], acc[ai][bj][m][n], 0, 0, 0); __builtin_amdgcn_s_setprio(0); } while (0)
; #define PG8_WAIT_V(n) asm volatile("s_waitcnt vmcnt(" #n ")" ::: "memory")
; #define PG8_WAIT_L(n) asm volatile("s_waitcnt lgkmcnt(" #n ")" ::: "memory")
; #define PG8_BAR __builtin_amdgcn_s_barrier()
; #define PG8_SCHED __builtin_amdgcn_sched_barrier(0)
; template <class Epi, class Sched, bool ALIGN_EPI = false, bool SP2 = false>
; __device__ __forceinline__ void gemm_phase(PG8_LAS unsigned char* lds, const Gemm g, const Sched& S, const Epi& E) {
;     ...
;             PG8_WAIT_V(8); PG8_WAIT_L(0); PG8_BAR; PG8_MMA(1, 0, At, B0); PG8_MMA(1, 1, At, B1); PG8_BAR; PG8_SCHED;
;             PG8_LDB(B0, 1, 0); PG8_LDB(B1, 1, 1); PG8_SCHED; PG8_LDA(At, 1, 0); PG8_STAGE(PG8_SA(0, 1), a2 + hstep, voffA);
;             PG8_WAIT_V(8); PG8_WAIT_L(0); PG8_BAR; PG8_MMA(0, 0, At, B0); PG8_MMA(0, 1, At, B1); PG8_BAR; PG8_SCHED;
	s_setprio 1
	s_waitcnt lgkmcnt(0)
	v_mfma_f32_16x16x32_bf16 v[60:63], v[156:159], v[198:201], v[60:63]
	v_mfma_f32_16x16x32_bf16 v[56:59], v[168:171], v[198:201], v[56:59]
	v_mfma_f32_16x16x32_bf16 v[52:55], v[156:159], v[206:209], v[52:55]
	v_mfma_f32_16x16x32_bf16 v[48:51], v[168:171], v[206:209], v[48:51]
	v_mfma_f32_16x16x32_bf16 v[40:43], v[156:159], v[214:217], v[40:43]
	v_mfma_f32_16x16x32_bf16 v[32:35], v[168:171], v[214:217], v[32:35]
	v_mfma_f32_16x16x32_bf16 v[24:27], v[156:159], v[222:225], v[24:27]
	v_mfma_f32_16x16x32_bf16 v[16:19], v[168:171], v[222:225], v[16:19]
	v_mfma_f32_16x16x32_bf16 v[60:63], v[160:163], v[202:205], v[60:63]
	v_mfma_f32_16x16x32_bf16 v[56:59], v[172:175], v[202:205], v[56:59]
	v_mfma_f32_16x16x32_bf16 v[52:55], v[160:163], v[210:213], v[52:55]
	v_mfma_f32_16x16x32_bf16 v[48:51], v[172:175], v[210:213], v[48:51]
	v_mfma_f32_16x16x32_bf16 v[40:43], v[160:163], v[218:221], v[40:43]
	v_mfma_f32_16x16x32_bf16 v[32:35], v[172:175], v[218:221], v[32:35]
	v_mfma_f32_16x16x32_bf16 v[24:27], v[160:163], v[226:229], v[24:27]
	v_mfma_f32_16x16x32_bf16 v[16:19], v[172:175], v[226:229], v[16:19]
	s_setprio 0
	s_setprio 1
	v_mfma_f32_16x16x32_bf16 v[44:47], v[182:185], v[198:201], v[44:47]
	v_mfma_f32_16x16x32_bf16 v[36:39], v[190:193], v[198:201], v[36:39]
	v_mfma_f32_16x16x32_bf16 v[28:31], v[182:185], v[206:209], v[28:31]
	v_mfma_f32_16x16x32_bf16 v[20:23], v[190:193], v[206:209], v[20:23]
	v_mfma_f32_16x16x32_bf16 v[12:15], v[182:185], v[214:217], v[12:15]
	v_mfma_f32_16x16x32_bf16 v[8:11], v[190:193], v[214:217], v[8:11]
	v_mfma_f32_16x16x32_bf16 v[4:7], v[182:185], v[222:225], v[4:7]
	v_mfma_f32_16x16x32_bf16 v[0:3], v[190:193], v[222:225], v[0:3]
	v_mfma_f32_16x16x32_bf16 v[44:47], v[186:189], v[202:205], v[44:47]
	v_mfma_f32_16x16x32_bf16 v[36:39], v[194:197], v[202:205], v[36:39]
	v_mfma_f32_16x16x32_bf16 v[28:31], v[186:189], v[210:213], v[28:31]
	v_mfma_f32_16x16x32_bf16 v[20:23], v[194:197], v[210:213], v[20:23]
	v_mfma_f32_16x16x32_bf16 v[12:15], v[186:189], v[218:221], v[12:15]
	v_mfma_f32_16x16x32_bf16 v[8:11], v[194:197], v[218:221], v[8:11]
	v_mfma_f32_16x16x32_bf16 v[4:7], v[186:189], v[226:229], v[4:7]
	v_mfma_f32_16x16x32_bf16 v[0:3], v[194:197], v[226:229], v[0:3]
	s_setprio 0
	s_barrier
	s_add_i32 s80, 0, 0x18000
	v_add_u32_e32 v167, s80, v149
	s_add_i32 s81, 0, 0x1c000
	ds_read_b128 v[156:159], v167
	ds_read_b128 v[160:163], v167 offset:1024
	ds_read_b128 v[168:171], v167 offset:2048
	ds_read_b128 v[172:175], v167 offset:3072
	v_add_u32_e32 v167, s81, v149
	ds_read_b128 v[182:185], v167
	ds_read_b128 v[186:189], v167 offset:1024
	ds_read_b128 v[190:193], v167 offset:2048
	ds_read_b128 v[194:197], v167 offset:3072
	s_add_u32 s52, s52, s10
	s_addc_u32 s53, s53, s11
	s_mov_b32 m0, s59
	v_lshl_add_u64 v[240:241], s[52:53], 0, v[128:129]
	ds_read_b128 v[198:201], v166 offset:32768
	ds_read_b128 v[202:205], v166 offset:33792
	ds_read_b128 v[206:209], v166 offset:34816
	ds_read_b128 v[210:213], v166 offset:35840
	ds_read_b128 v[214:217], v166 offset:36864
	ds_read_b128 v[218:221], v166 offset:37888
	ds_read_b128 v[222:225], v166 offset:38912
	ds_read_b128 v[226:229], v166 offset:39936
	global_load_lds_dwordx4 v[240:241], off
	v_lshl_add_u64 v[240:241], s[52:53], 0, v[132:133]
	s_mov_b32 m0, s60
	s_nop 0
	global_load_lds_dwordx4 v[240:241], off
	s_waitcnt vmcnt(8)
	s_waitcnt lgkmcnt(0)
	s_barrier
	s_setprio 1
	s_waitcnt lgkmcnt(0)
	v_mfma_f32_16x16x32_bf16 v[124:127], v[156:159], v[198:201], v[124:127]
	v_mfma_f32_16x16x32_bf16 v[120:123], v[168:171], v[198:201], v[120:123]
	v_mfma_f32_16x16x32_bf16 v[116:119], v[156:159], v[206:209], v[116:119]
	v_mfma_f32_16x16x32_bf16 v[112:115], v[168:171], v[206:209], v[112:115]
	v_mfma_f32_16x16x32_bf16 v[104:107], v[156:159], v[214:217], v[104:107]
	v_mfma_f32_16x16x32_bf16 v[96:99], v[168:171], v[214:217], v[96:99]
	v_mfma_f32_16x16x32_bf16 v[88:91], v[156:159], v[222:225], v[88:91]
	v_mfma_f32_16x16x32_bf16 v[80:83], v[168:171], v[222:225], v[80:83]
	v_mfma_f32_16x16x32_bf16 v[124:127], v[160:163], v[202:205], v[124:127]
	v_mfma_f32_16x16x32_bf16 v[120:123], v[172:175], v[202:205], v[120:123]
	v_mfma_f32_16x16x32_bf16 v[116:119], v[160:163], v[210:213], v[116:119]
	v_mfma_f32_16x16x32_bf16 v[112:115], v[172:175], v[210:213], v[112:115]
	v_mfma_f32_16x16x32_bf16 v[104:107], v[160:163], v[218:221], v[104:107]
	v_mfma_f32_16x16x32_bf16 v[96:99], v[172:175], v[218:221], v[96:99]
	v_mfma_f32_16x16x32_bf16 v[88:91], v[160:163], v[226:229], v[88:91]
	v_mfma_f32_16x16x32_bf16 v[80:83], v[172:175], v[226:229], v[80:83]
	s_setprio 0
	s_setprio 1
	v_mfma_f32_16x16x32_bf16 v[108:111], v[182:185], v[198:201], v[108:111]
	v_mfma_f32_16x16x32_bf16 v[100:103], v[190:193], v[198:201], v[100:103]
	v_mfma_f32_16x16x32_bf16 v[92:95], v[182:185], v[206:209], v[92:95]
	v_mfma_f32_16x16x32_bf16 v[84:87], v[190:193], v[206:209], v[84:87]
	v_mfma_f32_16x16x32_bf16 v[76:79], v[182:185], v[214:217], v[76:79]
	v_mfma_f32_16x16x32_bf16 v[72:75], v[190:193], v[214:217], v[72:75]
	v_mfma_f32_16x16x32_bf16 v[68:71], v[182:185], v[222:225], v[68:71]
	v_mfma_f32_16x16x32_bf16 v[64:67], v[190:193], v[222:225], v[64:67]
	v_mfma_f32_16x16x32_bf16 v[108:111], v[186:189], v[202:205], v[108:111]
	v_mfma_f32_16x16x32_bf16 v[100:103], v[194:197], v[202:205], v[100:103]
	v_mfma_f32_16x16x32_bf16 v[92:95], v[186:189], v[210:213], v[92:95]
	v_mfma_f32_16x16x32_bf16 v[84:87], v[194:197], v[210:213], v[84:87]
	v_mfma_f32_16x16x32_bf16 v[76:79], v[186:189], v[218:221], v[76:79]
	v_mfma_f32_16x16x32_bf16 v[72:75], v[194:197], v[218:221], v[72:75]
	v_mfma_f32_16x16x32_bf16 v[68:71], v[186:189], v[226:229], v[68:71]
	v_mfma_f32_16x16x32_bf16 v[64:67], v[194:197], v[226:229], v[64:67]
	s_setprio 0
	s_barrier
; #define PG8_STAGE(bufoff, gbase, voff) do { _Pragma("unroll") for (int _i = 0; _i < 2; ++_i) \
;         __builtin_amdgcn_global_load_lds((const unsigned*)((const char*)(gbase) + (voff)[_i]), (PG8_LAS unsigned*)(lds + (bufoff) + ldsw + _i * 8192), 16, 0, 0); } while (0)
; #define PG8_LDA(dst, b, h) do { _Pragma("unroll") for (int m = 0; m < 4; ++m) _Pragma("unroll") for (int k = 0; k < 2; ++k) dst[m][k] = *(const PG8_LAS bf16x8*)(lds + PG8_SA(b, h) + aoff + m * 2048 + k * 1024); } while (0)
; #define PG8_MMA(ai, bj, At, Bt) do { __builtin_amdgcn_s_setprio(1); _Pragma("unroll") for (int m = 0; m < 4; ++m) _Pragma("unroll") for (int n = 0; n < 2; ++n) _Pragma("unroll") for (int k = 0; k < 2; ++k) \
;         acc[ai][bj][m][n] = __builtin_amdgcn_mfma_f32_16x16x32_bf16(Bt[n][k], At[m][k], acc[ai][bj][m][n], 0, 0, 0); __builtin_amdgcn_s_setprio(0); } while (0)
; #define PG8_WAIT_V(n) asm volatile("s_waitcnt vmcnt(" #n ")" ::: "memory")
; #define PG8_WAIT_L(n) asm volatile("s_waitcnt lgkmcnt(" #n ")" ::: "memory")
; #define PG8_BAR __builtin_amdgcn_s_barrier()
; #define PG8_SCHED __builtin_amdgcn_sched_barrier(0)
;     __device__ __forceinline__ void operator()(const f32x4 (&acc)[2][2][4][2], const Unit& u, int wr, int wc, int fr, int fq) const {
;     ...
;                 for (int bj = 0; bj < 2; ++bj) { f32x4 v0 = acc[ai][bj][m][0] + bv[bj][0], v1 = acc[ai][bj][m][1] + bv[bj][1];
; template <class Epi, class Sched, bool ALIGN_EPI = false, bool SP2 = false>
; __device__ __forceinline__ void gemm_phase(PG8_LAS unsigned char* lds, const Gemm g, const Sched& S, const Epi& E) {
;     ...
;             PG8_LDA(At, 1, 1); PG8_STAGE(PG8_SB(1, 0), b3, voffB); PG8_STAGE(PG8_SB(1, 1), b3 + hstep, voffB); PG8_STAGE(PG8_SA(1, 0), a3, voffA);
;             PG8_WAIT_V(8); PG8_WAIT_L(0); PG8_BAR; PG8_MMA(1, 0, At, B0); PG8_MMA(1, 1, At, B1); PG8_BAR; PG8_SCHED;
	s_add_i32 s52, s80, s56
	v_lshl_add_u64 v[176:177], v[176:177], 0, s[18:19]
	s_mov_b32 m0, s52
	ds_read_b128 v[198:201], v166 offset:49152
	ds_read_b128 v[202:205], v166 offset:50176
	ds_read_b128 v[206:209], v166 offset:51200
	ds_read_b128 v[210:213], v166 offset:52224
	ds_read_b128 v[214:217], v166 offset:53248
	ds_read_b128 v[218:221], v166 offset:54272
	ds_read_b128 v[222:225], v166 offset:55296
	ds_read_b128 v[226:229], v166 offset:56320
	global_load_lds_dwordx4 v[176:177], off
	v_lshl_add_u64 v[176:177], v[230:231], 0, s[18:19]
	s_add_i32 m0, s52, 0x2000
	s_add_i32 s52, s81, s56
	global_load_lds_dwordx4 v[176:177], off
	v_lshl_add_u64 v[176:177], v[232:233], 0, s[18:19]
	s_mov_b32 m0, s52
	s_nop 0
	global_load_lds_dwordx4 v[176:177], off
	v_lshl_add_u64 v[176:177], v[234:235], 0, s[18:19]
	s_add_i32 m0, s52, 0x2000
	s_nop 0
	global_load_lds_dwordx4 v[176:177], off
	v_lshl_add_u64 v[176:177], v[236:237], 0, s[18:19]
	s_mov_b32 m0, s62
	s_nop 0
	global_load_lds_dwordx4 v[176:177], off
	v_lshl_add_u64 v[176:177], v[238:239], 0, s[18:19]
	s_mov_b32 m0, s63
	s_nop 0
	global_load_lds_dwordx4 v[176:177], off
	s_waitcnt vmcnt(8)
	s_waitcnt lgkmcnt(0)
	s_barrier
	s_setprio 1
	s_waitcnt lgkmcnt(0)
	v_mfma_f32_16x16x32_bf16 v[60:63], v[156:159], v[198:201], v[60:63]
	v_mfma_f32_16x16x32_bf16 v[56:59], v[168:171], v[198:201], v[56:59]
	v_mfma_f32_16x16x32_bf16 v[52:55], v[156:159], v[206:209], v[52:55]
	v_mfma_f32_16x16x32_bf16 v[48:51], v[168:171], v[206:209], v[48:51]
	v_mfma_f32_16x16x32_bf16 v[40:43], v[156:159], v[214:217], v[40:43]
	v_mfma_f32_16x16x32_bf16 v[32:35], v[168:171], v[214:217], v[32:35]
	v_mfma_f32_16x16x32_bf16 v[24:27], v[156:159], v[222:225], v[24:27]
	v_mfma_f32_16x16x32_bf16 v[16:19], v[168:171], v[222:225], v[16:19]
	v_mfma_f32_16x16x32_bf16 v[60:63], v[160:163], v[202:205], v[60:63]
	v_mfma_f32_16x16x32_bf16 v[56:59], v[172:175], v[202:205], v[56:59]
	v_mfma_f32_16x16x32_bf16 v[52:55], v[160:163], v[210:213], v[52:55]
	v_mfma_f32_16x16x32_bf16 v[48:51], v[172:175], v[210:213], v[48:51]
	v_mfma_f32_16x16x32_bf16 v[40:43], v[160:163], v[218:221], v[40:43]
	v_mfma_f32_16x16x32_bf16 v[32:35], v[172:175], v[218:221], v[32:35]
	v_mfma_f32_16x16x32_bf16 v[24:27], v[160:163], v[226:229], v[24:27]
	v_mfma_f32_16x16x32_bf16 v[16:19], v[172:175], v[226:229], v[16:19]
	s_setprio 0
	s_setprio 1
	v_mfma_f32_16x16x32_bf16 v[44:47], v[182:185], v[198:201], v[44:47]
	v_mfma_f32_16x16x32_bf16 v[36:39], v[190:193], v[198:201], v[36:39]
	v_mfma_f32_16x16x32_bf16 v[28:31], v[182:185], v[206:209], v[28:31]
	v_mfma_f32_16x16x32_bf16 v[20:23], v[190:193], v[206:209], v[20:23]
	v_mfma_f32_16x16x32_bf16 v[12:15], v[182:185], v[214:217], v[12:15]
	v_mfma_f32_16x16x32_bf16 v[8:11], v[190:193], v[214:217], v[8:11]
	v_mfma_f32_16x16x32_bf16 v[4:7], v[182:185], v[222:225], v[4:7]
	v_mfma_f32_16x16x32_bf16 v[0:3], v[190:193], v[222:225], v[0:3]
	v_mfma_f32_16x16x32_bf16 v[44:47], v[186:189], v[202:205], v[44:47]
	v_mfma_f32_16x16x32_bf16 v[36:39], v[194:197], v[202:205], v[36:39]
	v_mfma_f32_16x16x32_bf16 v[28:31], v[186:189], v[210:213], v[28:31]
	v_mfma_f32_16x16x32_bf16 v[20:23], v[194:197], v[210:213], v[20:23]
	v_mfma_f32_16x16x32_bf16 v[12:15], v[186:189], v[218:221], v[12:15]
	v_mfma_f32_16x16x32_bf16 v[8:11], v[194:197], v[218:221], v[8:11]
	v_mfma_f32_16x16x32_bf16 v[4:7], v[186:189], v[226:229], v[4:7]
	v_mfma_f32_16x16x32_bf16 v[0:3], v[194:197], v[226:229], v[0:3]
	s_setprio 0
	s_add_u32 s77, s77, 0x100
	s_addc_u32 s78, s78, 0
	s_add_u32 s50, s50, 0x100
	s_addc_u32 s51, s51, 0
	s_cmp_ge_i32 s79, s64
	s_mov_b32 s52, s79
	s_barrier
	s_cbranch_scc0 .LBB0_506
	v_pk_add_f32 v[126:127], v[126:127], 0 op_sel_hi:[1,0]
	v_pk_add_f32 v[124:125], v[124:125], 0 op_sel_hi:[1,0]
	v_pk_add_f32 v[122:123], v[122:123], 0 op_sel_hi:[1,0]
	v_pk_add_f32 v[120:121], v[120:121], 0 op_sel_hi:[1,0]
	v_pk_add_f32 v[156:157], v[110:111], 0 op_sel_hi:[1,0]
	v_pk_add_f32 v[158:159], v[108:109], 0 op_sel_hi:[1,0]
	v_pk_add_f32 v[160:161], v[102:103], 0 op_sel_hi:[1,0]
	v_pk_add_f32 v[162:163], v[100:101], 0 op_sel_hi:[1,0]
	v_pk_add_f32 v[100:101], v[118:119], 0 op_sel_hi:[1,0]
	v_pk_add_f32 v[102:103], v[116:117], 0 op_sel_hi:[1,0]
	v_pk_add_f32 v[108:109], v[114:115], 0 op_sel_hi:[1,0]
	v_pk_add_f32 v[110:111], v[112:113], 0 op_sel_hi:[1,0]
	v_pk_add_f32 v[112:113], v[94:95], 0 op_sel_hi:[1,0]
	v_pk_add_f32 v[114:115], v[92:93], 0 op_sel_hi:[1,0]
	v_pk_add_f32 v[116:117], v[86:87], 0 op_sel_hi:[1,0]
	v_pk_add_f32 v[118:119], v[84:85], 0 op_sel_hi:[1,0]
	v_pk_add_f32 v[84:85], v[106:107], 0 op_sel_hi:[1,0]
	v_pk_add_f32 v[86:87], v[104:105], 0 op_sel_hi:[1,0]
	v_pk_add_f32 v[92:93], v[98:99], 0 op_sel_hi:[1,0]
	v_pk_add_f32 v[94:95], v[96:97], 0 op_sel_hi:[1,0]
	v_pk_add_f32 v[96:97], v[78:79], 0 op_sel_hi:[1,0]
	v_pk_add_f32 v[98:99], v[76:77], 0 op_sel_hi:[1,0]
	v_pk_add_f32 v[104:105], v[74:75], 0 op_sel_hi:[1,0]
	v_pk_add_f32 v[106:107], v[72:73], 0 op_sel_hi:[1,0]
	v_pk_add_f32 v[72:73], v[90:91], 0 op_sel_hi:[1,0]
	v_pk_add_f32 v[74:75], v[88:89], 0 op_sel_hi:[1,0]
	v_pk_add_f32 v[76:77], v[82:83], 0 op_sel_hi:[1,0]
	v_pk_add_f32 v[78:79], v[80:81], 0 op_sel_hi:[1,0]
	v_pk_add_f32 v[70:71], v[70:71], 0 op_sel_hi:[1,0]
	v_pk_add_f32 v[68:69], v[68:69], 0 op_sel_hi:[1,0]
	v_pk_add_f32 v[66:67], v[66:67], 0 op_sel_hi:[1,0]
	v_pk_add_f32 v[64:65], v[64:65], 0 op_sel_hi:[1,0]
	v_pk_add_f32 v[62:63], v[62:63], 0 op_sel_hi:[1,0]
	v_pk_add_f32 v[60:61], v[60:61], 0 op_sel_hi:[1,0]
	v_pk_add_f32 v[58:59], v[58:59], 0 op_sel_hi:[1,0]
	v_pk_add_f32 v[56:57], v[56:57], 0 op_sel_hi:[1,0]
	v_pk_add_f32 v[80:81], v[46:47], 0 op_sel_hi:[1,0]
	v_pk_add_f32 v[82:83], v[44:45], 0 op_sel_hi:[1,0]
	v_pk_add_f32 v[88:89], v[38:39], 0 op_sel_hi:[1,0]
	v_pk_add_f32 v[90:91], v[36:37], 0 op_sel_hi:[1,0]
	v_pk_add_f32 v[36:37], v[54:55], 0 op_sel_hi:[1,0]
	v_pk_add_f32 v[38:39], v[52:53], 0 op_sel_hi:[1,0]
	v_pk_add_f32 v[44:45], v[50:51], 0 op_sel_hi:[1,0]
	v_pk_add_f32 v[46:47], v[48:49], 0 op_sel_hi:[1,0]
	v_pk_add_f32 v[48:49], v[30:31], 0 op_sel_hi:[1,0]
	v_pk_add_f32 v[50:51], v[28:29], 0 op_sel_hi:[1,0]
	v_pk_add_f32 v[52:53], v[22:23], 0 op_sel_hi:[1,0]
	v_pk_add_f32 v[54:55], v[20:21], 0 op_sel_hi:[1,0]
	v_pk_add_f32 v[20:21], v[42:43], 0 op_sel_hi:[1,0]
	v_pk_add_f32 v[22:23], v[40:41], 0 op_sel_hi:[1,0]
	v_pk_add_f32 v[28:29], v[34:35], 0 op_sel_hi:[1,0]
	v_pk_add_f32 v[30:31], v[32:33], 0 op_sel_hi:[1,0]
	v_pk_add_f32 v[32:33], v[14:15], 0 op_sel_hi:[1,0]
	v_pk_add_f32 v[34:35], v[12:13], 0 op_sel_hi:[1,0]
	v_pk_add_f32 v[40:41], v[10:11], 0 op_sel_hi:[1,0]
	v_pk_add_f32 v[42:43], v[8:9], 0 op_sel_hi:[1,0]
	v_pk_add_f32 v[8:9], v[26:27], 0 op_sel_hi:[1,0]
	v_pk_add_f32 v[10:11], v[24:25], 0 op_sel_hi:[1,0]
	v_pk_add_f32 v[12:13], v[18:19], 0 op_sel_hi:[1,0]
	v_pk_add_f32 v[14:15], v[16:17], 0 op_sel_hi:[1,0]
	v_pk_add_f32 v[6:7], v[6:7], 0 op_sel_hi:[1,0]
	v_pk_add_f32 v[4:5], v[4:5], 0 op_sel_hi:[1,0]
	v_pk_add_f32 v[2:3], v[2:3], 0 op_sel_hi:[1,0]
	v_pk_add_f32 v[0:1], v[0:1], 0 op_sel_hi:[1,0]

; #define PG8_STAGE(bufoff, gbase, voff) do { _Pragma("unroll") for (int _i = 0; _i < 2; ++_i) \
;         __builtin_amdgcn_global_load_lds((const unsigned*)((const char*)(gbase) + (voff)[_i]), (PG8_LAS unsigned*)(lds + (bufoff) + ldsw + _i * 8192), 16, 0, 0); } while (0)
; #define PG8_LDA(dst, b, h) do { _Pragma("unroll") for (int m = 0; m < 4; ++m) _Pragma("unroll") for (int k = 0; k < 2; ++k) dst[m][k] = *(const PG8_LAS bf16x8*)(lds + PG8_SA(b, h) + aoff + m * 2048 + k * 1024); } while (0)
; #define PG8_LDB(dst, b, h) do { _Pragma("unroll") for (int n = 0; n < 2; ++n) _Pragma("unroll") for (int k = 0; k < 2; ++k) dst[n][k] = *(const PG8_LAS bf16x8*)(lds + PG8_SB(b, h) + boff + n * 2048 + k * 1024); } while (0)
; #define PG8_MMA(ai, bj, At, Bt) do { __builtin_amdgcn_s_setprio(1); _Pragma("unroll") for (int m = 0; m < 4; ++m) _Pragma("unroll") for (int n = 0; n < 2; ++n) _Pragma("unroll") for (int k = 0; k < 2; ++k) \
;         acc[ai][bj][m][n] = __builtin_amdgcn_mfma_f32_16x16x32_bf16(Bt[n][k], At[m][k], acc[ai][bj][m][n], 0, 0, 0); __builtin_amdgcn_s_setprio(0); } while (0)
; #define PG8_WAIT_V(n) asm volatile("s_waitcnt vmcnt(" #n ")" ::: "memory")
; #define PG8_WAIT_L(n) asm volatile("s_waitcnt lgkmcnt(" #n ")" ::: "memory")
; #define PG8_BAR __builtin_amdgcn_s_barrier()
; #define PG8_SCHED __builtin_amdgcn_sched_barrier(0)
; template <class Epi, class Sched, bool ALIGN_EPI = false, bool SP2 = false>
; __device__ __forceinline__ void gemm_phase(PG8_LAS unsigned char* lds, const Gemm g, const Sched& S, const Epi& E) {
;     ...
;             PG8_LDB(B0, 0, 0); PG8_LDB(B1, 0, 1); PG8_SCHED; PG8_LDA(At, 0, 0); PG8_STAGE(PG8_SA(1, 1), a1 + hstep, voffA);
;             PG8_WAIT_V(8); PG8_WAIT_L(0); PG8_BAR; PG8_MMA(0, 0, At, B0); PG8_MMA(0, 1, At, B1); PG8_BAR; PG8_SCHED;
;             PG8_LDA(At, 0, 1); PG8_STAGE(PG8_SB(0, 0), b2, voffB); PG8_STAGE(PG8_SB(0, 1), b2 + hstep, voffB); PG8_STAGE(PG8_SA(0, 0), a2, voffA);
.LBB0_650:
	ds_read_b128 v[152:155], v156
	ds_read_b128 v[162:165], v156 offset:1024
	ds_read_b128 v[170:173], v156 offset:2048
	ds_read_b128 v[174:177], v156 offset:3072
	ds_read_b128 v[182:185], v157
	ds_read_b128 v[186:189], v157 offset:1024
	ds_read_b128 v[190:193], v157 offset:2048
	ds_read_b128 v[194:197], v157 offset:3072
	s_add_i32 s74, s50, 2
	s_add_u32 s75, s48, 0x80
	s_addc_u32 s51, s49, 0
	s_cmp_eq_u32 s64, s50
	s_cselect_b32 s50, s8, s75
	s_cselect_b32 s51, s9, s51
	s_cselect_b32 s77, s47, s73
	s_cselect_b32 s76, s46, s72
	v_lshl_add_u64 v[166:167], s[48:49], 0, v[146:147]
	s_add_i32 m0, s56, 0xc000
	ds_read_b128 v[198:201], v158
	ds_read_b128 v[202:205], v158 offset:1024
	ds_read_b128 v[206:209], v158 offset:2048
	ds_read_b128 v[210:213], v158 offset:3072
	ds_read_b128 v[214:217], v158 offset:4096
	ds_read_b128 v[218:221], v158 offset:5120
	ds_read_b128 v[222:225], v158 offset:6144
	ds_read_b128 v[226:229], v158 offset:7168
	global_load_lds_dwordx4 v[166:167], off
	v_lshl_add_u64 v[166:167], s[48:49], 0, v[138:139]
	s_add_i32 m0, s56, 0xe000
	s_nop 0
	global_load_lds_dwordx4 v[166:167], off
	s_waitcnt vmcnt(8)
	s_waitcnt lgkmcnt(0)
	s_barrier
	s_setprio 1
	s_waitcnt lgkmcnt(0)
	v_mfma_f32_16x16x32_bf16 v[124:127], v[152:155], v[198:201], v[124:127]
	v_mfma_f32_16x16x32_bf16 v[120:123], v[170:173], v[198:201], v[120:123]
	v_mfma_f32_16x16x32_bf16 v[108:111], v[152:155], v[206:209], v[108:111]
	v_mfma_f32_16x16x32_bf16 v[104:107], v[170:173], v[206:209], v[104:107]
	v_mfma_f32_16x16x32_bf16 v[92:95], v[152:155], v[214:217], v[92:95]
	v_mfma_f32_16x16x32_bf16 v[88:91], v[170:173], v[214:217], v[88:91]
	v_mfma_f32_16x16x32_bf16 v[76:79], v[152:155], v[222:225], v[76:79]
	v_mfma_f32_16x16x32_bf16 v[72:75], v[170:173], v[222:225], v[72:75]
	v_mfma_f32_16x16x32_bf16 v[124:127], v[162:165], v[202:205], v[124:127]
	v_mfma_f32_16x16x32_bf16 v[120:123], v[174:177], v[202:205], v[120:123]
	v_mfma_f32_16x16x32_bf16 v[108:111], v[162:165], v[210:213], v[108:111]
	v_mfma_f32_16x16x32_bf16 v[104:107], v[174:177], v[210:213], v[104:107]
	v_mfma_f32_16x16x32_bf16 v[92:95], v[162:165], v[218:221], v[92:95]
	v_mfma_f32_16x16x32_bf16 v[88:91], v[174:177], v[218:221], v[88:91]
	v_mfma_f32_16x16x32_bf16 v[76:79], v[162:165], v[226:229], v[76:79]
	v_mfma_f32_16x16x32_bf16 v[72:75], v[174:177], v[226:229], v[72:75]
	s_setprio 0
	s_setprio 1
	v_mfma_f32_16x16x32_bf16 v[116:119], v[182:185], v[198:201], v[116:119]
	v_mfma_f32_16x16x32_bf16 v[112:115], v[190:193], v[198:201], v[112:115]
	v_mfma_f32_16x16x32_bf16 v[100:103], v[182:185], v[206:209], v[100:103]
	v_mfma_f32_16x16x32_bf16 v[96:99], v[190:193], v[206:209], v[96:99]
	v_mfma_f32_16x16x32_bf16 v[84:87], v[182:185], v[214:217], v[84:87]
	v_mfma_f32_16x16x32_bf16 v[80:83], v[190:193], v[214:217], v[80:83]
	v_mfma_f32_16x16x32_bf16 v[68:71], v[182:185], v[222:225], v[68:71]
	v_mfma_f32_16x16x32_bf16 v[64:67], v[190:193], v[222:225], v[64:67]
	v_mfma_f32_16x16x32_bf16 v[116:119], v[186:189], v[202:205], v[116:119]
	v_mfma_f32_16x16x32_bf16 v[112:115], v[194:197], v[202:205], v[112:115]
	v_mfma_f32_16x16x32_bf16 v[100:103], v[186:189], v[210:213], v[100:103]
	v_mfma_f32_16x16x32_bf16 v[96:99], v[194:197], v[210:213], v[96:99]
	v_mfma_f32_16x16x32_bf16 v[84:87], v[186:189], v[218:221], v[84:87]
	v_mfma_f32_16x16x32_bf16 v[80:83], v[194:197], v[218:221], v[80:83]
	v_mfma_f32_16x16x32_bf16 v[68:71], v[186:189], v[226:229], v[68:71]
	v_mfma_f32_16x16x32_bf16 v[64:67], v[194:197], v[226:229], v[64:67]
	s_setprio 0
	s_barrier
	s_add_i32 s75, s67, s54
	v_lshl_add_u64 v[166:167], s[76:77], 0, v[132:133]
	s_mov_b32 m0, s75
	ds_read_b128 v[198:201], v158 offset:16384
	ds_read_b128 v[202:205], v158 offset:17408
	ds_read_b128 v[206:209], v158 offset:18432
	ds_read_b128 v[210:213], v158 offset:19456
	ds_read_b128 v[214:217], v158 offset:20480
	ds_read_b128 v[218:221], v158 offset:21504
	ds_read_b128 v[222:225], v158 offset:22528
	ds_read_b128 v[226:229], v158 offset:23552
	global_load_lds_dwordx4 v[166:167], off
	s_add_i32 m0, s75, 0x2000
	v_lshl_add_u64 v[230:231], s[76:77], 0, v[130:131]
	s_add_u32 s76, s76, s14
	s_addc_u32 s77, s77, s15
	s_add_i32 s75, s68, s54
	global_load_lds_dwordx4 v[230:231], off
	v_lshl_add_u64 v[232:233], s[76:77], 0, v[132:133]
	s_mov_b32 m0, s75
	v_lshl_add_u64 v[234:235], s[76:77], 0, v[130:131]
	global_load_lds_dwordx4 v[232:233], off
	s_add_i32 m0, s75, 0x2000
	v_lshl_add_u64 v[236:237], s[50:51], 0, v[132:133]
	global_load_lds_dwordx4 v[234:235], off
	s_mov_b32 m0, s56
	v_lshl_add_u64 v[238:239], s[50:51], 0, v[130:131]
	global_load_lds_dwordx4 v[236:237], off
	s_mov_b32 m0, s57
	s_nop 0
	global_load_lds_dwordx4 v[238:239], off
	s_waitcnt vmcnt(8)
	s_waitcnt lgkmcnt(0)
	s_barrier
; #define PG8_STAGE(bufoff, gbase, voff) do { _Pragma("unroll") for (int _i = 0; _i < 2; ++_i) \
;         __builtin_amdgcn_global_load_lds((const unsigned*)((const char*)(gbase) + (voff)[_i]), (PG8_LAS unsigned*)(lds + (bufoff) + ldsw + _i * 8192), 16, 0, 0); } while (0)
; #define PG8_LDA(dst, b, h) do { _Pragma("unroll") for (int m = 0; m < 4; ++m) _Pragma("unroll") for (int k = 0; k < 2; ++k) dst[m][k] = *(const PG8_LAS bf16x8*)(lds + PG8_SA(b, h) + aoff + m * 2048 + k * 1024); } while (0)
; #define PG8_LDB(dst, b, h) do { _Pragma("unroll") for (int n = 0; n < 2; ++n) _Pragma("unroll") for (int k = 0; k < 2; ++k) dst[n][k] = *(const PG8_LAS bf16x8*)(lds + PG8_SB(b, h) + boff + n * 2048 + k * 1024); } while (0)
; #define PG8_MMA(ai, bj, At, Bt) do { __builtin_amdgcn_s_setprio(1); _Pragma("unroll") for (int m = 0; m < 4; ++m) _Pragma("unroll") for (int n = 0; n < 2; ++n) _Pragma("unroll") for (int k = 0; k < 2; ++k) \
;         acc[ai][bj][m][n] = __builtin_amdgcn_mfma_f32_16x16x32_bf16(Bt[n][k], At[m][k], acc[ai][bj][m][n], 0, 0, 0); __builtin_amdgcn_s_setprio(0); } while (0)
; #define PG8_WAIT_V(n) asm volatile("s_waitcnt vmcnt(" #n ")" ::: "memory")
; #define PG8_WAIT_L(n) asm volatile("s_waitcnt lgkmcnt(" #n ")" ::: "memory")
; #define PG8_BAR __builtin_amdgcn_s_barrier()
; #define PG8_SCHED __builtin_amdgcn_sched_barrier(0)
; template <class Epi, class Sched, bool ALIGN_EPI = false, bool SP2 = false>
; __device__ __forceinline__ void gemm_phase(PG8_LAS unsigned char* lds, const Gemm g, const Sched& S, const Epi& E) {
;     ...
;             PG8_WAIT_V(8); PG8_WAIT_L(0); PG8_BAR; PG8_MMA(1, 0, At, B0); PG8_MMA(1, 1, At, B1); PG8_BAR; PG8_SCHED;
;             PG8_LDB(B0, 1, 0); PG8_LDB(B1, 1, 1); PG8_SCHED; PG8_LDA(At, 1, 0); PG8_STAGE(PG8_SA(0, 1), a2 + hstep, voffA);
;             PG8_WAIT_V(8); PG8_WAIT_L(0); PG8_BAR; PG8_MMA(0, 0, At, B0); PG8_MMA(0, 1, At, B1); PG8_BAR; PG8_SCHED;
	s_setprio 1
	s_waitcnt lgkmcnt(0)
	v_mfma_f32_16x16x32_bf16 v[60:63], v[152:155], v[198:201], v[60:63]
	v_mfma_f32_16x16x32_bf16 v[56:59], v[170:173], v[198:201], v[56:59]
	v_mfma_f32_16x16x32_bf16 v[44:47], v[152:155], v[206:209], v[44:47]
	v_mfma_f32_16x16x32_bf16 v[40:43], v[170:173], v[206:209], v[40:43]
	v_mfma_f32_16x16x32_bf16 v[28:31], v[152:155], v[214:217], v[28:31]
	v_mfma_f32_16x16x32_bf16 v[24:27], v[170:173], v[214:217], v[24:27]
	v_mfma_f32_16x16x32_bf16 v[12:15], v[152:155], v[222:225], v[12:15]
	v_mfma_f32_16x16x32_bf16 v[8:11], v[170:173], v[222:225], v[8:11]
	v_mfma_f32_16x16x32_bf16 v[60:63], v[162:165], v[202:205], v[60:63]
	v_mfma_f32_16x16x32_bf16 v[56:59], v[174:177], v[202:205], v[56:59]
	v_mfma_f32_16x16x32_bf16 v[44:47], v[162:165], v[210:213], v[44:47]
	v_mfma_f32_16x16x32_bf16 v[40:43], v[174:177], v[210:213], v[40:43]
	v_mfma_f32_16x16x32_bf16 v[28:31], v[162:165], v[218:221], v[28:31]
	v_mfma_f32_16x16x32_bf16 v[24:27], v[174:177], v[218:221], v[24:27]
	v_mfma_f32_16x16x32_bf16 v[12:15], v[162:165], v[226:229], v[12:15]
	v_mfma_f32_16x16x32_bf16 v[8:11], v[174:177], v[226:229], v[8:11]
	s_setprio 0
	s_setprio 1
	v_mfma_f32_16x16x32_bf16 v[52:55], v[182:185], v[198:201], v[52:55]
	v_mfma_f32_16x16x32_bf16 v[48:51], v[190:193], v[198:201], v[48:51]
	v_mfma_f32_16x16x32_bf16 v[36:39], v[182:185], v[206:209], v[36:39]
	v_mfma_f32_16x16x32_bf16 v[32:35], v[190:193], v[206:209], v[32:35]
	v_mfma_f32_16x16x32_bf16 v[20:23], v[182:185], v[214:217], v[20:23]
	v_mfma_f32_16x16x32_bf16 v[16:19], v[190:193], v[214:217], v[16:19]
	v_mfma_f32_16x16x32_bf16 v[4:7], v[182:185], v[222:225], v[4:7]
	v_mfma_f32_16x16x32_bf16 v[0:3], v[190:193], v[222:225], v[0:3]
	v_mfma_f32_16x16x32_bf16 v[52:55], v[186:189], v[202:205], v[52:55]
	v_mfma_f32_16x16x32_bf16 v[48:51], v[194:197], v[202:205], v[48:51]
	v_mfma_f32_16x16x32_bf16 v[36:39], v[186:189], v[210:213], v[36:39]
	v_mfma_f32_16x16x32_bf16 v[32:35], v[194:197], v[210:213], v[32:35]
	v_mfma_f32_16x16x32_bf16 v[20:23], v[186:189], v[218:221], v[20:23]
	v_mfma_f32_16x16x32_bf16 v[16:19], v[194:197], v[218:221], v[16:19]
	v_mfma_f32_16x16x32_bf16 v[4:7], v[186:189], v[226:229], v[4:7]
	v_mfma_f32_16x16x32_bf16 v[0:3], v[194:197], v[226:229], v[0:3]
	s_setprio 0
	s_barrier
	s_add_i32 s75, 0, 0x18000
	v_add_u32_e32 v134, s75, v141
	s_add_i32 s76, 0, 0x1c000
	ds_read_b128 v[152:155], v134
	ds_read_b128 v[162:165], v134 offset:1024
	ds_read_b128 v[170:173], v134 offset:2048
	ds_read_b128 v[174:177], v134 offset:3072
	v_add_u32_e32 v134, s76, v141
	ds_read_b128 v[182:185], v134
	ds_read_b128 v[186:189], v134 offset:1024
	ds_read_b128 v[190:193], v134 offset:2048
	ds_read_b128 v[194:197], v134 offset:3072
	s_add_u32 s50, s50, s14
	s_addc_u32 s51, s51, s15
	s_mov_b32 m0, s58
	v_lshl_add_u64 v[240:241], s[50:51], 0, v[132:133]
	ds_read_b128 v[198:201], v158 offset:32768
	ds_read_b128 v[202:205], v158 offset:33792
	ds_read_b128 v[206:209], v158 offset:34816
	ds_read_b128 v[210:213], v158 offset:35840
	ds_read_b128 v[214:217], v158 offset:36864
	ds_read_b128 v[218:221], v158 offset:37888
	ds_read_b128 v[222:225], v158 offset:38912
	ds_read_b128 v[226:229], v158 offset:39936
	global_load_lds_dwordx4 v[240:241], off
	v_lshl_add_u64 v[240:241], s[50:51], 0, v[130:131]
	s_mov_b32 m0, s59
	s_nop 0
	global_load_lds_dwordx4 v[240:241], off
	s_waitcnt vmcnt(8)
	s_waitcnt lgkmcnt(0)
	s_barrier
	s_setprio 1
	s_waitcnt lgkmcnt(0)
	v_mfma_f32_16x16x32_bf16 v[124:127], v[152:155], v[198:201], v[124:127]
	v_mfma_f32_16x16x32_bf16 v[120:123], v[170:173], v[198:201], v[120:123]
	v_mfma_f32_16x16x32_bf16 v[108:111], v[152:155], v[206:209], v[108:111]
	v_mfma_f32_16x16x32_bf16 v[104:107], v[170:173], v[206:209], v[104:107]
	v_mfma_f32_16x16x32_bf16 v[92:95], v[152:155], v[214:217], v[92:95]
	v_mfma_f32_16x16x32_bf16 v[88:91], v[170:173], v[214:217], v[88:91]
	v_mfma_f32_16x16x32_bf16 v[76:79], v[152:155], v[222:225], v[76:79]
	v_mfma_f32_16x16x32_bf16 v[72:75], v[170:173], v[222:225], v[72:75]
	v_mfma_f32_16x16x32_bf16 v[124:127], v[162:165], v[202:205], v[124:127]
	v_mfma_f32_16x16x32_bf16 v[120:123], v[174:177], v[202:205], v[120:123]
	v_mfma_f32_16x16x32_bf16 v[108:111], v[162:165], v[210:213], v[108:111]
	v_mfma_f32_16x16x32_bf16 v[104:107], v[174:177], v[210:213], v[104:107]
	v_mfma_f32_16x16x32_bf16 v[92:95], v[162:165], v[218:221], v[92:95]
	v_mfma_f32_16x16x32_bf16 v[88:91], v[174:177], v[218:221], v[88:91]
	v_mfma_f32_16x16x32_bf16 v[76:79], v[162:165], v[226:229], v[76:79]
	v_mfma_f32_16x16x32_bf16 v[72:75], v[174:177], v[226:229], v[72:75]
	s_setprio 0
	s_setprio 1
	v_mfma_f32_16x16x32_bf16 v[116:119], v[182:185], v[198:201], v[116:119]
	v_mfma_f32_16x16x32_bf16 v[112:115], v[190:193], v[198:201], v[112:115]
	v_mfma_f32_16x16x32_bf16 v[100:103], v[182:185], v[206:209], v[100:103]
	v_mfma_f32_16x16x32_bf16 v[96:99], v[190:193], v[206:209], v[96:99]
	v_mfma_f32_16x16x32_bf16 v[84:87], v[182:185], v[214:217], v[84:87]
	v_mfma_f32_16x16x32_bf16 v[80:83], v[190:193], v[214:217], v[80:83]
	v_mfma_f32_16x16x32_bf16 v[68:71], v[182:185], v[222:225], v[68:71]
	v_mfma_f32_16x16x32_bf16 v[64:67], v[190:193], v[222:225], v[64:67]
	v_mfma_f32_16x16x32_bf16 v[116:119], v[186:189], v[202:205], v[116:119]
	v_mfma_f32_16x16x32_bf16 v[112:115], v[194:197], v[202:205], v[112:115]
	v_mfma_f32_16x16x32_bf16 v[100:103], v[186:189], v[210:213], v[100:103]
	v_mfma_f32_16x16x32_bf16 v[96:99], v[194:197], v[210:213], v[96:99]
	v_mfma_f32_16x16x32_bf16 v[84:87], v[186:189], v[218:221], v[84:87]
	v_mfma_f32_16x16x32_bf16 v[80:83], v[194:197], v[218:221], v[80:83]
	v_mfma_f32_16x16x32_bf16 v[68:71], v[186:189], v[226:229], v[68:71]
	v_mfma_f32_16x16x32_bf16 v[64:67], v[194:197], v[226:229], v[64:67]
	s_setprio 0
	s_barrier
; #define PG8_STAGE(bufoff, gbase, voff) do { _Pragma("unroll") for (int _i = 0; _i < 2; ++_i) \
;         __builtin_amdgcn_global_load_lds((const unsigned*)((const char*)(gbase) + (voff)[_i]), (PG8_LAS unsigned*)(lds + (bufoff) + ldsw + _i * 8192), 16, 0, 0); } while (0)
; #define PG8_LDA(dst, b, h) do { _Pragma("unroll") for (int m = 0; m < 4; ++m) _Pragma("unroll") for (int k = 0; k < 2; ++k) dst[m][k] = *(const PG8_LAS bf16x8*)(lds + PG8_SA(b, h) + aoff + m * 2048 + k * 1024); } while (0)
; #define PG8_MMA(ai, bj, At, Bt) do { __builtin_amdgcn_s_setprio(1); _Pragma("unroll") for (int m = 0; m < 4; ++m) _Pragma("unroll") for (int n = 0; n < 2; ++n) _Pragma("unroll") for (int k = 0; k < 2; ++k) \
;         acc[ai][bj][m][n] = __builtin_amdgcn_mfma_f32_16x16x32_bf16(Bt[n][k], At[m][k], acc[ai][bj][m][n], 0, 0, 0); __builtin_amdgcn_s_setprio(0); } while (0)
; #define PG8_WAIT_V(n) asm volatile("s_waitcnt vmcnt(" #n ")" ::: "memory")
; #define PG8_WAIT_L(n) asm volatile("s_waitcnt lgkmcnt(" #n ")" ::: "memory")
; #define PG8_BAR __builtin_amdgcn_s_barrier()
; #define PG8_SCHED __builtin_amdgcn_sched_barrier(0)
; template <class Epi, class Sched, bool ALIGN_EPI = false, bool SP2 = false>
; __device__ __forceinline__ void gemm_phase(PG8_LAS unsigned char* lds, const Gemm g, const Sched& S, const Epi& E) {
;     ...
;         for (int t = 0; t < nt; t += 2) {
;             const bool last = (t == nt - 2);
;             const char* a1 = cA + (size_t)(t + 1) * kstep;
;             const char* a2 = last ? nA : cA + (size_t)(t + 2) * kstep; const char* b2 = last ? nB : cB + (size_t)(t + 2) * kstep;
;             const char* a3 = a2 + kstep; const char* b3 = b2 + kstep;
;     ...
;             PG8_LDA(At, 1, 1); PG8_STAGE(PG8_SB(1, 0), b3, voffB); PG8_STAGE(PG8_SB(1, 1), b3 + hstep, voffB); PG8_STAGE(PG8_SA(1, 0), a3, voffA);
;             PG8_WAIT_V(8); PG8_WAIT_L(0); PG8_BAR; PG8_MMA(1, 0, At, B0); PG8_MMA(1, 1, At, B1); PG8_BAR; PG8_SCHED;
	s_add_i32 s50, s75, s54
	v_lshl_add_u64 v[166:167], v[166:167], 0, s[38:39]
	s_mov_b32 m0, s50
	ds_read_b128 v[198:201], v158 offset:49152
	ds_read_b128 v[202:205], v158 offset:50176
	ds_read_b128 v[206:209], v158 offset:51200
	ds_read_b128 v[210:213], v158 offset:52224
	ds_read_b128 v[214:217], v158 offset:53248
	ds_read_b128 v[218:221], v158 offset:54272
	ds_read_b128 v[222:225], v158 offset:55296
	ds_read_b128 v[226:229], v158 offset:56320
	global_load_lds_dwordx4 v[166:167], off
	v_lshl_add_u64 v[166:167], v[230:231], 0, s[38:39]
	s_add_i32 m0, s50, 0x2000
	s_add_i32 s50, s76, s54
	global_load_lds_dwordx4 v[166:167], off
	v_lshl_add_u64 v[166:167], v[232:233], 0, s[38:39]
	s_mov_b32 m0, s50
	s_nop 0
	global_load_lds_dwordx4 v[166:167], off
	v_lshl_add_u64 v[166:167], v[234:235], 0, s[38:39]
	s_add_i32 m0, s50, 0x2000
	s_nop 0
	global_load_lds_dwordx4 v[166:167], off
	v_lshl_add_u64 v[166:167], v[236:237], 0, s[38:39]
	s_mov_b32 m0, s61
	s_nop 0
	global_load_lds_dwordx4 v[166:167], off
	v_lshl_add_u64 v[166:167], v[238:239], 0, s[38:39]
	s_mov_b32 m0, s62
	s_nop 0
	global_load_lds_dwordx4 v[166:167], off
	s_waitcnt vmcnt(8)
	s_waitcnt lgkmcnt(0)
	s_barrier
	s_setprio 1
	s_waitcnt lgkmcnt(0)
	v_mfma_f32_16x16x32_bf16 v[60:63], v[152:155], v[198:201], v[60:63]
	v_mfma_f32_16x16x32_bf16 v[56:59], v[170:173], v[198:201], v[56:59]
	v_mfma_f32_16x16x32_bf16 v[44:47], v[152:155], v[206:209], v[44:47]
	v_mfma_f32_16x16x32_bf16 v[40:43], v[170:173], v[206:209], v[40:43]
	v_mfma_f32_16x16x32_bf16 v[28:31], v[152:155], v[214:217], v[28:31]
	v_mfma_f32_16x16x32_bf16 v[24:27], v[170:173], v[214:217], v[24:27]
	v_mfma_f32_16x16x32_bf16 v[12:15], v[152:155], v[222:225], v[12:15]
	v_mfma_f32_16x16x32_bf16 v[8:11], v[170:173], v[222:225], v[8:11]
	v_mfma_f32_16x16x32_bf16 v[60:63], v[162:165], v[202:205], v[60:63]
	v_mfma_f32_16x16x32_bf16 v[56:59], v[174:177], v[202:205], v[56:59]
	v_mfma_f32_16x16x32_bf16 v[44:47], v[162:165], v[210:213], v[44:47]
	v_mfma_f32_16x16x32_bf16 v[40:43], v[174:177], v[210:213], v[40:43]
	v_mfma_f32_16x16x32_bf16 v[28:31], v[162:165], v[218:221], v[28:31]
	v_mfma_f32_16x16x32_bf16 v[24:27], v[174:177], v[218:221], v[24:27]
	v_mfma_f32_16x16x32_bf16 v[12:15], v[162:165], v[226:229], v[12:15]
	v_mfma_f32_16x16x32_bf16 v[8:11], v[174:177], v[226:229], v[8:11]
	s_setprio 0
	s_setprio 1
	v_mfma_f32_16x16x32_bf16 v[52:55], v[182:185], v[198:201], v[52:55]
	v_mfma_f32_16x16x32_bf16 v[48:51], v[190:193], v[198:201], v[48:51]
	v_mfma_f32_16x16x32_bf16 v[36:39], v[182:185], v[206:209], v[36:39]
	v_mfma_f32_16x16x32_bf16 v[32:35], v[190:193], v[206:209], v[32:35]
	v_mfma_f32_16x16x32_bf16 v[20:23], v[182:185], v[214:217], v[20:23]
	v_mfma_f32_16x16x32_bf16 v[16:19], v[190:193], v[214:217], v[16:19]
	v_mfma_f32_16x16x32_bf16 v[4:7], v[182:185], v[222:225], v[4:7]
	v_mfma_f32_16x16x32_bf16 v[0:3], v[190:193], v[222:225], v[0:3]
	v_mfma_f32_16x16x32_bf16 v[52:55], v[186:189], v[202:205], v[52:55]
	v_mfma_f32_16x16x32_bf16 v[48:51], v[194:197], v[202:205], v[48:51]
	v_mfma_f32_16x16x32_bf16 v[36:39], v[186:189], v[210:213], v[36:39]
	v_mfma_f32_16x16x32_bf16 v[32:35], v[194:197], v[210:213], v[32:35]
	v_mfma_f32_16x16x32_bf16 v[20:23], v[186:189], v[218:221], v[20:23]
	v_mfma_f32_16x16x32_bf16 v[16:19], v[194:197], v[218:221], v[16:19]
	v_mfma_f32_16x16x32_bf16 v[4:7], v[186:189], v[226:229], v[4:7]
	v_mfma_f32_16x16x32_bf16 v[0:3], v[194:197], v[226:229], v[0:3]
	s_setprio 0
	s_add_u32 s72, s72, 0x100
	s_addc_u32 s73, s73, 0
	s_add_u32 s48, s48, 0x100
	s_addc_u32 s49, s49, 0
	s_cmp_ge_i32 s74, s63
	s_mov_b32 s50, s74
	s_barrier
	s_cbranch_scc0 .LBB0_650

; #define PG8_STAGE(bufoff, gbase, voff) do { _Pragma("unroll") for (int _i = 0; _i < 2; ++_i) \
;         __builtin_amdgcn_global_load_lds((const unsigned*)((const char*)(gbase) + (voff)[_i]), (PG8_LAS unsigned*)(lds + (bufoff) + ldsw + _i * 8192), 16, 0, 0); } while (0)
; #define PG8_LDA(dst, b, h) do { _Pragma("unroll") for (int m = 0; m < 4; ++m) _Pragma("unroll") for (int k = 0; k < 2; ++k) dst[m][k] = *(const PG8_LAS bf16x8*)(lds + PG8_SA(b, h) + aoff + m * 2048 + k * 1024); } while (0)
; #define PG8_LDB(dst, b, h) do { _Pragma("unroll") for (int n = 0; n < 2; ++n) _Pragma("unroll") for (int k = 0; k < 2; ++k) dst[n][k] = *(const PG8_LAS bf16x8*)(lds + PG8_SB(b, h) + boff + n * 2048 + k * 1024); } while (0)
; #define PG8_MMA(ai, bj, At, Bt) do { __builtin_amdgcn_s_setprio(1); _Pragma("unroll") for (int m = 0; m < 4; ++m) _Pragma("unroll") for (int n = 0; n < 2; ++n) _Pragma("unroll") for (int k = 0; k < 2; ++k) \
;         acc[ai][bj][m][n] = __builtin_amdgcn_mfma_f32_16x16x32_bf16(Bt[n][k], At[m][k], acc[ai][bj][m][n], 0, 0, 0); __builtin_amdgcn_s_setprio(0); } while (0)
; #define PG8_WAIT_V(n) asm volatile("s_waitcnt vmcnt(" #n ")" ::: "memory")
; #define PG8_WAIT_L(n) asm volatile("s_waitcnt lgkmcnt(" #n ")" ::: "memory")
; #define PG8_BAR __builtin_amdgcn_s_barrier()
; #define PG8_SCHED __builtin_amdgcn_sched_barrier(0)
; template <class Epi, class Sched, bool ALIGN_EPI = false, bool SP2 = false>
; __device__ __forceinline__ void gemm_phase(PG8_LAS unsigned char* lds, const Gemm g, const Sched& S, const Epi& E) {
;     ...
;             PG8_LDB(B0, 0, 0); PG8_LDB(B1, 0, 1); PG8_SCHED; PG8_LDA(At, 0, 0); PG8_STAGE(PG8_SA(1, 1), a1 + hstep, voffA);
;             PG8_WAIT_V(8); PG8_WAIT_L(0); PG8_BAR; PG8_MMA(0, 0, At, B0); PG8_MMA(0, 1, At, B1); PG8_BAR; PG8_SCHED;
;             PG8_LDA(At, 0, 1); PG8_STAGE(PG8_SB(0, 0), b2, voffB); PG8_STAGE(PG8_SB(0, 1), b2 + hstep, voffB); PG8_STAGE(PG8_SA(0, 0), a2, voffA);
.LBB0_683:
	ds_read_b128 v[148:151], v141
	ds_read_b128 v[152:155], v141 offset:1024
	ds_read_b128 v[156:159], v141 offset:2048
	ds_read_b128 v[162:165], v141 offset:3072
	ds_read_b128 v[170:173], v143
	ds_read_b128 v[174:177], v143 offset:1024
	ds_read_b128 v[182:185], v143 offset:2048
	ds_read_b128 v[186:189], v143 offset:3072
	s_add_i32 s89, s58, 2
	s_add_u32 s90, s56, 0x80
	s_addc_u32 s59, s57, 0
	s_cmp_eq_u32 s74, s58
	s_cselect_b32 s58, s52, s90
	s_cselect_b32 s59, s53, s59
	s_cselect_b32 s91, s55, s88
	s_cselect_b32 s90, s54, s87
	v_lshl_add_u64 v[166:167], s[56:57], 0, v[136:137]
	s_add_i32 m0, s66, 0xc000
	ds_read_b128 v[190:193], v146
	ds_read_b128 v[194:197], v146 offset:1024
	ds_read_b128 v[198:201], v146 offset:2048
	ds_read_b128 v[202:205], v146 offset:3072
	ds_read_b128 v[206:209], v146 offset:4096
	ds_read_b128 v[210:213], v146 offset:5120
	ds_read_b128 v[214:217], v146 offset:6144
	ds_read_b128 v[218:221], v146 offset:7168
	global_load_lds_dwordx4 v[166:167], off
	v_lshl_add_u64 v[166:167], s[56:57], 0, v[134:135]
	s_add_i32 m0, s66, 0xe000
	s_nop 0
	global_load_lds_dwordx4 v[166:167], off
	s_waitcnt vmcnt(8)
	s_waitcnt lgkmcnt(0)
	s_barrier
	s_setprio 1
	s_waitcnt lgkmcnt(0)
	v_mfma_f32_16x16x32_bf16 v[124:127], v[148:151], v[190:193], v[124:127]
	v_mfma_f32_16x16x32_bf16 v[120:123], v[156:159], v[190:193], v[120:123]
	v_mfma_f32_16x16x32_bf16 v[108:111], v[148:151], v[198:201], v[108:111]
	v_mfma_f32_16x16x32_bf16 v[104:107], v[156:159], v[198:201], v[104:107]
	v_mfma_f32_16x16x32_bf16 v[92:95], v[148:151], v[206:209], v[92:95]
	v_mfma_f32_16x16x32_bf16 v[88:91], v[156:159], v[206:209], v[88:91]
	v_mfma_f32_16x16x32_bf16 v[76:79], v[148:151], v[214:217], v[76:79]
	v_mfma_f32_16x16x32_bf16 v[72:75], v[156:159], v[214:217], v[72:75]
	v_mfma_f32_16x16x32_bf16 v[124:127], v[152:155], v[194:197], v[124:127]
	v_mfma_f32_16x16x32_bf16 v[120:123], v[162:165], v[194:197], v[120:123]
	v_mfma_f32_16x16x32_bf16 v[108:111], v[152:155], v[202:205], v[108:111]
	v_mfma_f32_16x16x32_bf16 v[104:107], v[162:165], v[202:205], v[104:107]
	v_mfma_f32_16x16x32_bf16 v[92:95], v[152:155], v[210:213], v[92:95]
	v_mfma_f32_16x16x32_bf16 v[88:91], v[162:165], v[210:213], v[88:91]
	v_mfma_f32_16x16x32_bf16 v[76:79], v[152:155], v[218:221], v[76:79]
	v_mfma_f32_16x16x32_bf16 v[72:75], v[162:165], v[218:221], v[72:75]
	s_setprio 0
	s_setprio 1
	v_mfma_f32_16x16x32_bf16 v[116:119], v[170:173], v[190:193], v[116:119]
	v_mfma_f32_16x16x32_bf16 v[112:115], v[182:185], v[190:193], v[112:115]
	v_mfma_f32_16x16x32_bf16 v[100:103], v[170:173], v[198:201], v[100:103]
	v_mfma_f32_16x16x32_bf16 v[96:99], v[182:185], v[198:201], v[96:99]
	v_mfma_f32_16x16x32_bf16 v[84:87], v[170:173], v[206:209], v[84:87]
	v_mfma_f32_16x16x32_bf16 v[80:83], v[182:185], v[206:209], v[80:83]
	v_mfma_f32_16x16x32_bf16 v[68:71], v[170:173], v[214:217], v[68:71]
	v_mfma_f32_16x16x32_bf16 v[64:67], v[182:185], v[214:217], v[64:67]
	v_mfma_f32_16x16x32_bf16 v[116:119], v[174:177], v[194:197], v[116:119]
	v_mfma_f32_16x16x32_bf16 v[112:115], v[186:189], v[194:197], v[112:115]
	v_mfma_f32_16x16x32_bf16 v[100:103], v[174:177], v[202:205], v[100:103]
	v_mfma_f32_16x16x32_bf16 v[96:99], v[186:189], v[202:205], v[96:99]
	v_mfma_f32_16x16x32_bf16 v[84:87], v[174:177], v[210:213], v[84:87]
	v_mfma_f32_16x16x32_bf16 v[80:83], v[186:189], v[210:213], v[80:83]
	v_mfma_f32_16x16x32_bf16 v[68:71], v[174:177], v[218:221], v[68:71]
	v_mfma_f32_16x16x32_bf16 v[64:67], v[186:189], v[218:221], v[64:67]
	s_setprio 0
	s_barrier
	s_add_i32 s92, s77, s65
	v_lshl_add_u64 v[166:167], s[90:91], 0, v[130:131]
	s_mov_b32 m0, s92
	ds_read_b128 v[190:193], v146 offset:16384
	ds_read_b128 v[194:197], v146 offset:17408
	ds_read_b128 v[198:201], v146 offset:18432
	ds_read_b128 v[202:205], v146 offset:19456
	ds_read_b128 v[206:209], v146 offset:20480
	ds_read_b128 v[210:213], v146 offset:21504
	ds_read_b128 v[214:217], v146 offset:22528
	ds_read_b128 v[218:221], v146 offset:23552
	global_load_lds_dwordx4 v[166:167], off
	s_add_i32 m0, s92, 0x2000
	v_lshl_add_u64 v[222:223], s[90:91], 0, v[132:133]
	s_add_u32 s90, s90, s14
	s_addc_u32 s91, s91, s15
	s_add_i32 s92, s78, s65
	global_load_lds_dwordx4 v[222:223], off
	v_lshl_add_u64 v[224:225], s[90:91], 0, v[130:131]
	s_mov_b32 m0, s92
	v_lshl_add_u64 v[226:227], s[90:91], 0, v[132:133]
	global_load_lds_dwordx4 v[224:225], off
	s_add_i32 m0, s92, 0x2000
	v_lshl_add_u64 v[228:229], s[58:59], 0, v[130:131]
	global_load_lds_dwordx4 v[226:227], off
	s_mov_b32 m0, s66
	v_lshl_add_u64 v[230:231], s[58:59], 0, v[132:133]
	global_load_lds_dwordx4 v[228:229], off
	s_mov_b32 m0, s67
	s_nop 0
	global_load_lds_dwordx4 v[230:231], off
	s_waitcnt vmcnt(8)
	s_waitcnt lgkmcnt(0)
	s_barrier
; #define PG8_STAGE(bufoff, gbase, voff) do { _Pragma("unroll") for (int _i = 0; _i < 2; ++_i) \
;         __builtin_amdgcn_global_load_lds((const unsigned*)((const char*)(gbase) + (voff)[_i]), (PG8_LAS unsigned*)(lds + (bufoff) + ldsw + _i * 8192), 16, 0, 0); } while (0)
; #define PG8_LDA(dst, b, h) do { _Pragma("unroll") for (int m = 0; m < 4; ++m) _Pragma("unroll") for (int k = 0; k < 2; ++k) dst[m][k] = *(const PG8_LAS bf16x8*)(lds + PG8_SA(b, h) + aoff + m * 2048 + k * 1024); } while (0)
; #define PG8_LDB(dst, b, h) do { _Pragma("unroll") for (int n = 0; n < 2; ++n) _Pragma("unroll") for (int k = 0; k < 2; ++k) dst[n][k] = *(const PG8_LAS bf16x8*)(lds + PG8_SB(b, h) + boff + n * 2048 + k * 1024); } while (0)
; #define PG8_MMA(ai, bj, At, Bt) do { __builtin_amdgcn_s_setprio(1); _Pragma("unroll") for (int m = 0; m < 4; ++m) _Pragma("unroll") for (int n = 0; n < 2; ++n) _Pragma("unroll") for (int k = 0; k < 2; ++k) \
;         acc[ai][bj][m][n] = __builtin_amdgcn_mfma_f32_16x16x32_bf16(Bt[n][k], At[m][k], acc[ai][bj][m][n], 0, 0, 0); __builtin_amdgcn_s_setprio(0); } while (0)
; #define PG8_WAIT_V(n) asm volatile("s_waitcnt vmcnt(" #n ")" ::: "memory")
; #define PG8_WAIT_L(n) asm volatile("s_waitcnt lgkmcnt(" #n ")" ::: "memory")
; #define PG8_BAR __builtin_amdgcn_s_barrier()
; #define PG8_SCHED __builtin_amdgcn_sched_barrier(0)
; template <class Epi, class Sched, bool ALIGN_EPI = false, bool SP2 = false>
; __device__ __forceinline__ void gemm_phase(PG8_LAS unsigned char* lds, const Gemm g, const Sched& S, const Epi& E) {
;     ...
;             PG8_WAIT_V(8); PG8_WAIT_L(0); PG8_BAR; PG8_MMA(1, 0, At, B0); PG8_MMA(1, 1, At, B1); PG8_BAR; PG8_SCHED;
;             PG8_LDB(B0, 1, 0); PG8_LDB(B1, 1, 1); PG8_SCHED; PG8_LDA(At, 1, 0); PG8_STAGE(PG8_SA(0, 1), a2 + hstep, voffA);
;             PG8_WAIT_V(8); PG8_WAIT_L(0); PG8_BAR; PG8_MMA(0, 0, At, B0); PG8_MMA(0, 1, At, B1); PG8_BAR; PG8_SCHED;
	s_setprio 1
	s_waitcnt lgkmcnt(0)
	v_mfma_f32_16x16x32_bf16 v[60:63], v[148:151], v[190:193], v[60:63]
	v_mfma_f32_16x16x32_bf16 v[56:59], v[156:159], v[190:193], v[56:59]
	v_mfma_f32_16x16x32_bf16 v[44:47], v[148:151], v[198:201], v[44:47]
	v_mfma_f32_16x16x32_bf16 v[40:43], v[156:159], v[198:201], v[40:43]
	v_mfma_f32_16x16x32_bf16 v[28:31], v[148:151], v[206:209], v[28:31]
	v_mfma_f32_16x16x32_bf16 v[24:27], v[156:159], v[206:209], v[24:27]
	v_mfma_f32_16x16x32_bf16 v[12:15], v[148:151], v[214:217], v[12:15]
	v_mfma_f32_16x16x32_bf16 v[8:11], v[156:159], v[214:217], v[8:11]
	v_mfma_f32_16x16x32_bf16 v[60:63], v[152:155], v[194:197], v[60:63]
	v_mfma_f32_16x16x32_bf16 v[56:59], v[162:165], v[194:197], v[56:59]
	v_mfma_f32_16x16x32_bf16 v[44:47], v[152:155], v[202:205], v[44:47]
	v_mfma_f32_16x16x32_bf16 v[40:43], v[162:165], v[202:205], v[40:43]
	v_mfma_f32_16x16x32_bf16 v[28:31], v[152:155], v[210:213], v[28:31]
	v_mfma_f32_16x16x32_bf16 v[24:27], v[162:165], v[210:213], v[24:27]
	v_mfma_f32_16x16x32_bf16 v[12:15], v[152:155], v[218:221], v[12:15]
	v_mfma_f32_16x16x32_bf16 v[8:11], v[162:165], v[218:221], v[8:11]
	s_setprio 0
	s_setprio 1
	v_mfma_f32_16x16x32_bf16 v[52:55], v[170:173], v[190:193], v[52:55]
	v_mfma_f32_16x16x32_bf16 v[48:51], v[182:185], v[190:193], v[48:51]
	v_mfma_f32_16x16x32_bf16 v[36:39], v[170:173], v[198:201], v[36:39]
	v_mfma_f32_16x16x32_bf16 v[32:35], v[182:185], v[198:201], v[32:35]
	v_mfma_f32_16x16x32_bf16 v[20:23], v[170:173], v[206:209], v[20:23]
	v_mfma_f32_16x16x32_bf16 v[16:19], v[182:185], v[206:209], v[16:19]
	v_mfma_f32_16x16x32_bf16 v[4:7], v[170:173], v[214:217], v[4:7]
	v_mfma_f32_16x16x32_bf16 v[0:3], v[182:185], v[214:217], v[0:3]
	v_mfma_f32_16x16x32_bf16 v[52:55], v[174:177], v[194:197], v[52:55]
	v_mfma_f32_16x16x32_bf16 v[48:51], v[186:189], v[194:197], v[48:51]
	v_mfma_f32_16x16x32_bf16 v[36:39], v[174:177], v[202:205], v[36:39]
	v_mfma_f32_16x16x32_bf16 v[32:35], v[186:189], v[202:205], v[32:35]
	v_mfma_f32_16x16x32_bf16 v[20:23], v[174:177], v[210:213], v[20:23]
	v_mfma_f32_16x16x32_bf16 v[16:19], v[186:189], v[210:213], v[16:19]
	v_mfma_f32_16x16x32_bf16 v[4:7], v[174:177], v[218:221], v[4:7]
	v_mfma_f32_16x16x32_bf16 v[0:3], v[186:189], v[218:221], v[0:3]
	s_setprio 0
	s_barrier
	s_add_i32 s90, 0, 0x18000
	v_add_u32_e32 v147, s90, v138
	s_add_i32 s91, 0, 0x1c000
	ds_read_b128 v[148:151], v147
	ds_read_b128 v[152:155], v147 offset:1024
	ds_read_b128 v[156:159], v147 offset:2048
	ds_read_b128 v[162:165], v147 offset:3072
	v_add_u32_e32 v147, s91, v138
	ds_read_b128 v[170:173], v147
	ds_read_b128 v[174:177], v147 offset:1024
	ds_read_b128 v[182:185], v147 offset:2048
	ds_read_b128 v[186:189], v147 offset:3072
	s_add_u32 s58, s58, s14
	s_addc_u32 s59, s59, s15
	s_mov_b32 m0, s68
	v_lshl_add_u64 v[232:233], s[58:59], 0, v[130:131]
	ds_read_b128 v[190:193], v146 offset:32768
	ds_read_b128 v[194:197], v146 offset:33792
	ds_read_b128 v[198:201], v146 offset:34816
	ds_read_b128 v[202:205], v146 offset:35840
	ds_read_b128 v[206:209], v146 offset:36864
	ds_read_b128 v[210:213], v146 offset:37888
	ds_read_b128 v[214:217], v146 offset:38912
	ds_read_b128 v[218:221], v146 offset:39936
	global_load_lds_dwordx4 v[232:233], off
	v_lshl_add_u64 v[232:233], s[58:59], 0, v[132:133]
	s_mov_b32 m0, s69
	s_nop 0
	global_load_lds_dwordx4 v[232:233], off
	s_waitcnt vmcnt(8)
	s_waitcnt lgkmcnt(0)
	s_barrier
	s_setprio 1
	s_waitcnt lgkmcnt(0)
	v_mfma_f32_16x16x32_bf16 v[124:127], v[148:151], v[190:193], v[124:127]
	v_mfma_f32_16x16x32_bf16 v[120:123], v[156:159], v[190:193], v[120:123]
	v_mfma_f32_16x16x32_bf16 v[108:111], v[148:151], v[198:201], v[108:111]
	v_mfma_f32_16x16x32_bf16 v[104:107], v[156:159], v[198:201], v[104:107]
	v_mfma_f32_16x16x32_bf16 v[92:95], v[148:151], v[206:209], v[92:95]
	v_mfma_f32_16x16x32_bf16 v[88:91], v[156:159], v[206:209], v[88:91]
	v_mfma_f32_16x16x32_bf16 v[76:79], v[148:151], v[214:217], v[76:79]
	v_mfma_f32_16x16x32_bf16 v[72:75], v[156:159], v[214:217], v[72:75]
	v_mfma_f32_16x16x32_bf16 v[124:127], v[152:155], v[194:197], v[124:127]
	v_mfma_f32_16x16x32_bf16 v[120:123], v[162:165], v[194:197], v[120:123]
	v_mfma_f32_16x16x32_bf16 v[108:111], v[152:155], v[202:205], v[108:111]
	v_mfma_f32_16x16x32_bf16 v[104:107], v[162:165], v[202:205], v[104:107]
	v_mfma_f32_16x16x32_bf16 v[92:95], v[152:155], v[210:213], v[92:95]
	v_mfma_f32_16x16x32_bf16 v[88:91], v[162:165], v[210:213], v[88:91]
	v_mfma_f32_16x16x32_bf16 v[76:79], v[152:155], v[218:221], v[76:79]
	v_mfma_f32_16x16x32_bf16 v[72:75], v[162:165], v[218:221], v[72:75]
	s_setprio 0
	s_setprio 1
	v_mfma_f32_16x16x32_bf16 v[116:119], v[170:173], v[190:193], v[116:119]
	v_mfma_f32_16x16x32_bf16 v[112:115], v[182:185], v[190:193], v[112:115]
	v_mfma_f32_16x16x32_bf16 v[100:103], v[170:173], v[198:201], v[100:103]
	v_mfma_f32_16x16x32_bf16 v[96:99], v[182:185], v[198:201], v[96:99]
	v_mfma_f32_16x16x32_bf16 v[84:87], v[170:173], v[206:209], v[84:87]
	v_mfma_f32_16x16x32_bf16 v[80:83], v[182:185], v[206:209], v[80:83]
	v_mfma_f32_16x16x32_bf16 v[68:71], v[170:173], v[214:217], v[68:71]
	v_mfma_f32_16x16x32_bf16 v[64:67], v[182:185], v[214:217], v[64:67]
	v_mfma_f32_16x16x32_bf16 v[116:119], v[174:177], v[194:197], v[116:119]
	v_mfma_f32_16x16x32_bf16 v[112:115], v[186:189], v[194:197], v[112:115]
	v_mfma_f32_16x16x32_bf16 v[100:103], v[174:177], v[202:205], v[100:103]
	v_mfma_f32_16x16x32_bf16 v[96:99], v[186:189], v[202:205], v[96:99]
	v_mfma_f32_16x16x32_bf16 v[84:87], v[174:177], v[210:213], v[84:87]
	v_mfma_f32_16x16x32_bf16 v[80:83], v[186:189], v[210:213], v[80:83]
	v_mfma_f32_16x16x32_bf16 v[68:71], v[174:177], v[218:221], v[68:71]
	v_mfma_f32_16x16x32_bf16 v[64:67], v[186:189], v[218:221], v[64:67]
	s_setprio 0
	s_barrier
; #define PG8_STAGE(bufoff, gbase, voff) do { _Pragma("unroll") for (int _i = 0; _i < 2; ++_i) \
;         __builtin_amdgcn_global_load_lds((const unsigned*)((const char*)(gbase) + (voff)[_i]), (PG8_LAS unsigned*)(lds + (bufoff) + ldsw + _i * 8192), 16, 0, 0); } while (0)
; #define PG8_LDA(dst, b, h) do { _Pragma("unroll") for (int m = 0; m < 4; ++m) _Pragma("unroll") for (int k = 0; k < 2; ++k) dst[m][k] = *(const PG8_LAS bf16x8*)(lds + PG8_SA(b, h) + aoff + m * 2048 + k * 1024); } while (0)
; #define PG8_MMA(ai, bj, At, Bt) do { __builtin_amdgcn_s_setprio(1); _Pragma("unroll") for (int m = 0; m < 4; ++m) _Pragma("unroll") for (int n = 0; n < 2; ++n) _Pragma("unroll") for (int k = 0; k < 2; ++k) \
;         acc[ai][bj][m][n] = __builtin_amdgcn_mfma_f32_16x16x32_bf16(Bt[n][k], At[m][k], acc[ai][bj][m][n], 0, 0, 0); __builtin_amdgcn_s_setprio(0); } while (0)
; #define PG8_WAIT_V(n) asm volatile("s_waitcnt vmcnt(" #n ")" ::: "memory")
; #define PG8_WAIT_L(n) asm volatile("s_waitcnt lgkmcnt(" #n ")" ::: "memory")
; #define PG8_BAR __builtin_amdgcn_s_barrier()
; #define PG8_SCHED __builtin_amdgcn_sched_barrier(0)
; template <class Epi, class Sched, bool ALIGN_EPI = false, bool SP2 = false>
; __device__ __forceinline__ void gemm_phase(PG8_LAS unsigned char* lds, const Gemm g, const Sched& S, const Epi& E) {
;     ...
;         for (int t = 0; t < nt; t += 2) {
;             const bool last = (t == nt - 2);
;             const char* a1 = cA + (size_t)(t + 1) * kstep;
;             const char* a2 = last ? nA : cA + (size_t)(t + 2) * kstep; const char* b2 = last ? nB : cB + (size_t)(t + 2) * kstep;
;             const char* a3 = a2 + kstep; const char* b3 = b2 + kstep;
;     ...
;             PG8_LDA(At, 1, 1); PG8_STAGE(PG8_SB(1, 0), b3, voffB); PG8_STAGE(PG8_SB(1, 1), b3 + hstep, voffB); PG8_STAGE(PG8_SA(1, 0), a3, voffA);
;             PG8_WAIT_V(8); PG8_WAIT_L(0); PG8_BAR; PG8_MMA(1, 0, At, B0); PG8_MMA(1, 1, At, B1); PG8_BAR; PG8_SCHED;
	s_add_i32 s58, s90, s65
	v_lshl_add_u64 v[166:167], v[166:167], 0, s[38:39]
	s_mov_b32 m0, s58
	ds_read_b128 v[190:193], v146 offset:49152
	ds_read_b128 v[194:197], v146 offset:50176
	ds_read_b128 v[198:201], v146 offset:51200
	ds_read_b128 v[202:205], v146 offset:52224
	ds_read_b128 v[206:209], v146 offset:53248
	ds_read_b128 v[210:213], v146 offset:54272
	ds_read_b128 v[214:217], v146 offset:55296
	ds_read_b128 v[218:221], v146 offset:56320
	global_load_lds_dwordx4 v[166:167], off
	v_lshl_add_u64 v[166:167], v[222:223], 0, s[38:39]
	s_add_i32 m0, s58, 0x2000
	s_add_i32 s58, s91, s65
	global_load_lds_dwordx4 v[166:167], off
	v_lshl_add_u64 v[166:167], v[224:225], 0, s[38:39]
	s_mov_b32 m0, s58
	s_nop 0
	global_load_lds_dwordx4 v[166:167], off
	v_lshl_add_u64 v[166:167], v[226:227], 0, s[38:39]
	s_add_i32 m0, s58, 0x2000
	s_nop 0
	global_load_lds_dwordx4 v[166:167], off
	v_lshl_add_u64 v[166:167], v[228:229], 0, s[38:39]
	s_mov_b32 m0, s71
	s_nop 0
	global_load_lds_dwordx4 v[166:167], off
	v_lshl_add_u64 v[166:167], v[230:231], 0, s[38:39]
	s_mov_b32 m0, s72
	s_nop 0
	global_load_lds_dwordx4 v[166:167], off
	s_waitcnt vmcnt(8)
	s_waitcnt lgkmcnt(0)
	s_barrier
	s_setprio 1
	s_waitcnt lgkmcnt(0)
	v_mfma_f32_16x16x32_bf16 v[60:63], v[148:151], v[190:193], v[60:63]
	v_mfma_f32_16x16x32_bf16 v[56:59], v[156:159], v[190:193], v[56:59]
	v_mfma_f32_16x16x32_bf16 v[44:47], v[148:151], v[198:201], v[44:47]
	v_mfma_f32_16x16x32_bf16 v[40:43], v[156:159], v[198:201], v[40:43]
	v_mfma_f32_16x16x32_bf16 v[28:31], v[148:151], v[206:209], v[28:31]
	v_mfma_f32_16x16x32_bf16 v[24:27], v[156:159], v[206:209], v[24:27]
	v_mfma_f32_16x16x32_bf16 v[12:15], v[148:151], v[214:217], v[12:15]
	v_mfma_f32_16x16x32_bf16 v[8:11], v[156:159], v[214:217], v[8:11]
	v_mfma_f32_16x16x32_bf16 v[60:63], v[152:155], v[194:197], v[60:63]
	v_mfma_f32_16x16x32_bf16 v[56:59], v[162:165], v[194:197], v[56:59]
	v_mfma_f32_16x16x32_bf16 v[44:47], v[152:155], v[202:205], v[44:47]
	v_mfma_f32_16x16x32_bf16 v[40:43], v[162:165], v[202:205], v[40:43]
	v_mfma_f32_16x16x32_bf16 v[28:31], v[152:155], v[210:213], v[28:31]
	v_mfma_f32_16x16x32_bf16 v[24:27], v[162:165], v[210:213], v[24:27]
	v_mfma_f32_16x16x32_bf16 v[12:15], v[152:155], v[218:221], v[12:15]
	v_mfma_f32_16x16x32_bf16 v[8:11], v[162:165], v[218:221], v[8:11]
	s_setprio 0
	s_setprio 1
	v_mfma_f32_16x16x32_bf16 v[52:55], v[170:173], v[190:193], v[52:55]
	v_mfma_f32_16x16x32_bf16 v[48:51], v[182:185], v[190:193], v[48:51]
	v_mfma_f32_16x16x32_bf16 v[36:39], v[170:173], v[198:201], v[36:39]
	v_mfma_f32_16x16x32_bf16 v[32:35], v[182:185], v[198:201], v[32:35]
	v_mfma_f32_16x16x32_bf16 v[20:23], v[170:173], v[206:209], v[20:23]
	v_mfma_f32_16x16x32_bf16 v[16:19], v[182:185], v[206:209], v[16:19]
	v_mfma_f32_16x16x32_bf16 v[4:7], v[170:173], v[214:217], v[4:7]
	v_mfma_f32_16x16x32_bf16 v[0:3], v[182:185], v[214:217], v[0:3]
	v_mfma_f32_16x16x32_bf16 v[52:55], v[174:177], v[194:197], v[52:55]
	v_mfma_f32_16x16x32_bf16 v[48:51], v[186:189], v[194:197], v[48:51]
	v_mfma_f32_16x16x32_bf16 v[36:39], v[174:177], v[202:205], v[36:39]
	v_mfma_f32_16x16x32_bf16 v[32:35], v[186:189], v[202:205], v[32:35]
	v_mfma_f32_16x16x32_bf16 v[20:23], v[174:177], v[210:213], v[20:23]
	v_mfma_f32_16x16x32_bf16 v[16:19], v[186:189], v[210:213], v[16:19]
	v_mfma_f32_16x16x32_bf16 v[4:7], v[174:177], v[218:221], v[4:7]
	v_mfma_f32_16x16x32_bf16 v[0:3], v[186:189], v[218:221], v[0:3]
	s_setprio 0
	s_add_u32 s87, s87, 0x100
	s_addc_u32 s88, s88, 0
	s_add_u32 s56, s56, 0x100
	s_addc_u32 s57, s57, 0
	s_cmp_ge_i32 s89, s73
	s_mov_b32 s58, s89
	s_barrier
	s_cbranch_scc0 .LBB0_683

; #define PG8_STAGE(bufoff, gbase, voff) do { _Pragma("unroll") for (int _i = 0; _i < 2; ++_i) \
;         __builtin_amdgcn_global_load_lds((const unsigned*)((const char*)(gbase) + (voff)[_i]), (PG8_LAS unsigned*)(lds + (bufoff) + ldsw + _i * 8192), 16, 0, 0); } while (0)
; #define PG8_LDA(dst, b, h) do { _Pragma("unroll") for (int m = 0; m < 4; ++m) _Pragma("unroll") for (int k = 0; k < 2; ++k) dst[m][k] = *(const PG8_LAS bf16x8*)(lds + PG8_SA(b, h) + aoff + m * 2048 + k * 1024); } while (0)
; #define PG8_LDB(dst, b, h) do { _Pragma("unroll") for (int n = 0; n < 2; ++n) _Pragma("unroll") for (int k = 0; k < 2; ++k) dst[n][k] = *(const PG8_LAS bf16x8*)(lds + PG8_SB(b, h) + boff + n * 2048 + k * 1024); } while (0)
; #define PG8_MMA(ai, bj, At, Bt) do { __builtin_amdgcn_s_setprio(1); _Pragma("unroll") for (int m = 0; m < 4; ++m) _Pragma("unroll") for (int n = 0; n < 2; ++n) _Pragma("unroll") for (int k = 0; k < 2; ++k) \
;         acc[ai][bj][m][n] = __builtin_amdgcn_mfma_f32_16x16x32_bf16(Bt[n][k], At[m][k], acc[ai][bj][m][n], 0, 0, 0); __builtin_amdgcn_s_setprio(0); } while (0)
; #define PG8_WAIT_V(n) asm volatile("s_waitcnt vmcnt(" #n ")" ::: "memory")
; #define PG8_WAIT_L(n) asm volatile("s_waitcnt lgkmcnt(" #n ")" ::: "memory")
; #define PG8_BAR __builtin_amdgcn_s_barrier()
; #define PG8_SCHED __builtin_amdgcn_sched_barrier(0)
; template <class Epi, class Sched, bool ALIGN_EPI = false, bool SP2 = false>
; __device__ __forceinline__ void gemm_phase(PG8_LAS unsigned char* lds, const Gemm g, const Sched& S, const Epi& E) {
;     ...
;             PG8_LDB(B0, 0, 0); PG8_LDB(B1, 0, 1); PG8_SCHED; PG8_LDA(At, 0, 0); PG8_STAGE(PG8_SA(1, 1), a1 + hstep, voffA);
;             PG8_WAIT_V(8); PG8_WAIT_L(0); PG8_BAR; PG8_MMA(0, 0, At, B0); PG8_MMA(0, 1, At, B1); PG8_BAR; PG8_SCHED;
;             PG8_LDA(At, 0, 1); PG8_STAGE(PG8_SB(0, 0), b2, voffB); PG8_STAGE(PG8_SB(0, 1), b2 + hstep, voffB); PG8_STAGE(PG8_SA(0, 0), a2, voffA);
.LBB0_712:
	ds_read_b128 v[148:151], v141
	ds_read_b128 v[152:155], v141 offset:1024
	ds_read_b128 v[156:159], v141 offset:2048
	ds_read_b128 v[162:165], v141 offset:3072
	ds_read_b128 v[170:173], v143
	ds_read_b128 v[174:177], v143 offset:1024
	ds_read_b128 v[182:185], v143 offset:2048
	ds_read_b128 v[186:189], v143 offset:3072
	s_add_i32 s85, s56, 2
	s_add_u32 s86, s54, 0x80
	s_addc_u32 s57, s55, 0
	s_cmp_eq_u32 s70, s56
	s_cselect_b32 s56, s50, s86
	s_cselect_b32 s57, s51, s57
	s_cselect_b32 s87, s53, s84
	s_cselect_b32 s86, s52, s83
	v_lshl_add_u64 v[166:167], s[54:55], 0, v[136:137]
	s_add_i32 m0, s62, 0xc000
	ds_read_b128 v[190:193], v146
	ds_read_b128 v[194:197], v146 offset:1024
	ds_read_b128 v[198:201], v146 offset:2048
	ds_read_b128 v[202:205], v146 offset:3072
	ds_read_b128 v[206:209], v146 offset:4096
	ds_read_b128 v[210:213], v146 offset:5120
	ds_read_b128 v[214:217], v146 offset:6144
	ds_read_b128 v[218:221], v146 offset:7168
	global_load_lds_dwordx4 v[166:167], off
	v_lshl_add_u64 v[166:167], s[54:55], 0, v[134:135]
	s_add_i32 m0, s62, 0xe000
	s_nop 0
	global_load_lds_dwordx4 v[166:167], off
	s_waitcnt vmcnt(8)
	s_waitcnt lgkmcnt(0)
	s_barrier
	s_setprio 1
	s_waitcnt lgkmcnt(0)
	v_mfma_f32_16x16x32_bf16 v[124:127], v[148:151], v[190:193], v[124:127]
	v_mfma_f32_16x16x32_bf16 v[120:123], v[156:159], v[190:193], v[120:123]
	v_mfma_f32_16x16x32_bf16 v[108:111], v[148:151], v[198:201], v[108:111]
	v_mfma_f32_16x16x32_bf16 v[104:107], v[156:159], v[198:201], v[104:107]
	v_mfma_f32_16x16x32_bf16 v[92:95], v[148:151], v[206:209], v[92:95]
	v_mfma_f32_16x16x32_bf16 v[88:91], v[156:159], v[206:209], v[88:91]
	v_mfma_f32_16x16x32_bf16 v[76:79], v[148:151], v[214:217], v[76:79]
	v_mfma_f32_16x16x32_bf16 v[72:75], v[156:159], v[214:217], v[72:75]
	v_mfma_f32_16x16x32_bf16 v[124:127], v[152:155], v[194:197], v[124:127]
	v_mfma_f32_16x16x32_bf16 v[120:123], v[162:165], v[194:197], v[120:123]
	v_mfma_f32_16x16x32_bf16 v[108:111], v[152:155], v[202:205], v[108:111]
	v_mfma_f32_16x16x32_bf16 v[104:107], v[162:165], v[202:205], v[104:107]
	v_mfma_f32_16x16x32_bf16 v[92:95], v[152:155], v[210:213], v[92:95]
	v_mfma_f32_16x16x32_bf16 v[88:91], v[162:165], v[210:213], v[88:91]
	v_mfma_f32_16x16x32_bf16 v[76:79], v[152:155], v[218:221], v[76:79]
	v_mfma_f32_16x16x32_bf16 v[72:75], v[162:165], v[218:221], v[72:75]
	s_setprio 0
	s_setprio 1
	v_mfma_f32_16x16x32_bf16 v[116:119], v[170:173], v[190:193], v[116:119]
	v_mfma_f32_16x16x32_bf16 v[112:115], v[182:185], v[190:193], v[112:115]
	v_mfma_f32_16x16x32_bf16 v[100:103], v[170:173], v[198:201], v[100:103]
	v_mfma_f32_16x16x32_bf16 v[96:99], v[182:185], v[198:201], v[96:99]
	v_mfma_f32_16x16x32_bf16 v[84:87], v[170:173], v[206:209], v[84:87]
	v_mfma_f32_16x16x32_bf16 v[80:83], v[182:185], v[206:209], v[80:83]
	v_mfma_f32_16x16x32_bf16 v[68:71], v[170:173], v[214:217], v[68:71]
	v_mfma_f32_16x16x32_bf16 v[64:67], v[182:185], v[214:217], v[64:67]
	v_mfma_f32_16x16x32_bf16 v[116:119], v[174:177], v[194:197], v[116:119]
	v_mfma_f32_16x16x32_bf16 v[112:115], v[186:189], v[194:197], v[112:115]
	v_mfma_f32_16x16x32_bf16 v[100:103], v[174:177], v[202:205], v[100:103]
	v_mfma_f32_16x16x32_bf16 v[96:99], v[186:189], v[202:205], v[96:99]
	v_mfma_f32_16x16x32_bf16 v[84:87], v[174:177], v[210:213], v[84:87]
	v_mfma_f32_16x16x32_bf16 v[80:83], v[186:189], v[210:213], v[80:83]
	v_mfma_f32_16x16x32_bf16 v[68:71], v[174:177], v[218:221], v[68:71]
	v_mfma_f32_16x16x32_bf16 v[64:67], v[186:189], v[218:221], v[64:67]
	s_setprio 0
	s_barrier
	s_add_i32 s88, s73, s61
	v_lshl_add_u64 v[166:167], s[86:87], 0, v[130:131]
	s_mov_b32 m0, s88
	ds_read_b128 v[190:193], v146 offset:16384
	ds_read_b128 v[194:197], v146 offset:17408
	ds_read_b128 v[198:201], v146 offset:18432
	ds_read_b128 v[202:205], v146 offset:19456
	ds_read_b128 v[206:209], v146 offset:20480
	ds_read_b128 v[210:213], v146 offset:21504
	ds_read_b128 v[214:217], v146 offset:22528
	ds_read_b128 v[218:221], v146 offset:23552
	global_load_lds_dwordx4 v[166:167], off
	s_add_i32 m0, s88, 0x2000
	v_lshl_add_u64 v[222:223], s[86:87], 0, v[132:133]
	s_add_u32 s86, s86, s14
	s_addc_u32 s87, s87, s15
	s_add_i32 s88, s74, s61
	global_load_lds_dwordx4 v[222:223], off
	v_lshl_add_u64 v[224:225], s[86:87], 0, v[130:131]
	s_mov_b32 m0, s88
	v_lshl_add_u64 v[226:227], s[86:87], 0, v[132:133]
	global_load_lds_dwordx4 v[224:225], off
	s_add_i32 m0, s88, 0x2000
	v_lshl_add_u64 v[228:229], s[56:57], 0, v[130:131]
	global_load_lds_dwordx4 v[226:227], off
	s_mov_b32 m0, s62
	v_lshl_add_u64 v[230:231], s[56:57], 0, v[132:133]
	global_load_lds_dwordx4 v[228:229], off
	s_mov_b32 m0, s63
	s_nop 0
	global_load_lds_dwordx4 v[230:231], off
	s_waitcnt vmcnt(8)
	s_waitcnt lgkmcnt(0)
	s_barrier
; #define PG8_STAGE(bufoff, gbase, voff) do { _Pragma("unroll") for (int _i = 0; _i < 2; ++_i) \
;         __builtin_amdgcn_global_load_lds((const unsigned*)((const char*)(gbase) + (voff)[_i]), (PG8_LAS unsigned*)(lds + (bufoff) + ldsw + _i * 8192), 16, 0, 0); } while (0)
; #define PG8_LDA(dst, b, h) do { _Pragma("unroll") for (int m = 0; m < 4; ++m) _Pragma("unroll") for (int k = 0; k < 2; ++k) dst[m][k] = *(const PG8_LAS bf16x8*)(lds + PG8_SA(b, h) + aoff + m * 2048 + k * 1024); } while (0)
; #define PG8_LDB(dst, b, h) do { _Pragma("unroll") for (int n = 0; n < 2; ++n) _Pragma("unroll") for (int k = 0; k < 2; ++k) dst[n][k] = *(const PG8_LAS bf16x8*)(lds + PG8_SB(b, h) + boff + n * 2048 + k * 1024); } while (0)
; #define PG8_MMA(ai, bj, At, Bt) do { __builtin_amdgcn_s_setprio(1); _Pragma("unroll") for (int m = 0; m < 4; ++m) _Pragma("unroll") for (int n = 0; n < 2; ++n) _Pragma("unroll") for (int k = 0; k < 2; ++k) \
;         acc[ai][bj][m][n] = __builtin_amdgcn_mfma_f32_16x16x32_bf16(Bt[n][k], At[m][k], acc[ai][bj][m][n], 0, 0, 0); __builtin_amdgcn_s_setprio(0); } while (0)
; #define PG8_WAIT_V(n) asm volatile("s_waitcnt vmcnt(" #n ")" ::: "memory")
; #define PG8_WAIT_L(n) asm volatile("s_waitcnt lgkmcnt(" #n ")" ::: "memory")
; #define PG8_BAR __builtin_amdgcn_s_barrier()
; #define PG8_SCHED __builtin_amdgcn_sched_barrier(0)
; template <class Epi, class Sched, bool ALIGN_EPI = false, bool SP2 = false>
; __device__ __forceinline__ void gemm_phase(PG8_LAS unsigned char* lds, const Gemm g, const Sched& S, const Epi& E) {
;     ...
;             PG8_WAIT_V(8); PG8_WAIT_L(0); PG8_BAR; PG8_MMA(1, 0, At, B0); PG8_MMA(1, 1, At, B1); PG8_BAR; PG8_SCHED;
;             PG8_LDB(B0, 1, 0); PG8_LDB(B1, 1, 1); PG8_SCHED; PG8_LDA(At, 1, 0); PG8_STAGE(PG8_SA(0, 1), a2 + hstep, voffA);
;             PG8_WAIT_V(8); PG8_WAIT_L(0); PG8_BAR; PG8_MMA(0, 0, At, B0); PG8_MMA(0, 1, At, B1); PG8_BAR; PG8_SCHED;
	s_setprio 1
	s_waitcnt lgkmcnt(0)
	v_mfma_f32_16x16x32_bf16 v[60:63], v[148:151], v[190:193], v[60:63]
	v_mfma_f32_16x16x32_bf16 v[56:59], v[156:159], v[190:193], v[56:59]
	v_mfma_f32_16x16x32_bf16 v[44:47], v[148:151], v[198:201], v[44:47]
	v_mfma_f32_16x16x32_bf16 v[40:43], v[156:159], v[198:201], v[40:43]
	v_mfma_f32_16x16x32_bf16 v[28:31], v[148:151], v[206:209], v[28:31]
	v_mfma_f32_16x16x32_bf16 v[24:27], v[156:159], v[206:209], v[24:27]
	v_mfma_f32_16x16x32_bf16 v[12:15], v[148:151], v[214:217], v[12:15]
	v_mfma_f32_16x16x32_bf16 v[8:11], v[156:159], v[214:217], v[8:11]
	v_mfma_f32_16x16x32_bf16 v[60:63], v[152:155], v[194:197], v[60:63]
	v_mfma_f32_16x16x32_bf16 v[56:59], v[162:165], v[194:197], v[56:59]
	v_mfma_f32_16x16x32_bf16 v[44:47], v[152:155], v[202:205], v[44:47]
	v_mfma_f32_16x16x32_bf16 v[40:43], v[162:165], v[202:205], v[40:43]
	v_mfma_f32_16x16x32_bf16 v[28:31], v[152:155], v[210:213], v[28:31]
	v_mfma_f32_16x16x32_bf16 v[24:27], v[162:165], v[210:213], v[24:27]
	v_mfma_f32_16x16x32_bf16 v[12:15], v[152:155], v[218:221], v[12:15]
	v_mfma_f32_16x16x32_bf16 v[8:11], v[162:165], v[218:221], v[8:11]
	s_setprio 0
	s_setprio 1
	v_mfma_f32_16x16x32_bf16 v[52:55], v[170:173], v[190:193], v[52:55]
	v_mfma_f32_16x16x32_bf16 v[48:51], v[182:185], v[190:193], v[48:51]
	v_mfma_f32_16x16x32_bf16 v[36:39], v[170:173], v[198:201], v[36:39]
	v_mfma_f32_16x16x32_bf16 v[32:35], v[182:185], v[198:201], v[32:35]
	v_mfma_f32_16x16x32_bf16 v[20:23], v[170:173], v[206:209], v[20:23]
	v_mfma_f32_16x16x32_bf16 v[16:19], v[182:185], v[206:209], v[16:19]
	v_mfma_f32_16x16x32_bf16 v[4:7], v[170:173], v[214:217], v[4:7]
	v_mfma_f32_16x16x32_bf16 v[0:3], v[182:185], v[214:217], v[0:3]
	v_mfma_f32_16x16x32_bf16 v[52:55], v[174:177], v[194:197], v[52:55]
	v_mfma_f32_16x16x32_bf16 v[48:51], v[186:189], v[194:197], v[48:51]
	v_mfma_f32_16x16x32_bf16 v[36:39], v[174:177], v[202:205], v[36:39]
	v_mfma_f32_16x16x32_bf16 v[32:35], v[186:189], v[202:205], v[32:35]
	v_mfma_f32_16x16x32_bf16 v[20:23], v[174:177], v[210:213], v[20:23]
	v_mfma_f32_16x16x32_bf16 v[16:19], v[186:189], v[210:213], v[16:19]
	v_mfma_f32_16x16x32_bf16 v[4:7], v[174:177], v[218:221], v[4:7]
	v_mfma_f32_16x16x32_bf16 v[0:3], v[186:189], v[218:221], v[0:3]
	s_setprio 0
	s_barrier
	s_add_i32 s86, 0, 0x18000
	v_add_u32_e32 v147, s86, v138
	s_add_i32 s87, 0, 0x1c000
	ds_read_b128 v[148:151], v147
	ds_read_b128 v[152:155], v147 offset:1024
	ds_read_b128 v[156:159], v147 offset:2048
	ds_read_b128 v[162:165], v147 offset:3072
	v_add_u32_e32 v147, s87, v138
	ds_read_b128 v[170:173], v147
	ds_read_b128 v[174:177], v147 offset:1024
	ds_read_b128 v[182:185], v147 offset:2048
	ds_read_b128 v[186:189], v147 offset:3072
	s_add_u32 s56, s56, s14
	s_addc_u32 s57, s57, s15
	s_mov_b32 m0, s64
	v_lshl_add_u64 v[232:233], s[56:57], 0, v[130:131]
	ds_read_b128 v[190:193], v146 offset:32768
	ds_read_b128 v[194:197], v146 offset:33792
	ds_read_b128 v[198:201], v146 offset:34816
	ds_read_b128 v[202:205], v146 offset:35840
	ds_read_b128 v[206:209], v146 offset:36864
	ds_read_b128 v[210:213], v146 offset:37888
	ds_read_b128 v[214:217], v146 offset:38912
	ds_read_b128 v[218:221], v146 offset:39936
	global_load_lds_dwordx4 v[232:233], off
	v_lshl_add_u64 v[232:233], s[56:57], 0, v[132:133]
	s_mov_b32 m0, s65
	s_nop 0
	global_load_lds_dwordx4 v[232:233], off
	s_waitcnt vmcnt(8)
	s_waitcnt lgkmcnt(0)
	s_barrier
	s_setprio 1
	s_waitcnt lgkmcnt(0)
	v_mfma_f32_16x16x32_bf16 v[124:127], v[148:151], v[190:193], v[124:127]
	v_mfma_f32_16x16x32_bf16 v[120:123], v[156:159], v[190:193], v[120:123]
	v_mfma_f32_16x16x32_bf16 v[108:111], v[148:151], v[198:201], v[108:111]
	v_mfma_f32_16x16x32_bf16 v[104:107], v[156:159], v[198:201], v[104:107]
	v_mfma_f32_16x16x32_bf16 v[92:95], v[148:151], v[206:209], v[92:95]
	v_mfma_f32_16x16x32_bf16 v[88:91], v[156:159], v[206:209], v[88:91]
	v_mfma_f32_16x16x32_bf16 v[76:79], v[148:151], v[214:217], v[76:79]
	v_mfma_f32_16x16x32_bf16 v[72:75], v[156:159], v[214:217], v[72:75]
	v_mfma_f32_16x16x32_bf16 v[124:127], v[152:155], v[194:197], v[124:127]
	v_mfma_f32_16x16x32_bf16 v[120:123], v[162:165], v[194:197], v[120:123]
	v_mfma_f32_16x16x32_bf16 v[108:111], v[152:155], v[202:205], v[108:111]
	v_mfma_f32_16x16x32_bf16 v[104:107], v[162:165], v[202:205], v[104:107]
	v_mfma_f32_16x16x32_bf16 v[92:95], v[152:155], v[210:213], v[92:95]
	v_mfma_f32_16x16x32_bf16 v[88:91], v[162:165], v[210:213], v[88:91]
	v_mfma_f32_16x16x32_bf16 v[76:79], v[152:155], v[218:221], v[76:79]
	v_mfma_f32_16x16x32_bf16 v[72:75], v[162:165], v[218:221], v[72:75]
	s_setprio 0
	s_setprio 1
	v_mfma_f32_16x16x32_bf16 v[116:119], v[170:173], v[190:193], v[116:119]
	v_mfma_f32_16x16x32_bf16 v[112:115], v[182:185], v[190:193], v[112:115]
	v_mfma_f32_16x16x32_bf16 v[100:103], v[170:173], v[198:201], v[100:103]
	v_mfma_f32_16x16x32_bf16 v[96:99], v[182:185], v[198:201], v[96:99]
	v_mfma_f32_16x16x32_bf16 v[84:87], v[170:173], v[206:209], v[84:87]
	v_mfma_f32_16x16x32_bf16 v[80:83], v[182:185], v[206:209], v[80:83]
	v_mfma_f32_16x16x32_bf16 v[68:71], v[170:173], v[214:217], v[68:71]
	v_mfma_f32_16x16x32_bf16 v[64:67], v[182:185], v[214:217], v[64:67]
	v_mfma_f32_16x16x32_bf16 v[116:119], v[174:177], v[194:197], v[116:119]
	v_mfma_f32_16x16x32_bf16 v[112:115], v[186:189], v[194:197], v[112:115]
	v_mfma_f32_16x16x32_bf16 v[100:103], v[174:177], v[202:205], v[100:103]
	v_mfma_f32_16x16x32_bf16 v[96:99], v[186:189], v[202:205], v[96:99]
	v_mfma_f32_16x16x32_bf16 v[84:87], v[174:177], v[210:213], v[84:87]
	v_mfma_f32_16x16x32_bf16 v[80:83], v[186:189], v[210:213], v[80:83]
	v_mfma_f32_16x16x32_bf16 v[68:71], v[174:177], v[218:221], v[68:71]
	v_mfma_f32_16x16x32_bf16 v[64:67], v[186:189], v[218:221], v[64:67]
	s_setprio 0
	s_barrier
; #define PG8_STAGE(bufoff, gbase, voff) do { _Pragma("unroll") for (int _i = 0; _i < 2; ++_i) \
;         __builtin_amdgcn_global_load_lds((const unsigned*)((const char*)(gbase) + (voff)[_i]), (PG8_LAS unsigned*)(lds + (bufoff) + ldsw + _i * 8192), 16, 0, 0); } while (0)
; #define PG8_LDA(dst, b, h) do { _Pragma("unroll") for (int m = 0; m < 4; ++m) _Pragma("unroll") for (int k = 0; k < 2; ++k) dst[m][k] = *(const PG8_LAS bf16x8*)(lds + PG8_SA(b, h) + aoff + m * 2048 + k * 1024); } while (0)
; #define PG8_MMA(ai, bj, At, Bt) do { __builtin_amdgcn_s_setprio(1); _Pragma("unroll") for (int m = 0; m < 4; ++m) _Pragma("unroll") for (int n = 0; n < 2; ++n) _Pragma("unroll") for (int k = 0; k < 2; ++k) \
;         acc[ai][bj][m][n] = __builtin_amdgcn_mfma_f32_16x16x32_bf16(Bt[n][k], At[m][k], acc[ai][bj][m][n], 0, 0, 0); __builtin_amdgcn_s_setprio(0); } while (0)
; #define PG8_WAIT_V(n) asm volatile("s_waitcnt vmcnt(" #n ")" ::: "memory")
; #define PG8_WAIT_L(n) asm volatile("s_waitcnt lgkmcnt(" #n ")" ::: "memory")
; #define PG8_BAR __builtin_amdgcn_s_barrier()
; #define PG8_SCHED __builtin_amdgcn_sched_barrier(0)
; template <class Epi, class Sched, bool ALIGN_EPI = false, bool SP2 = false>
; __device__ __forceinline__ void gemm_phase(PG8_LAS unsigned char* lds, const Gemm g, const Sched& S, const Epi& E) {
;     ...
;         for (int t = 0; t < nt; t += 2) {
;             const bool last = (t == nt - 2);
;             const char* a1 = cA + (size_t)(t + 1) * kstep;
;             const char* a2 = last ? nA : cA + (size_t)(t + 2) * kstep; const char* b2 = last ? nB : cB + (size_t)(t + 2) * kstep;
;             const char* a3 = a2 + kstep; const char* b3 = b2 + kstep;
;     ...
;             PG8_LDA(At, 1, 1); PG8_STAGE(PG8_SB(1, 0), b3, voffB); PG8_STAGE(PG8_SB(1, 1), b3 + hstep, voffB); PG8_STAGE(PG8_SA(1, 0), a3, voffA);
;             PG8_WAIT_V(8); PG8_WAIT_L(0); PG8_BAR; PG8_MMA(1, 0, At, B0); PG8_MMA(1, 1, At, B1); PG8_BAR; PG8_SCHED;
	s_add_i32 s56, s86, s61
	v_lshl_add_u64 v[166:167], v[166:167], 0, s[38:39]
	s_mov_b32 m0, s56
	ds_read_b128 v[190:193], v146 offset:49152
	ds_read_b128 v[194:197], v146 offset:50176
	ds_read_b128 v[198:201], v146 offset:51200
	ds_read_b128 v[202:205], v146 offset:52224
	ds_read_b128 v[206:209], v146 offset:53248
	ds_read_b128 v[210:213], v146 offset:54272
	ds_read_b128 v[214:217], v146 offset:55296
	ds_read_b128 v[218:221], v146 offset:56320
	global_load_lds_dwordx4 v[166:167], off
	v_lshl_add_u64 v[166:167], v[222:223], 0, s[38:39]
	s_add_i32 m0, s56, 0x2000
	s_add_i32 s56, s87, s61
	global_load_lds_dwordx4 v[166:167], off
	v_lshl_add_u64 v[166:167], v[224:225], 0, s[38:39]
	s_mov_b32 m0, s56
	s_nop 0
	global_load_lds_dwordx4 v[166:167], off
	v_lshl_add_u64 v[166:167], v[226:227], 0, s[38:39]
	s_add_i32 m0, s56, 0x2000
	s_nop 0
	global_load_lds_dwordx4 v[166:167], off
	v_lshl_add_u64 v[166:167], v[228:229], 0, s[38:39]
	s_mov_b32 m0, s67
	s_nop 0
	global_load_lds_dwordx4 v[166:167], off
	v_lshl_add_u64 v[166:167], v[230:231], 0, s[38:39]
	s_mov_b32 m0, s68
	s_nop 0
	global_load_lds_dwordx4 v[166:167], off
	s_waitcnt vmcnt(8)
	s_waitcnt lgkmcnt(0)
	s_barrier
	s_setprio 1
	s_waitcnt lgkmcnt(0)
	v_mfma_f32_16x16x32_bf16 v[60:63], v[148:151], v[190:193], v[60:63]
	v_mfma_f32_16x16x32_bf16 v[56:59], v[156:159], v[190:193], v[56:59]
	v_mfma_f32_16x16x32_bf16 v[44:47], v[148:151], v[198:201], v[44:47]
	v_mfma_f32_16x16x32_bf16 v[40:43], v[156:159], v[198:201], v[40:43]
	v_mfma_f32_16x16x32_bf16 v[28:31], v[148:151], v[206:209], v[28:31]
	v_mfma_f32_16x16x32_bf16 v[24:27], v[156:159], v[206:209], v[24:27]
	v_mfma_f32_16x16x32_bf16 v[12:15], v[148:151], v[214:217], v[12:15]
	v_mfma_f32_16x16x32_bf16 v[8:11], v[156:159], v[214:217], v[8:11]
	v_mfma_f32_16x16x32_bf16 v[60:63], v[152:155], v[194:197], v[60:63]
	v_mfma_f32_16x16x32_bf16 v[56:59], v[162:165], v[194:197], v[56:59]
	v_mfma_f32_16x16x32_bf16 v[44:47], v[152:155], v[202:205], v[44:47]
	v_mfma_f32_16x16x32_bf16 v[40:43], v[162:165], v[202:205], v[40:43]
	v_mfma_f32_16x16x32_bf16 v[28:31], v[152:155], v[210:213], v[28:31]
	v_mfma_f32_16x16x32_bf16 v[24:27], v[162:165], v[210:213], v[24:27]
	v_mfma_f32_16x16x32_bf16 v[12:15], v[152:155], v[218:221], v[12:15]
	v_mfma_f32_16x16x32_bf16 v[8:11], v[162:165], v[218:221], v[8:11]
	s_setprio 0
	s_setprio 1
	v_mfma_f32_16x16x32_bf16 v[52:55], v[170:173], v[190:193], v[52:55]
	v_mfma_f32_16x16x32_bf16 v[48:51], v[182:185], v[190:193], v[48:51]
	v_mfma_f32_16x16x32_bf16 v[36:39], v[170:173], v[198:201], v[36:39]
	v_mfma_f32_16x16x32_bf16 v[32:35], v[182:185], v[198:201], v[32:35]
	v_mfma_f32_16x16x32_bf16 v[20:23], v[170:173], v[206:209], v[20:23]
	v_mfma_f32_16x16x32_bf16 v[16:19], v[182:185], v[206:209], v[16:19]
	v_mfma_f32_16x16x32_bf16 v[4:7], v[170:173], v[214:217], v[4:7]
	v_mfma_f32_16x16x32_bf16 v[0:3], v[182:185], v[214:217], v[0:3]
	v_mfma_f32_16x16x32_bf16 v[52:55], v[174:177], v[194:197], v[52:55]
	v_mfma_f32_16x16x32_bf16 v[48:51], v[186:189], v[194:197], v[48:51]
	v_mfma_f32_16x16x32_bf16 v[36:39], v[174:177], v[202:205], v[36:39]
	v_mfma_f32_16x16x32_bf16 v[32:35], v[186:189], v[202:205], v[32:35]
	v_mfma_f32_16x16x32_bf16 v[20:23], v[174:177], v[210:213], v[20:23]
	v_mfma_f32_16x16x32_bf16 v[16:19], v[186:189], v[210:213], v[16:19]
	v_mfma_f32_16x16x32_bf16 v[4:7], v[174:177], v[218:221], v[4:7]
	v_mfma_f32_16x16x32_bf16 v[0:3], v[186:189], v[218:221], v[0:3]
	s_setprio 0
	s_add_u32 s83, s83, 0x100
	s_addc_u32 s84, s84, 0
	s_add_u32 s54, s54, 0x100
	s_addc_u32 s55, s55, 0
	s_cmp_ge_i32 s85, s69
	s_mov_b32 s56, s85
	s_barrier
	s_cbranch_scc0 .LBB0_712

; #define PG8_STAGE(bufoff, gbase, voff) do { _Pragma("unroll") for (int _i = 0; _i < 2; ++_i) \
;         __builtin_amdgcn_global_load_lds((const unsigned*)((const char*)(gbase) + (voff)[_i]), (PG8_LAS unsigned*)(lds + (bufoff) + ldsw + _i * 8192), 16, 0, 0); } while (0)
; #define PG8_LDA(dst, b, h) do { _Pragma("unroll") for (int m = 0; m < 4; ++m) _Pragma("unroll") for (int k = 0; k < 2; ++k) dst[m][k] = *(const PG8_LAS bf16x8*)(lds + PG8_SA(b, h) + aoff + m * 2048 + k * 1024); } while (0)
; #define PG8_LDB(dst, b, h) do { _Pragma("unroll") for (int n = 0; n < 2; ++n) _Pragma("unroll") for (int k = 0; k < 2; ++k) dst[n][k] = *(const PG8_LAS bf16x8*)(lds + PG8_SB(b, h) + boff + n * 2048 + k * 1024); } while (0)
; #define PG8_MMA(ai, bj, At, Bt) do { __builtin_amdgcn_s_setprio(1); _Pragma("unroll") for (int m = 0; m < 4; ++m) _Pragma("unroll") for (int n = 0; n < 2; ++n) _Pragma("unroll") for (int k = 0; k < 2; ++k) \
;         acc[ai][bj][m][n] = __builtin_amdgcn_mfma_f32_16x16x32_bf16(Bt[n][k], At[m][k], acc[ai][bj][m][n], 0, 0, 0); __builtin_amdgcn_s_setprio(0); } while (0)
; #define PG8_WAIT_V(n) asm volatile("s_waitcnt vmcnt(" #n ")" ::: "memory")
; #define PG8_WAIT_L(n) asm volatile("s_waitcnt lgkmcnt(" #n ")" ::: "memory")
; #define PG8_BAR __builtin_amdgcn_s_barrier()
; #define PG8_SCHED __builtin_amdgcn_sched_barrier(0)
; template <class Epi, class Sched, bool ALIGN_EPI = false, bool SP2 = false>
; __device__ __forceinline__ void gemm_phase(PG8_LAS unsigned char* lds, const Gemm g, const Sched& S, const Epi& E) {
;     ...
;         for (int t = 0; t < nt; t += 2) {
;             const bool last = (t == nt - 2);
;             const char* a1 = cA + (size_t)(t + 1) * kstep;
;             const char* a2 = last ? nA : cA + (size_t)(t + 2) * kstep; const char* b2 = last ? nB : cB + (size_t)(t + 2) * kstep;
;             const char* a3 = a2 + kstep; const char* b3 = b2 + kstep;
;             if (last && has_next) S.a_ready(nxt);
;             if constexpr (SP2) {
;             PG8_LDB(B0, 0, 0); PG8_LDB(B1, 0, 1); PG8_SCHED; PG8_LDA(At, 0, 0); PG8_STAGE(PG8_SA(1, 1), a1 + hstep, voffA);
;             PG8_WAIT_V(8); PG8_WAIT_L(0); PG8_BAR; PG8_MMA(0, 0, At, B0); PG8_MMA(0, 1, At, B1); PG8_BAR; PG8_SCHED;
;             PG8_LDA(At, 0, 1); PG8_STAGE(PG8_SB(0, 0), b2, voffB); PG8_STAGE(PG8_SB(0, 1), b2 + hstep, voffB); PG8_STAGE(PG8_SA(0, 0), a2, voffA);
.LBB0_741:
	ds_read_b128 v[152:155], v161
	ds_read_b128 v[156:159], v161 offset:1024
	ds_read_b128 v[164:167], v161 offset:2048
	ds_read_b128 v[170:173], v161 offset:3072
	ds_read_b128 v[174:177], v162
	ds_read_b128 v[182:185], v162 offset:1024
	ds_read_b128 v[186:189], v162 offset:2048
	ds_read_b128 v[190:193], v162 offset:3072
	s_add_i32 s80, s52, 2
	s_add_u32 s81, s50, 0x80
	s_addc_u32 s53, s51, 0
	s_cmp_eq_u32 s67, s52
	s_cselect_b32 s52, s8, s81
	s_cselect_b32 s53, s9, s53
	s_cselect_b32 s83, s49, s79
	s_cselect_b32 s82, s48, s78
	v_lshl_add_u64 v[226:227], s[50:51], 0, v[146:147]
	s_add_i32 m0, s58, 0xc000
	ds_read_b128 v[194:197], v163
	ds_read_b128 v[198:201], v163 offset:1024
	ds_read_b128 v[202:205], v163 offset:2048
	ds_read_b128 v[206:209], v163 offset:3072
	ds_read_b128 v[210:213], v163 offset:4096
	ds_read_b128 v[214:217], v163 offset:5120
	ds_read_b128 v[218:221], v163 offset:6144
	ds_read_b128 v[222:225], v163 offset:7168
	global_load_lds_dwordx4 v[226:227], off
	v_lshl_add_u64 v[226:227], s[50:51], 0, v[138:139]
	s_add_i32 m0, s58, 0xe000
	s_nop 0
	global_load_lds_dwordx4 v[226:227], off
	s_waitcnt vmcnt(8)
	s_waitcnt lgkmcnt(0)
	s_barrier
	s_setprio 1
	s_waitcnt lgkmcnt(0)
	v_mfma_f32_16x16x32_bf16 v[124:127], v[152:155], v[194:197], v[124:127]
	v_mfma_f32_16x16x32_bf16 v[120:123], v[164:167], v[194:197], v[120:123]
	v_mfma_f32_16x16x32_bf16 v[116:119], v[152:155], v[202:205], v[116:119]
	v_mfma_f32_16x16x32_bf16 v[112:115], v[164:167], v[202:205], v[112:115]
	v_mfma_f32_16x16x32_bf16 v[104:107], v[152:155], v[210:213], v[104:107]
	v_mfma_f32_16x16x32_bf16 v[96:99], v[164:167], v[210:213], v[96:99]
	v_mfma_f32_16x16x32_bf16 v[88:91], v[152:155], v[218:221], v[88:91]
	v_mfma_f32_16x16x32_bf16 v[80:83], v[164:167], v[218:221], v[80:83]
	v_mfma_f32_16x16x32_bf16 v[124:127], v[156:159], v[198:201], v[124:127]
	v_mfma_f32_16x16x32_bf16 v[120:123], v[170:173], v[198:201], v[120:123]
	v_mfma_f32_16x16x32_bf16 v[116:119], v[156:159], v[206:209], v[116:119]
	v_mfma_f32_16x16x32_bf16 v[112:115], v[170:173], v[206:209], v[112:115]
	v_mfma_f32_16x16x32_bf16 v[104:107], v[156:159], v[214:217], v[104:107]
	v_mfma_f32_16x16x32_bf16 v[96:99], v[170:173], v[214:217], v[96:99]
	v_mfma_f32_16x16x32_bf16 v[88:91], v[156:159], v[222:225], v[88:91]
	v_mfma_f32_16x16x32_bf16 v[80:83], v[170:173], v[222:225], v[80:83]
	s_setprio 0
	s_setprio 1
	v_mfma_f32_16x16x32_bf16 v[108:111], v[174:177], v[194:197], v[108:111]
	v_mfma_f32_16x16x32_bf16 v[100:103], v[186:189], v[194:197], v[100:103]
	v_mfma_f32_16x16x32_bf16 v[92:95], v[174:177], v[202:205], v[92:95]
	v_mfma_f32_16x16x32_bf16 v[84:87], v[186:189], v[202:205], v[84:87]
	v_mfma_f32_16x16x32_bf16 v[76:79], v[174:177], v[210:213], v[76:79]
	v_mfma_f32_16x16x32_bf16 v[72:75], v[186:189], v[210:213], v[72:75]
	v_mfma_f32_16x16x32_bf16 v[68:71], v[174:177], v[218:221], v[68:71]
	v_mfma_f32_16x16x32_bf16 v[64:67], v[186:189], v[218:221], v[64:67]
	v_mfma_f32_16x16x32_bf16 v[108:111], v[182:185], v[198:201], v[108:111]
	v_mfma_f32_16x16x32_bf16 v[100:103], v[190:193], v[198:201], v[100:103]
	v_mfma_f32_16x16x32_bf16 v[92:95], v[182:185], v[206:209], v[92:95]
	v_mfma_f32_16x16x32_bf16 v[84:87], v[190:193], v[206:209], v[84:87]
	v_mfma_f32_16x16x32_bf16 v[76:79], v[182:185], v[214:217], v[76:79]
	v_mfma_f32_16x16x32_bf16 v[72:75], v[190:193], v[214:217], v[72:75]
	v_mfma_f32_16x16x32_bf16 v[68:71], v[182:185], v[222:225], v[68:71]
	v_mfma_f32_16x16x32_bf16 v[64:67], v[190:193], v[222:225], v[64:67]
	s_setprio 0
	s_barrier
	s_add_i32 s81, s69, s57
	v_lshl_add_u64 v[226:227], s[82:83], 0, v[132:133]
	s_mov_b32 m0, s81
	ds_read_b128 v[194:197], v163 offset:16384
	ds_read_b128 v[198:201], v163 offset:17408
	ds_read_b128 v[202:205], v163 offset:18432
	ds_read_b128 v[206:209], v163 offset:19456
	ds_read_b128 v[210:213], v163 offset:20480
	ds_read_b128 v[214:217], v163 offset:21504
	ds_read_b128 v[218:221], v163 offset:22528
	ds_read_b128 v[222:225], v163 offset:23552
	global_load_lds_dwordx4 v[226:227], off
	s_add_i32 m0, s81, 0x2000
	v_lshl_add_u64 v[228:229], s[82:83], 0, v[136:137]
	s_add_u32 s82, s82, s12
	s_addc_u32 s83, s83, s13
	s_add_i32 s81, s70, s57
	global_load_lds_dwordx4 v[228:229], off
	v_lshl_add_u64 v[230:231], s[82:83], 0, v[132:133]
	s_mov_b32 m0, s81
	v_lshl_add_u64 v[232:233], s[82:83], 0, v[136:137]
	global_load_lds_dwordx4 v[230:231], off
	s_add_i32 m0, s81, 0x2000
	v_lshl_add_u64 v[234:235], s[52:53], 0, v[130:131]
	global_load_lds_dwordx4 v[232:233], off
	s_mov_b32 m0, s58
	v_lshl_add_u64 v[236:237], s[52:53], 0, v[134:135]
	global_load_lds_dwordx4 v[234:235], off
	s_mov_b32 m0, s59
	s_nop 0
	global_load_lds_dwordx4 v[236:237], off
	s_waitcnt vmcnt(8)
	s_waitcnt lgkmcnt(0)
	s_barrier
; #define PG8_STAGE(bufoff, gbase, voff) do { _Pragma("unroll") for (int _i = 0; _i < 2; ++_i) \
;         __builtin_amdgcn_global_load_lds((const unsigned*)((const char*)(gbase) + (voff)[_i]), (PG8_LAS unsigned*)(lds + (bufoff) + ldsw + _i * 8192), 16, 0, 0); } while (0)
; #define PG8_LDA(dst, b, h) do { _Pragma("unroll") for (int m = 0; m < 4; ++m) _Pragma("unroll") for (int k = 0; k < 2; ++k) dst[m][k] = *(const PG8_LAS bf16x8*)(lds + PG8_SA(b, h) + aoff + m * 2048 + k * 1024); } while (0)
; #define PG8_LDB(dst, b, h) do { _Pragma("unroll") for (int n = 0; n < 2; ++n) _Pragma("unroll") for (int k = 0; k < 2; ++k) dst[n][k] = *(const PG8_LAS bf16x8*)(lds + PG8_SB(b, h) + boff + n * 2048 + k * 1024); } while (0)
; #define PG8_MMA(ai, bj, At, Bt) do { __builtin_amdgcn_s_setprio(1); _Pragma("unroll") for (int m = 0; m < 4; ++m) _Pragma("unroll") for (int n = 0; n < 2; ++n) _Pragma("unroll") for (int k = 0; k < 2; ++k) \
;         acc[ai][bj][m][n] = __builtin_amdgcn_mfma_f32_16x16x32_bf16(Bt[n][k], At[m][k], acc[ai][bj][m][n], 0, 0, 0); __builtin_amdgcn_s_setprio(0); } while (0)
; #define PG8_WAIT_V(n) asm volatile("s_waitcnt vmcnt(" #n ")" ::: "memory")
; #define PG8_WAIT_L(n) asm volatile("s_waitcnt lgkmcnt(" #n ")" ::: "memory")
; #define PG8_BAR __builtin_amdgcn_s_barrier()
; #define PG8_SCHED __builtin_amdgcn_sched_barrier(0)
; template <class Epi, class Sched, bool ALIGN_EPI = false, bool SP2 = false>
; __device__ __forceinline__ void gemm_phase(PG8_LAS unsigned char* lds, const Gemm g, const Sched& S, const Epi& E) {
;     ...
;             PG8_WAIT_V(8); PG8_WAIT_L(0); PG8_BAR; PG8_MMA(1, 0, At, B0); PG8_MMA(1, 1, At, B1); PG8_BAR; PG8_SCHED;
;             PG8_LDB(B0, 1, 0); PG8_LDB(B1, 1, 1); PG8_SCHED; PG8_LDA(At, 1, 0); PG8_STAGE(PG8_SA(0, 1), a2 + hstep, voffA);
;             PG8_WAIT_V(8); PG8_WAIT_L(0); PG8_BAR; PG8_MMA(0, 0, At, B0); PG8_MMA(0, 1, At, B1); PG8_BAR; PG8_SCHED;
	s_setprio 1
	s_waitcnt lgkmcnt(0)
	v_mfma_f32_16x16x32_bf16 v[60:63], v[152:155], v[194:197], v[60:63]
	v_mfma_f32_16x16x32_bf16 v[56:59], v[164:167], v[194:197], v[56:59]
	v_mfma_f32_16x16x32_bf16 v[52:55], v[152:155], v[202:205], v[52:55]
	v_mfma_f32_16x16x32_bf16 v[48:51], v[164:167], v[202:205], v[48:51]
	v_mfma_f32_16x16x32_bf16 v[40:43], v[152:155], v[210:213], v[40:43]
	v_mfma_f32_16x16x32_bf16 v[32:35], v[164:167], v[210:213], v[32:35]
	v_mfma_f32_16x16x32_bf16 v[24:27], v[152:155], v[218:221], v[24:27]
	v_mfma_f32_16x16x32_bf16 v[16:19], v[164:167], v[218:221], v[16:19]
	v_mfma_f32_16x16x32_bf16 v[60:63], v[156:159], v[198:201], v[60:63]
	v_mfma_f32_16x16x32_bf16 v[56:59], v[170:173], v[198:201], v[56:59]
	v_mfma_f32_16x16x32_bf16 v[52:55], v[156:159], v[206:209], v[52:55]
	v_mfma_f32_16x16x32_bf16 v[48:51], v[170:173], v[206:209], v[48:51]
	v_mfma_f32_16x16x32_bf16 v[40:43], v[156:159], v[214:217], v[40:43]
	v_mfma_f32_16x16x32_bf16 v[32:35], v[170:173], v[214:217], v[32:35]
	v_mfma_f32_16x16x32_bf16 v[24:27], v[156:159], v[222:225], v[24:27]
	v_mfma_f32_16x16x32_bf16 v[16:19], v[170:173], v[222:225], v[16:19]
	s_setprio 0
	s_setprio 1
	v_mfma_f32_16x16x32_bf16 v[44:47], v[174:177], v[194:197], v[44:47]
	v_mfma_f32_16x16x32_bf16 v[36:39], v[186:189], v[194:197], v[36:39]
	v_mfma_f32_16x16x32_bf16 v[28:31], v[174:177], v[202:205], v[28:31]
	v_mfma_f32_16x16x32_bf16 v[20:23], v[186:189], v[202:205], v[20:23]
	v_mfma_f32_16x16x32_bf16 v[12:15], v[174:177], v[210:213], v[12:15]
	v_mfma_f32_16x16x32_bf16 v[8:11], v[186:189], v[210:213], v[8:11]
	v_mfma_f32_16x16x32_bf16 v[4:7], v[174:177], v[218:221], v[4:7]
	v_mfma_f32_16x16x32_bf16 v[0:3], v[186:189], v[218:221], v[0:3]
	v_mfma_f32_16x16x32_bf16 v[44:47], v[182:185], v[198:201], v[44:47]
	v_mfma_f32_16x16x32_bf16 v[36:39], v[190:193], v[198:201], v[36:39]
	v_mfma_f32_16x16x32_bf16 v[28:31], v[182:185], v[206:209], v[28:31]
	v_mfma_f32_16x16x32_bf16 v[20:23], v[190:193], v[206:209], v[20:23]
	v_mfma_f32_16x16x32_bf16 v[12:15], v[182:185], v[214:217], v[12:15]
	v_mfma_f32_16x16x32_bf16 v[8:11], v[190:193], v[214:217], v[8:11]
	v_mfma_f32_16x16x32_bf16 v[4:7], v[182:185], v[222:225], v[4:7]
	v_mfma_f32_16x16x32_bf16 v[0:3], v[190:193], v[222:225], v[0:3]
	s_setprio 0
	s_barrier
	s_add_i32 s81, 0, 0x18000
	v_add_u32_e32 v169, s81, v141
	s_add_i32 s82, 0, 0x1c000
	ds_read_b128 v[152:155], v169
	ds_read_b128 v[156:159], v169 offset:1024
	ds_read_b128 v[164:167], v169 offset:2048
	ds_read_b128 v[170:173], v169 offset:3072
	v_add_u32_e32 v169, s82, v141
	ds_read_b128 v[174:177], v169
	ds_read_b128 v[182:185], v169 offset:1024
	ds_read_b128 v[186:189], v169 offset:2048
	ds_read_b128 v[190:193], v169 offset:3072
	s_add_u32 s52, s52, s12
	s_addc_u32 s53, s53, s13
	s_mov_b32 m0, s60
	v_lshl_add_u64 v[238:239], s[52:53], 0, v[130:131]
	ds_read_b128 v[194:197], v163 offset:32768
	ds_read_b128 v[198:201], v163 offset:33792
	ds_read_b128 v[202:205], v163 offset:34816
	ds_read_b128 v[206:209], v163 offset:35840
	ds_read_b128 v[210:213], v163 offset:36864
	ds_read_b128 v[214:217], v163 offset:37888
	ds_read_b128 v[218:221], v163 offset:38912
	ds_read_b128 v[222:225], v163 offset:39936
	global_load_lds_dwordx4 v[238:239], off
	v_lshl_add_u64 v[238:239], s[52:53], 0, v[134:135]
	s_mov_b32 m0, s61
	s_nop 0
	global_load_lds_dwordx4 v[238:239], off
	s_waitcnt vmcnt(8)
	s_waitcnt lgkmcnt(0)
	s_barrier
	s_setprio 1
	s_waitcnt lgkmcnt(0)
	v_mfma_f32_16x16x32_bf16 v[124:127], v[152:155], v[194:197], v[124:127]
	v_mfma_f32_16x16x32_bf16 v[120:123], v[164:167], v[194:197], v[120:123]
	v_mfma_f32_16x16x32_bf16 v[116:119], v[152:155], v[202:205], v[116:119]
	v_mfma_f32_16x16x32_bf16 v[112:115], v[164:167], v[202:205], v[112:115]
	v_mfma_f32_16x16x32_bf16 v[104:107], v[152:155], v[210:213], v[104:107]
	v_mfma_f32_16x16x32_bf16 v[96:99], v[164:167], v[210:213], v[96:99]
	v_mfma_f32_16x16x32_bf16 v[88:91], v[152:155], v[218:221], v[88:91]
	v_mfma_f32_16x16x32_bf16 v[80:83], v[164:167], v[218:221], v[80:83]
	v_mfma_f32_16x16x32_bf16 v[124:127], v[156:159], v[198:201], v[124:127]
	v_mfma_f32_16x16x32_bf16 v[120:123], v[170:173], v[198:201], v[120:123]
	v_mfma_f32_16x16x32_bf16 v[116:119], v[156:159], v[206:209], v[116:119]
	v_mfma_f32_16x16x32_bf16 v[112:115], v[170:173], v[206:209], v[112:115]
	v_mfma_f32_16x16x32_bf16 v[104:107], v[156:159], v[214:217], v[104:107]
	v_mfma_f32_16x16x32_bf16 v[96:99], v[170:173], v[214:217], v[96:99]
	v_mfma_f32_16x16x32_bf16 v[88:91], v[156:159], v[222:225], v[88:91]
	v_mfma_f32_16x16x32_bf16 v[80:83], v[170:173], v[222:225], v[80:83]
	s_setprio 0
	s_setprio 1
	v_mfma_f32_16x16x32_bf16 v[108:111], v[174:177], v[194:197], v[108:111]
	v_mfma_f32_16x16x32_bf16 v[100:103], v[186:189], v[194:197], v[100:103]
	v_mfma_f32_16x16x32_bf16 v[92:95], v[174:177], v[202:205], v[92:95]
	v_mfma_f32_16x16x32_bf16 v[84:87], v[186:189], v[202:205], v[84:87]
	v_mfma_f32_16x16x32_bf16 v[76:79], v[174:177], v[210:213], v[76:79]
	v_mfma_f32_16x16x32_bf16 v[72:75], v[186:189], v[210:213], v[72:75]
	v_mfma_f32_16x16x32_bf16 v[68:71], v[174:177], v[218:221], v[68:71]
	v_mfma_f32_16x16x32_bf16 v[64:67], v[186:189], v[218:221], v[64:67]
	v_mfma_f32_16x16x32_bf16 v[108:111], v[182:185], v[198:201], v[108:111]
	v_mfma_f32_16x16x32_bf16 v[100:103], v[190:193], v[198:201], v[100:103]
	v_mfma_f32_16x16x32_bf16 v[92:95], v[182:185], v[206:209], v[92:95]
	v_mfma_f32_16x16x32_bf16 v[84:87], v[190:193], v[206:209], v[84:87]
	v_mfma_f32_16x16x32_bf16 v[76:79], v[182:185], v[214:217], v[76:79]
	v_mfma_f32_16x16x32_bf16 v[72:75], v[190:193], v[214:217], v[72:75]
	v_mfma_f32_16x16x32_bf16 v[68:71], v[182:185], v[222:225], v[68:71]
	v_mfma_f32_16x16x32_bf16 v[64:67], v[190:193], v[222:225], v[64:67]
	s_setprio 0
	s_barrier
; #define PG8_STAGE(bufoff, gbase, voff) do { _Pragma("unroll") for (int _i = 0; _i < 2; ++_i) \
;         __builtin_amdgcn_global_load_lds((const unsigned*)((const char*)(gbase) + (voff)[_i]), (PG8_LAS unsigned*)(lds + (bufoff) + ldsw + _i * 8192), 16, 0, 0); } while (0)
; #define PG8_LDA(dst, b, h) do { _Pragma("unroll") for (int m = 0; m < 4; ++m) _Pragma("unroll") for (int k = 0; k < 2; ++k) dst[m][k] = *(const PG8_LAS bf16x8*)(lds + PG8_SA(b, h) + aoff + m * 2048 + k * 1024); } while (0)
; #define PG8_MMA(ai, bj, At, Bt) do { __builtin_amdgcn_s_setprio(1); _Pragma("unroll") for (int m = 0; m < 4; ++m) _Pragma("unroll") for (int n = 0; n < 2; ++n) _Pragma("unroll") for (int k = 0; k < 2; ++k) \
;         acc[ai][bj][m][n] = __builtin_amdgcn_mfma_f32_16x16x32_bf16(Bt[n][k], At[m][k], acc[ai][bj][m][n], 0, 0, 0); __builtin_amdgcn_s_setprio(0); } while (0)
; #define PG8_WAIT_V(n) asm volatile("s_waitcnt vmcnt(" #n ")" ::: "memory")
; #define PG8_WAIT_L(n) asm volatile("s_waitcnt lgkmcnt(" #n ")" ::: "memory")
; #define PG8_BAR __builtin_amdgcn_s_barrier()
; #define PG8_SCHED __builtin_amdgcn_sched_barrier(0)
;     __device__ __forceinline__ void operator()(const f32x4 (&acc)[2][2][4][2], const Unit& u, int wr, int wc, int fr, int fq) const {
;     ...
;         for (int ai = 0; ai < 2; ++ai)
; #pragma unroll
;             for (int m = 0; m < 4; ++m) { bf16_t* rowp = base + (size_t)(row0 + ai * HALF + m * 16) * ldc + col0;
; #pragma unroll
;                 for (int bj = 0; bj < 2; ++bj) { f32x4 v0 = acc[ai][bj][m][0] + bv[bj][0], v1 = acc[ai][bj][m][1] + bv[bj][1];
; template <class Epi, class Sched, bool ALIGN_EPI = false, bool SP2 = false>
; __device__ __forceinline__ void gemm_phase(PG8_LAS unsigned char* lds, const Gemm g, const Sched& S, const Epi& E) {
;     ...
;             PG8_LDA(At, 1, 1); PG8_STAGE(PG8_SB(1, 0), b3, voffB); PG8_STAGE(PG8_SB(1, 1), b3 + hstep, voffB); PG8_STAGE(PG8_SA(1, 0), a3, voffA);
;             PG8_WAIT_V(8); PG8_WAIT_L(0); PG8_BAR; PG8_MMA(1, 0, At, B0); PG8_MMA(1, 1, At, B1); PG8_BAR; PG8_SCHED;
	s_add_i32 s52, s81, s57
	v_lshl_add_u64 v[226:227], v[226:227], 0, s[18:19]
	s_mov_b32 m0, s52
	ds_read_b128 v[194:197], v163 offset:49152
	ds_read_b128 v[198:201], v163 offset:50176
	ds_read_b128 v[202:205], v163 offset:51200
	ds_read_b128 v[206:209], v163 offset:52224
	ds_read_b128 v[210:213], v163 offset:53248
	ds_read_b128 v[214:217], v163 offset:54272
	ds_read_b128 v[218:221], v163 offset:55296
	ds_read_b128 v[222:225], v163 offset:56320
	global_load_lds_dwordx4 v[226:227], off
	v_lshl_add_u64 v[226:227], v[228:229], 0, s[18:19]
	s_add_i32 m0, s52, 0x2000
	s_add_i32 s52, s82, s57
	global_load_lds_dwordx4 v[226:227], off
	v_lshl_add_u64 v[226:227], v[230:231], 0, s[18:19]
	s_mov_b32 m0, s52
	s_nop 0
	global_load_lds_dwordx4 v[226:227], off
	v_lshl_add_u64 v[226:227], v[232:233], 0, s[18:19]
	s_add_i32 m0, s52, 0x2000
	s_nop 0
	global_load_lds_dwordx4 v[226:227], off
	v_lshl_add_u64 v[226:227], v[234:235], 0, s[18:19]
	s_mov_b32 m0, s64
	s_nop 0
	global_load_lds_dwordx4 v[226:227], off
	v_lshl_add_u64 v[226:227], v[236:237], 0, s[18:19]
	s_mov_b32 m0, s65
	s_nop 0
	global_load_lds_dwordx4 v[226:227], off
	s_waitcnt vmcnt(8)
	s_waitcnt lgkmcnt(0)
	s_barrier
	s_setprio 1
	s_waitcnt lgkmcnt(0)
	v_mfma_f32_16x16x32_bf16 v[60:63], v[152:155], v[194:197], v[60:63]
	v_mfma_f32_16x16x32_bf16 v[56:59], v[164:167], v[194:197], v[56:59]
	v_mfma_f32_16x16x32_bf16 v[52:55], v[152:155], v[202:205], v[52:55]
	v_mfma_f32_16x16x32_bf16 v[48:51], v[164:167], v[202:205], v[48:51]
	v_mfma_f32_16x16x32_bf16 v[40:43], v[152:155], v[210:213], v[40:43]
	v_mfma_f32_16x16x32_bf16 v[32:35], v[164:167], v[210:213], v[32:35]
	v_mfma_f32_16x16x32_bf16 v[24:27], v[152:155], v[218:221], v[24:27]
	v_mfma_f32_16x16x32_bf16 v[16:19], v[164:167], v[218:221], v[16:19]
	v_mfma_f32_16x16x32_bf16 v[60:63], v[156:159], v[198:201], v[60:63]
	v_mfma_f32_16x16x32_bf16 v[56:59], v[170:173], v[198:201], v[56:59]
	v_mfma_f32_16x16x32_bf16 v[52:55], v[156:159], v[206:209], v[52:55]
	v_mfma_f32_16x16x32_bf16 v[48:51], v[170:173], v[206:209], v[48:51]
	v_mfma_f32_16x16x32_bf16 v[40:43], v[156:159], v[214:217], v[40:43]
	v_mfma_f32_16x16x32_bf16 v[32:35], v[170:173], v[214:217], v[32:35]
	v_mfma_f32_16x16x32_bf16 v[24:27], v[156:159], v[222:225], v[24:27]
	v_mfma_f32_16x16x32_bf16 v[16:19], v[170:173], v[222:225], v[16:19]
	s_setprio 0
	s_setprio 1
	v_mfma_f32_16x16x32_bf16 v[44:47], v[174:177], v[194:197], v[44:47]
	v_mfma_f32_16x16x32_bf16 v[36:39], v[186:189], v[194:197], v[36:39]
	v_mfma_f32_16x16x32_bf16 v[28:31], v[174:177], v[202:205], v[28:31]
	v_mfma_f32_16x16x32_bf16 v[20:23], v[186:189], v[202:205], v[20:23]
	v_mfma_f32_16x16x32_bf16 v[12:15], v[174:177], v[210:213], v[12:15]
	v_mfma_f32_16x16x32_bf16 v[8:11], v[186:189], v[210:213], v[8:11]
	v_mfma_f32_16x16x32_bf16 v[4:7], v[174:177], v[218:221], v[4:7]
	v_mfma_f32_16x16x32_bf16 v[0:3], v[186:189], v[218:221], v[0:3]
	v_mfma_f32_16x16x32_bf16 v[44:47], v[182:185], v[198:201], v[44:47]
	v_mfma_f32_16x16x32_bf16 v[36:39], v[190:193], v[198:201], v[36:39]
	v_mfma_f32_16x16x32_bf16 v[28:31], v[182:185], v[206:209], v[28:31]
	v_mfma_f32_16x16x32_bf16 v[20:23], v[190:193], v[206:209], v[20:23]
	v_mfma_f32_16x16x32_bf16 v[12:15], v[182:185], v[214:217], v[12:15]
	v_mfma_f32_16x16x32_bf16 v[8:11], v[190:193], v[214:217], v[8:11]
	v_mfma_f32_16x16x32_bf16 v[4:7], v[182:185], v[222:225], v[4:7]
	v_mfma_f32_16x16x32_bf16 v[0:3], v[190:193], v[222:225], v[0:3]
	s_setprio 0
	s_add_u32 s78, s78, 0x100
	s_addc_u32 s79, s79, 0
	s_add_u32 s50, s50, 0x100
	s_addc_u32 s51, s51, 0
	s_cmp_ge_i32 s80, s66
	s_mov_b32 s52, s80
	s_barrier
	s_cbranch_scc0 .LBB0_741
	v_pk_add_f32 v[126:127], v[126:127], 0 op_sel_hi:[1,0]
	v_pk_add_f32 v[124:125], v[124:125], 0 op_sel_hi:[1,0]
	v_pk_add_f32 v[122:123], v[122:123], 0 op_sel_hi:[1,0]
	v_pk_add_f32 v[120:121], v[120:121], 0 op_sel_hi:[1,0]
	v_pk_add_f32 v[152:153], v[110:111], 0 op_sel_hi:[1,0]
	v_pk_add_f32 v[154:155], v[108:109], 0 op_sel_hi:[1,0]
	v_pk_add_f32 v[156:157], v[102:103], 0 op_sel_hi:[1,0]
	v_pk_add_f32 v[158:159], v[100:101], 0 op_sel_hi:[1,0]
	v_pk_add_f32 v[100:101], v[118:119], 0 op_sel_hi:[1,0]
	v_pk_add_f32 v[102:103], v[116:117], 0 op_sel_hi:[1,0]
	v_pk_add_f32 v[108:109], v[114:115], 0 op_sel_hi:[1,0]
	v_pk_add_f32 v[110:111], v[112:113], 0 op_sel_hi:[1,0]
	v_pk_add_f32 v[112:113], v[94:95], 0 op_sel_hi:[1,0]
	v_pk_add_f32 v[114:115], v[92:93], 0 op_sel_hi:[1,0]
	v_pk_add_f32 v[116:117], v[86:87], 0 op_sel_hi:[1,0]
	v_pk_add_f32 v[118:119], v[84:85], 0 op_sel_hi:[1,0]
	v_pk_add_f32 v[84:85], v[106:107], 0 op_sel_hi:[1,0]
	v_pk_add_f32 v[86:87], v[104:105], 0 op_sel_hi:[1,0]
	v_pk_add_f32 v[92:93], v[98:99], 0 op_sel_hi:[1,0]
	v_pk_add_f32 v[94:95], v[96:97], 0 op_sel_hi:[1,0]
	v_pk_add_f32 v[96:97], v[78:79], 0 op_sel_hi:[1,0]
	v_pk_add_f32 v[98:99], v[76:77], 0 op_sel_hi:[1,0]
	v_pk_add_f32 v[104:105], v[74:75], 0 op_sel_hi:[1,0]
	v_pk_add_f32 v[106:107], v[72:73], 0 op_sel_hi:[1,0]
	v_pk_add_f32 v[72:73], v[90:91], 0 op_sel_hi:[1,0]
	v_pk_add_f32 v[74:75], v[88:89], 0 op_sel_hi:[1,0]
	v_pk_add_f32 v[76:77], v[82:83], 0 op_sel_hi:[1,0]
	v_pk_add_f32 v[78:79], v[80:81], 0 op_sel_hi:[1,0]
	v_pk_add_f32 v[70:71], v[70:71], 0 op_sel_hi:[1,0]
	v_pk_add_f32 v[68:69], v[68:69], 0 op_sel_hi:[1,0]
	v_pk_add_f32 v[66:67], v[66:67], 0 op_sel_hi:[1,0]
	v_pk_add_f32 v[64:65], v[64:65], 0 op_sel_hi:[1,0]
	v_pk_add_f32 v[62:63], v[62:63], 0 op_sel_hi:[1,0]
	v_pk_add_f32 v[60:61], v[60:61], 0 op_sel_hi:[1,0]
	v_pk_add_f32 v[58:59], v[58:59], 0 op_sel_hi:[1,0]
	v_pk_add_f32 v[56:57], v[56:57], 0 op_sel_hi:[1,0]
	v_pk_add_f32 v[80:81], v[46:47], 0 op_sel_hi:[1,0]
	v_pk_add_f32 v[82:83], v[44:45], 0 op_sel_hi:[1,0]
	v_pk_add_f32 v[88:89], v[38:39], 0 op_sel_hi:[1,0]
	v_pk_add_f32 v[90:91], v[36:37], 0 op_sel_hi:[1,0]
	v_pk_add_f32 v[36:37], v[54:55], 0 op_sel_hi:[1,0]
	v_pk_add_f32 v[38:39], v[52:53], 0 op_sel_hi:[1,0]
	v_pk_add_f32 v[44:45], v[50:51], 0 op_sel_hi:[1,0]
	v_pk_add_f32 v[46:47], v[48:49], 0 op_sel_hi:[1,0]
	v_pk_add_f32 v[48:49], v[30:31], 0 op_sel_hi:[1,0]
	v_pk_add_f32 v[50:51], v[28:29], 0 op_sel_hi:[1,0]
	v_pk_add_f32 v[52:53], v[22:23], 0 op_sel_hi:[1,0]
	v_pk_add_f32 v[54:55], v[20:21], 0 op_sel_hi:[1,0]
	v_pk_add_f32 v[20:21], v[42:43], 0 op_sel_hi:[1,0]
	v_pk_add_f32 v[22:23], v[40:41], 0 op_sel_hi:[1,0]
	v_pk_add_f32 v[28:29], v[34:35], 0 op_sel_hi:[1,0]
	v_pk_add_f32 v[30:31], v[32:33], 0 op_sel_hi:[1,0]
	v_pk_add_f32 v[32:33], v[14:15], 0 op_sel_hi:[1,0]
	v_pk_add_f32 v[34:35], v[12:13], 0 op_sel_hi:[1,0]
	v_pk_add_f32 v[40:41], v[10:11], 0 op_sel_hi:[1,0]
	v_pk_add_f32 v[42:43], v[8:9], 0 op_sel_hi:[1,0]
	v_pk_add_f32 v[8:9], v[26:27], 0 op_sel_hi:[1,0]
	v_pk_add_f32 v[10:11], v[24:25], 0 op_sel_hi:[1,0]
	v_pk_add_f32 v[12:13], v[18:19], 0 op_sel_hi:[1,0]
	v_pk_add_f32 v[14:15], v[16:17], 0 op_sel_hi:[1,0]
	v_pk_add_f32 v[6:7], v[6:7], 0 op_sel_hi:[1,0]
	v_pk_add_f32 v[4:5], v[4:5], 0 op_sel_hi:[1,0]
	v_pk_add_f32 v[2:3], v[2:3], 0 op_sel_hi:[1,0]
	v_pk_add_f32 v[0:1], v[0:1], 0 op_sel_hi:[1,0]

; #define LAS __attribute__((address_space(3)))
; template <int I0, int NQ, int VO> __device__ __forceinline__ void tile_y(LAS unsigned char* lds, float (&l)[2], f32x4 (&o)[2][4], f32x4 (&s)[2][4], int fr, int fq) {
;     bf16x8 pb[NQ][2];
; #pragma unroll
;     for (int q = 0; q < NQ; ++q) {
;         f32x4 (&sq)[4] = s[I0 + q];
;         f32x2_t rs2 = {0.f, 0.f};
; #pragma unroll
;         for (int ss = 0; ss < 4; ++ss) {
; #pragma unroll
;             for (int i = 0; i < 4; ++i) sq[ss][i] = __builtin_amdgcn_exp2f(sq[ss][i]);
;             rs2 += (f32x2_t){sq[ss][0], sq[ss][1]}; rs2 += (f32x2_t){sq[ss][2], sq[ss][3]};
;         }
;         l[I0 + q] += rs2.x + rs2.y;
; #pragma unroll
;         for (int j = 0; j < 2; ++j) {
;             const v4u w = (v4u){cvtpk(sq[2 * j][0], sq[2 * j][1]), cvtpk(sq[2 * j][2], sq[2 * j][3]), cvtpk(sq[2 * j + 1][0], sq[2 * j + 1][1]), cvtpk(sq[2 * j + 1][2], sq[2 * j + 1][3])};
;             pb[q][j] = __builtin_bit_cast(bf16x8, w);
;         }
;     }
; #pragma unroll
;     for (int dt = 0; dt < 4; ++dt)
; #pragma unroll
;         for (int j = 0; j < 2; ++j) {
;             LAS unsigned char* vp = lds + VO + ((32 * j + 4 * fq + (fr >> 2)) * VSTR + 16 * dt + 4 * (fr & 3)) * 2;
;             const s16x4 lo = __builtin_bit_cast(s16x4, __builtin_amdgcn_ds_read_tr16_b64_v4i16((LAS v4i16_t*)vp));
;             const s16x4 hi = __builtin_bit_cast(s16x4, __builtin_amdgcn_ds_read_tr16_b64_v4i16((LAS v4i16_t*)(vp + 16 * VSTR * 2)));
;             const bf16x8 vf = (bf16x8){lo[0], lo[1], lo[2], lo[3], hi[0], hi[1], hi[2], hi[3]};
; #pragma unroll
;             for (int q = 0; q < NQ; ++q) o[I0 + q][dt] = __builtin_amdgcn_mfma_f32_16x16x32_bf16(vf, pb[q][j], o[I0 + q][dt], 0, 0, 0);
;         }
; }
; template <int DQK> __device__ __forceinline__ void x1_tile(LAS unsigned char* lds, const bf16x8 (&qf)[2][DQK / 32], const float (&m)[2], f32x4 (&s)[2][4], int fr, int fq) {
;     constexpr int NKS = DQK / 32;
; #pragma unroll
;     for (int q = 0; q < 2; ++q) { const float c = (m[q] > -1e29f) ? -m[q] : 0.f;
; #pragma unroll
;         for (int ss = 0; ss < 4; ++ss) s[q][ss] = (f32x4){c, c, c, c}; }
; #pragma unroll
;     for (int ss = 0; ss < 4; ++ss)
; #pragma unroll
;         for (int ks = 0; ks < NKS; ++ks) {
;             const bf16x8 kf = *(const LAS bf16x8*)(lds + k_off<DQK>(16 * ss + fr, 4 * ks + fq));
; #pragma unroll
.Lmla_nostage0:
	s_cmp_ge_u32 s49, s9
	s_cbranch_scc1 .Lmla_tail0
	ds_read_b64_tr_b16 v[220:221], v251 offset:16384
	ds_read_b64_tr_b16 v[222:223], v251 offset:18944
	ds_read_b64_tr_b16 v[224:225], v251 offset:21504
	ds_read_b64_tr_b16 v[226:227], v251 offset:24064
	ds_read_b64_tr_b16 v[228:229], v251 offset:16416
	ds_read_b64_tr_b16 v[230:231], v251 offset:18976
	ds_read_b64_tr_b16 v[232:233], v251 offset:21536
	ds_read_b64_tr_b16 v[234:235], v251 offset:24096
	ds_read_b128 v[236:239], v195
	ds_read_b128 v[240:243], v196
	ds_read_b128 v[244:247], v202
	s_waitcnt lgkmcnt(2)
	v_mfma_f32_16x16x32_bf16 v[24:27], v[236:239], v[0:3], v[204:207]
	v_exp_f32_e32 v100, v100
	v_mfma_f32_16x16x32_bf16 v[40:43], v[236:239], v[12:15], v[252:255]
	v_exp_f32_e32 v101, v101
	ds_read_b128 v[236:239], v195 offset:4096
	s_waitcnt lgkmcnt(2)
	v_mfma_f32_16x16x32_bf16 v[24:27], v[240:243], v[4:7], v[24:27]
	v_exp_f32_e32 v102, v102
	v_mfma_f32_16x16x32_bf16 v[40:43], v[240:243], v[16:19], v[40:43]
	v_exp_f32_e32 v103, v103
	ds_read_b128 v[240:243], v196 offset:4096
	s_waitcnt lgkmcnt(2)
	v_mfma_f32_16x16x32_bf16 v[24:27], v[244:247], v[8:11], v[24:27]
	v_exp_f32_e32 v104, v104
	v_mfma_f32_16x16x32_bf16 v[40:43], v[244:247], v[20:23], v[40:43]
	v_exp_f32_e32 v105, v105
	ds_read_b128 v[244:247], v202 offset:4096
	s_waitcnt lgkmcnt(2)
	v_mfma_f32_16x16x32_bf16 v[28:31], v[236:239], v[0:3], v[204:207]
	v_exp_f32_e32 v106, v106
	v_mfma_f32_16x16x32_bf16 v[44:47], v[236:239], v[12:15], v[252:255]
	v_exp_f32_e32 v107, v107
	ds_read_b128 v[236:239], v195 offset:8192
	s_waitcnt lgkmcnt(2)
	v_mfma_f32_16x16x32_bf16 v[28:31], v[240:243], v[4:7], v[28:31]
	v_exp_f32_e32 v108, v108
	v_mfma_f32_16x16x32_bf16 v[44:47], v[240:243], v[16:19], v[44:47]
	v_exp_f32_e32 v109, v109
	ds_read_b128 v[240:243], v196 offset:8192
	s_waitcnt lgkmcnt(2)
	v_mfma_f32_16x16x32_bf16 v[28:31], v[244:247], v[8:11], v[28:31]
	v_exp_f32_e32 v110, v110
	v_mfma_f32_16x16x32_bf16 v[44:47], v[244:247], v[20:23], v[44:47]
	v_exp_f32_e32 v111, v111
	ds_read_b128 v[244:247], v202 offset:8192
	s_waitcnt lgkmcnt(2)
	v_mfma_f32_16x16x32_bf16 v[32:35], v[236:239], v[0:3], v[204:207]
	v_exp_f32_e32 v112, v112
	v_mfma_f32_16x16x32_bf16 v[212:215], v[236:239], v[12:15], v[252:255]
	v_exp_f32_e32 v113, v113
	ds_read_b128 v[236:239], v195 offset:12288
	s_waitcnt lgkmcnt(2)
	v_mfma_f32_16x16x32_bf16 v[32:35], v[240:243], v[4:7], v[32:35]
	v_exp_f32_e32 v114, v114
	v_mfma_f32_16x16x32_bf16 v[212:215], v[240:243], v[16:19], v[212:215]
	v_exp_f32_e32 v115, v115
	ds_read_b128 v[240:243], v196 offset:12288
	s_waitcnt lgkmcnt(2)
	v_mfma_f32_16x16x32_bf16 v[32:35], v[244:247], v[8:11], v[32:35]
	v_cvt_pk_bf16_f32 v132, v100, v101
	v_cvt_pk_bf16_f32 v133, v102, v103
	v_mfma_f32_16x16x32_bf16 v[212:215], v[244:247], v[20:23], v[212:215]
	v_cvt_pk_bf16_f32 v134, v104, v105
	v_cvt_pk_bf16_f32 v135, v106, v107
	ds_read_b128 v[244:247], v202 offset:12288
	s_waitcnt lgkmcnt(2)
	v_mfma_f32_16x16x32_bf16 v[36:39], v[236:239], v[0:3], v[204:207]
	v_cvt_pk_bf16_f32 v136, v108, v109
	v_cvt_pk_bf16_f32 v137, v110, v111
	v_mfma_f32_16x16x32_bf16 v[216:219], v[236:239], v[12:15], v[252:255]
	v_cvt_pk_bf16_f32 v138, v112, v113
	v_cvt_pk_bf16_f32 v139, v114, v115
	ds_read_b64_tr_b16 v[236:237], v251 offset:16448
	ds_read_b64_tr_b16 v[238:239], v251 offset:19008
	s_waitcnt lgkmcnt(3)
	v_mfma_f32_16x16x32_bf16 v[36:39], v[240:243], v[4:7], v[36:39]
	v_exp_f32_e32 v116, v116
	v_mfma_f32_16x16x32_bf16 v[216:219], v[240:243], v[16:19], v[216:219]
	v_exp_f32_e32 v117, v117
	ds_read_b64_tr_b16 v[240:241], v251 offset:21568
	ds_read_b64_tr_b16 v[242:243], v251 offset:24128
	s_waitcnt lgkmcnt(4)
	v_mfma_f32_16x16x32_bf16 v[36:39], v[244:247], v[8:11], v[36:39]
	v_exp_f32_e32 v118, v118
	v_mfma_f32_16x16x32_bf16 v[216:219], v[244:247], v[20:23], v[216:219]
	v_exp_f32_e32 v119, v119
	ds_read_b64_tr_b16 v[244:245], v251 offset:16480
	ds_read_b64_tr_b16 v[246:247], v251 offset:19040
	v_exp_f32_e32 v120, v120
	v_exp_f32_e32 v121, v121
	v_exp_f32_e32 v122, v122
	v_exp_f32_e32 v123, v123
	v_exp_f32_e32 v124, v124
	v_exp_f32_e32 v125, v125
	v_exp_f32_e32 v126, v126
	v_exp_f32_e32 v127, v127
	v_exp_f32_e32 v128, v128
	v_exp_f32_e32 v129, v129
	v_exp_f32_e32 v130, v130
	v_exp_f32_e32 v131, v131
	v_cvt_pk_bf16_f32 v140, v116, v117
	v_cvt_pk_bf16_f32 v141, v118, v119
	v_cvt_pk_bf16_f32 v142, v120, v121
	v_cvt_pk_bf16_f32 v143, v122, v123
	v_cvt_pk_bf16_f32 v52, v124, v125
	v_cvt_pk_bf16_f32 v53, v126, v127
	v_cvt_pk_bf16_f32 v54, v128, v129
	v_cvt_pk_bf16_f32 v55, v130, v131
	s_waitcnt lgkmcnt(15)
	v_mfma_f32_16x16x32_bf16 v[96:99], v[220:223], v[132:135], v[96:99]
	v_add_f32_e32 v100, v100, v101
	v_add_f32_e32 v102, v102, v103
	v_mfma_f32_16x16x32_bf16 v[84:87], v[220:223], v[140:143], v[84:87]
	v_add_f32_e32 v104, v104, v105
	v_add_f32_e32 v106, v106, v107
	v_mfma_f32_16x16x32_bf16 v[96:99], v[224:227], v[136:139], v[96:99]
	v_add_f32_e32 v108, v108, v109
	v_add_f32_e32 v110, v110, v111
	v_mfma_f32_16x16x32_bf16 v[84:87], v[224:227], v[52:55], v[84:87]
	v_add_f32_e32 v112, v112, v113
	v_add_f32_e32 v114, v114, v115
	ds_read_b64_tr_b16 v[220:221], v251 offset:21600
	ds_read_b64_tr_b16 v[222:223], v251 offset:24160
	v_mfma_f32_16x16x32_bf16 v[88:91], v[228:231], v[132:135], v[88:91]
	v_add_f32_e32 v100, v100, v102
	v_add_f32_e32 v104, v104, v106
	v_mfma_f32_16x16x32_bf16 v[76:79], v[228:231], v[140:143], v[76:79]
	v_add_f32_e32 v108, v108, v110
	v_add_f32_e32 v112, v112, v114
	v_mfma_f32_16x16x32_bf16 v[88:91], v[232:235], v[136:139], v[88:91]
	v_add_f32_e32 v100, v100, v104
	v_add_f32_e32 v108, v108, v112
	v_mfma_f32_16x16x32_bf16 v[76:79], v[232:235], v[52:55], v[76:79]
	v_add_f32_e32 v100, v100, v108
	v_add_f32_e32 v165, v165, v100
	s_waitcnt lgkmcnt(0)
	v_mfma_f32_16x16x32_bf16 v[92:95], v[236:239], v[132:135], v[92:95]
	v_add_f32_e32 v116, v116, v117
	v_add_f32_e32 v118, v118, v119
	v_mfma_f32_16x16x32_bf16 v[80:83], v[236:239], v[140:143], v[80:83]
	v_add_f32_e32 v120, v120, v121
	v_add_f32_e32 v122, v122, v123
	v_mfma_f32_16x16x32_bf16 v[92:95], v[240:243], v[136:139], v[92:95]
	v_add_f32_e32 v124, v124, v125
	v_add_f32_e32 v126, v126, v127
	v_mfma_f32_16x16x32_bf16 v[80:83], v[240:243], v[52:55], v[80:83]
	v_add_f32_e32 v128, v128, v129
	v_add_f32_e32 v130, v130, v131
	v_mfma_f32_16x16x32_bf16 v[48:51], v[244:247], v[132:135], v[48:51]
	v_add_f32_e32 v116, v116, v118
	v_add_f32_e32 v120, v120, v122
	v_mfma_f32_16x16x32_bf16 v[56:59], v[244:247], v[140:143], v[56:59]
	v_add_f32_e32 v124, v124, v126
	v_add_f32_e32 v128, v128, v130
	v_mfma_f32_16x16x32_bf16 v[48:51], v[220:223], v[136:139], v[48:51]
	v_add_f32_e32 v116, v116, v120
	v_add_f32_e32 v124, v124, v128
	v_mfma_f32_16x16x32_bf16 v[56:59], v[220:223], v[52:55], v[56:59]
	v_add_f32_e32 v116, v116, v124
	v_add_f32_e32 v164, v164, v116
	s_add_i32 s32, s49, 1
	s_cmp_eq_u32 s32, s9
	s_cbranch_scc1 .Lmla_mask0

; #define LAS __attribute__((address_space(3)))
; template <int I0, int NQ, int VO> __device__ __forceinline__ void tile_y(LAS unsigned char* lds, float (&l)[2], f32x4 (&o)[2][4], f32x4 (&s)[2][4], int fr, int fq) {
;     bf16x8 pb[NQ][2];
; #pragma unroll
;     for (int q = 0; q < NQ; ++q) {
;         f32x4 (&sq)[4] = s[I0 + q];
;         f32x2_t rs2 = {0.f, 0.f};
; #pragma unroll
;         for (int ss = 0; ss < 4; ++ss) {
; #pragma unroll
;             for (int i = 0; i < 4; ++i) sq[ss][i] = __builtin_amdgcn_exp2f(sq[ss][i]);
;             rs2 += (f32x2_t){sq[ss][0], sq[ss][1]}; rs2 += (f32x2_t){sq[ss][2], sq[ss][3]};
;         }
;         l[I0 + q] += rs2.x + rs2.y;
; #pragma unroll
;         for (int j = 0; j < 2; ++j) {
;             const v4u w = (v4u){cvtpk(sq[2 * j][0], sq[2 * j][1]), cvtpk(sq[2 * j][2], sq[2 * j][3]), cvtpk(sq[2 * j + 1][0], sq[2 * j + 1][1]), cvtpk(sq[2 * j + 1][2], sq[2 * j + 1][3])};
;             pb[q][j] = __builtin_bit_cast(bf16x8, w);
;         }
;     }
; #pragma unroll
;     for (int dt = 0; dt < 4; ++dt)
; #pragma unroll
;         for (int j = 0; j < 2; ++j) {
;             LAS unsigned char* vp = lds + VO + ((32 * j + 4 * fq + (fr >> 2)) * VSTR + 16 * dt + 4 * (fr & 3)) * 2;
;             const s16x4 lo = __builtin_bit_cast(s16x4, __builtin_amdgcn_ds_read_tr16_b64_v4i16((LAS v4i16_t*)vp));
;             const s16x4 hi = __builtin_bit_cast(s16x4, __builtin_amdgcn_ds_read_tr16_b64_v4i16((LAS v4i16_t*)(vp + 16 * VSTR * 2)));
;             const bf16x8 vf = (bf16x8){lo[0], lo[1], lo[2], lo[3], hi[0], hi[1], hi[2], hi[3]};
; #pragma unroll
;             for (int q = 0; q < NQ; ++q) o[I0 + q][dt] = __builtin_amdgcn_mfma_f32_16x16x32_bf16(vf, pb[q][j], o[I0 + q][dt], 0, 0, 0);
;         }
; }
; template <int DQK> __device__ __forceinline__ void x1_tile(LAS unsigned char* lds, const bf16x8 (&qf)[2][DQK / 32], const float (&m)[2], f32x4 (&s)[2][4], int fr, int fq) {
;     constexpr int NKS = DQK / 32;
; #pragma unroll
;     for (int q = 0; q < 2; ++q) { const float c = (m[q] > -1e29f) ? -m[q] : 0.f;
; #pragma unroll
;         for (int ss = 0; ss < 4; ++ss) s[q][ss] = (f32x4){c, c, c, c}; }
; #pragma unroll
;     for (int ss = 0; ss < 4; ++ss)
; #pragma unroll
;         for (int ks = 0; ks < NKS; ++ks) {
;             const bf16x8 kf = *(const LAS bf16x8*)(lds + k_off<DQK>(16 * ss + fr, 4 * ks + fq));
; #pragma unroll
.Lmla_nostage1:
	s_cmp_ge_u32 s49, s9
	s_cbranch_scc1 .Lmla_tail1
	ds_read_b64_tr_b16 v[220:221], v203 offset:16384
	ds_read_b64_tr_b16 v[222:223], v203 offset:18944
	ds_read_b64_tr_b16 v[224:225], v203 offset:21504
	ds_read_b64_tr_b16 v[226:227], v203 offset:24064
	ds_read_b64_tr_b16 v[228:229], v203 offset:16416
	ds_read_b64_tr_b16 v[230:231], v203 offset:18976
	ds_read_b64_tr_b16 v[232:233], v203 offset:21536
	ds_read_b64_tr_b16 v[234:235], v203 offset:24096
	ds_read_b128 v[236:239], v195 offset:26624
	ds_read_b128 v[240:243], v196 offset:26624
	ds_read_b128 v[244:247], v202 offset:26624
	s_waitcnt lgkmcnt(2)
	v_mfma_f32_16x16x32_bf16 v[100:103], v[236:239], v[0:3], v[204:207]
	v_exp_f32_e32 v24, v24
	v_mfma_f32_16x16x32_bf16 v[116:119], v[236:239], v[12:15], v[252:255]
	v_exp_f32_e32 v25, v25
	ds_read_b128 v[236:239], v195 offset:30720
	s_waitcnt lgkmcnt(2)
	v_mfma_f32_16x16x32_bf16 v[100:103], v[240:243], v[4:7], v[100:103]
	v_exp_f32_e32 v26, v26
	v_mfma_f32_16x16x32_bf16 v[116:119], v[240:243], v[16:19], v[116:119]
	v_exp_f32_e32 v27, v27
	ds_read_b128 v[240:243], v196 offset:30720
	s_waitcnt lgkmcnt(2)
	v_mfma_f32_16x16x32_bf16 v[100:103], v[244:247], v[8:11], v[100:103]
	v_exp_f32_e32 v28, v28
	v_mfma_f32_16x16x32_bf16 v[116:119], v[244:247], v[20:23], v[116:119]
	v_exp_f32_e32 v29, v29
	ds_read_b128 v[244:247], v202 offset:30720
	s_waitcnt lgkmcnt(2)
	v_mfma_f32_16x16x32_bf16 v[104:107], v[236:239], v[0:3], v[204:207]
	v_exp_f32_e32 v30, v30
	v_mfma_f32_16x16x32_bf16 v[120:123], v[236:239], v[12:15], v[252:255]
	v_exp_f32_e32 v31, v31
	ds_read_b128 v[236:239], v195 offset:34816
	s_waitcnt lgkmcnt(2)
	v_mfma_f32_16x16x32_bf16 v[104:107], v[240:243], v[4:7], v[104:107]
	v_exp_f32_e32 v32, v32
	v_mfma_f32_16x16x32_bf16 v[120:123], v[240:243], v[16:19], v[120:123]
	v_exp_f32_e32 v33, v33
	ds_read_b128 v[240:243], v196 offset:34816
	s_waitcnt lgkmcnt(2)
	v_mfma_f32_16x16x32_bf16 v[104:107], v[244:247], v[8:11], v[104:107]
	v_exp_f32_e32 v34, v34
	v_mfma_f32_16x16x32_bf16 v[120:123], v[244:247], v[20:23], v[120:123]
	v_exp_f32_e32 v35, v35
	ds_read_b128 v[244:247], v202 offset:34816
	s_waitcnt lgkmcnt(2)
	v_mfma_f32_16x16x32_bf16 v[108:111], v[236:239], v[0:3], v[204:207]
	v_exp_f32_e32 v36, v36
	v_mfma_f32_16x16x32_bf16 v[124:127], v[236:239], v[12:15], v[252:255]
	v_exp_f32_e32 v37, v37
	ds_read_b128 v[236:239], v195 offset:38912
	s_waitcnt lgkmcnt(2)
	v_mfma_f32_16x16x32_bf16 v[108:111], v[240:243], v[4:7], v[108:111]
	v_exp_f32_e32 v38, v38
	v_mfma_f32_16x16x32_bf16 v[124:127], v[240:243], v[16:19], v[124:127]
	v_exp_f32_e32 v39, v39
	ds_read_b128 v[240:243], v196 offset:38912
	s_waitcnt lgkmcnt(2)
	v_mfma_f32_16x16x32_bf16 v[108:111], v[244:247], v[8:11], v[108:111]
	v_cvt_pk_bf16_f32 v132, v24, v25
	v_cvt_pk_bf16_f32 v133, v26, v27
	v_mfma_f32_16x16x32_bf16 v[124:127], v[244:247], v[20:23], v[124:127]
	v_cvt_pk_bf16_f32 v134, v28, v29
	v_cvt_pk_bf16_f32 v135, v30, v31
	ds_read_b128 v[244:247], v202 offset:38912
	s_waitcnt lgkmcnt(2)
	v_mfma_f32_16x16x32_bf16 v[112:115], v[236:239], v[0:3], v[204:207]
	v_cvt_pk_bf16_f32 v136, v32, v33
	v_cvt_pk_bf16_f32 v137, v34, v35
	v_mfma_f32_16x16x32_bf16 v[128:131], v[236:239], v[12:15], v[252:255]
	v_cvt_pk_bf16_f32 v138, v36, v37
	v_cvt_pk_bf16_f32 v139, v38, v39
	ds_read_b64_tr_b16 v[236:237], v203 offset:16448
	ds_read_b64_tr_b16 v[238:239], v203 offset:19008
	s_waitcnt lgkmcnt(3)
	v_mfma_f32_16x16x32_bf16 v[112:115], v[240:243], v[4:7], v[112:115]
	v_exp_f32_e32 v40, v40
	v_mfma_f32_16x16x32_bf16 v[128:131], v[240:243], v[16:19], v[128:131]
	v_exp_f32_e32 v41, v41
	ds_read_b64_tr_b16 v[240:241], v203 offset:21568
	ds_read_b64_tr_b16 v[242:243], v203 offset:24128
	s_waitcnt lgkmcnt(4)
	v_mfma_f32_16x16x32_bf16 v[112:115], v[244:247], v[8:11], v[112:115]
	v_exp_f32_e32 v42, v42
	v_mfma_f32_16x16x32_bf16 v[128:131], v[244:247], v[20:23], v[128:131]
	v_exp_f32_e32 v43, v43
	ds_read_b64_tr_b16 v[244:245], v203 offset:16480
	ds_read_b64_tr_b16 v[246:247], v203 offset:19040
	v_exp_f32_e32 v44, v44
	v_exp_f32_e32 v45, v45
	v_exp_f32_e32 v46, v46
	v_exp_f32_e32 v47, v47
	v_exp_f32_e32 v212, v212
	v_exp_f32_e32 v213, v213
	v_exp_f32_e32 v214, v214
	v_exp_f32_e32 v215, v215
	v_exp_f32_e32 v216, v216
	v_exp_f32_e32 v217, v217
	v_exp_f32_e32 v218, v218
	v_exp_f32_e32 v219, v219
	v_cvt_pk_bf16_f32 v140, v40, v41
	v_cvt_pk_bf16_f32 v141, v42, v43
	v_cvt_pk_bf16_f32 v142, v44, v45
	v_cvt_pk_bf16_f32 v143, v46, v47
	v_cvt_pk_bf16_f32 v52, v212, v213
	v_cvt_pk_bf16_f32 v53, v214, v215
	v_cvt_pk_bf16_f32 v54, v216, v217
	v_cvt_pk_bf16_f32 v55, v218, v219
	s_waitcnt lgkmcnt(15)
	v_mfma_f32_16x16x32_bf16 v[96:99], v[220:223], v[132:135], v[96:99]
	v_add_f32_e32 v24, v24, v25
	v_add_f32_e32 v26, v26, v27
	v_mfma_f32_16x16x32_bf16 v[84:87], v[220:223], v[140:143], v[84:87]
	v_add_f32_e32 v28, v28, v29
	v_add_f32_e32 v30, v30, v31
	v_mfma_f32_16x16x32_bf16 v[96:99], v[224:227], v[136:139], v[96:99]
	v_add_f32_e32 v32, v32, v33
	v_add_f32_e32 v34, v34, v35
	v_mfma_f32_16x16x32_bf16 v[84:87], v[224:227], v[52:55], v[84:87]
	v_add_f32_e32 v36, v36, v37
	v_add_f32_e32 v38, v38, v39
	ds_read_b64_tr_b16 v[220:221], v203 offset:21600
	ds_read_b64_tr_b16 v[222:223], v203 offset:24160
	v_mfma_f32_16x16x32_bf16 v[88:91], v[228:231], v[132:135], v[88:91]
	v_add_f32_e32 v24, v24, v26
	v_add_f32_e32 v28, v28, v30
	v_mfma_f32_16x16x32_bf16 v[76:79], v[228:231], v[140:143], v[76:79]
	v_add_f32_e32 v32, v32, v34
	v_add_f32_e32 v36, v36, v38
	v_mfma_f32_16x16x32_bf16 v[88:91], v[232:235], v[136:139], v[88:91]
	v_add_f32_e32 v24, v24, v28
	v_add_f32_e32 v32, v32, v36
	v_mfma_f32_16x16x32_bf16 v[76:79], v[232:235], v[52:55], v[76:79]
	v_add_f32_e32 v24, v24, v32
	v_add_f32_e32 v165, v165, v24
	s_waitcnt lgkmcnt(0)
	v_mfma_f32_16x16x32_bf16 v[92:95], v[236:239], v[132:135], v[92:95]
	v_add_f32_e32 v40, v40, v41
	v_add_f32_e32 v42, v42, v43
	v_mfma_f32_16x16x32_bf16 v[80:83], v[236:239], v[140:143], v[80:83]
	v_add_f32_e32 v44, v44, v45
	v_add_f32_e32 v46, v46, v47
	v_mfma_f32_16x16x32_bf16 v[92:95], v[240:243], v[136:139], v[92:95]
	v_add_f32_e32 v212, v212, v213
	v_add_f32_e32 v214, v214, v215
	v_mfma_f32_16x16x32_bf16 v[80:83], v[240:243], v[52:55], v[80:83]
	v_add_f32_e32 v216, v216, v217
	v_add_f32_e32 v218, v218, v219
	v_mfma_f32_16x16x32_bf16 v[48:51], v[244:247], v[132:135], v[48:51]
	v_add_f32_e32 v40, v40, v42
	v_add_f32_e32 v44, v44, v46
	v_mfma_f32_16x16x32_bf16 v[56:59], v[244:247], v[140:143], v[56:59]
	v_add_f32_e32 v212, v212, v214
	v_add_f32_e32 v216, v216, v218
	v_mfma_f32_16x16x32_bf16 v[48:51], v[220:223], v[136:139], v[48:51]
	v_add_f32_e32 v40, v40, v44
	v_add_f32_e32 v212, v212, v216
	v_mfma_f32_16x16x32_bf16 v[56:59], v[220:223], v[52:55], v[56:59]
	v_add_f32_e32 v40, v40, v212
	v_add_f32_e32 v164, v164, v40
	s_add_i32 s32, s49, 1
	s_cmp_eq_u32 s32, s9
	s_cbranch_scc1 .Lmla_mask1

; #define LAS __attribute__((address_space(3)))
; template <int I0, int NQ, int VO> __device__ __forceinline__ void tile_y(LAS unsigned char* lds, float (&l)[2], f32x4 (&o)[2][4], f32x4 (&s)[2][4], int fr, int fq) {
;     bf16x8 pb[NQ][2];
; #pragma unroll
;     for (int q = 0; q < NQ; ++q) {
;         f32x4 (&sq)[4] = s[I0 + q];
;         f32x2_t rs2 = {0.f, 0.f};
; #pragma unroll
;         for (int ss = 0; ss < 4; ++ss) {
; #pragma unroll
;             for (int i = 0; i < 4; ++i) sq[ss][i] = __builtin_amdgcn_exp2f(sq[ss][i]);
;             rs2 += (f32x2_t){sq[ss][0], sq[ss][1]}; rs2 += (f32x2_t){sq[ss][2], sq[ss][3]};
;         }
;         l[I0 + q] += rs2.x + rs2.y;
; #pragma unroll
;         for (int j = 0; j < 2; ++j) {
;             const v4u w = (v4u){cvtpk(sq[2 * j][0], sq[2 * j][1]), cvtpk(sq[2 * j][2], sq[2 * j][3]), cvtpk(sq[2 * j + 1][0], sq[2 * j + 1][1]), cvtpk(sq[2 * j + 1][2], sq[2 * j + 1][3])};
;             pb[q][j] = __builtin_bit_cast(bf16x8, w);
;         }
;     }
; #pragma unroll
;     for (int dt = 0; dt < 4; ++dt)
; #pragma unroll
;         for (int j = 0; j < 2; ++j) {
;             LAS unsigned char* vp = lds + VO + ((32 * j + 4 * fq + (fr >> 2)) * VSTR + 16 * dt + 4 * (fr & 3)) * 2;
;             const s16x4 lo = __builtin_bit_cast(s16x4, __builtin_amdgcn_ds_read_tr16_b64_v4i16((LAS v4i16_t*)vp));
;             const s16x4 hi = __builtin_bit_cast(s16x4, __builtin_amdgcn_ds_read_tr16_b64_v4i16((LAS v4i16_t*)(vp + 16 * VSTR * 2)));
;             const bf16x8 vf = (bf16x8){lo[0], lo[1], lo[2], lo[3], hi[0], hi[1], hi[2], hi[3]};
; #pragma unroll
;             for (int q = 0; q < NQ; ++q) o[I0 + q][dt] = __builtin_amdgcn_mfma_f32_16x16x32_bf16(vf, pb[q][j], o[I0 + q][dt], 0, 0, 0);
;         }
; }
; template <int DQK> __device__ __forceinline__ void x1_tile(LAS unsigned char* lds, const bf16x8 (&qf)[2][DQK / 32], const float (&m)[2], f32x4 (&s)[2][4], int fr, int fq) {
;     constexpr int NKS = DQK / 32;
; #pragma unroll
;     for (int q = 0; q < 2; ++q) { const float c = (m[q] > -1e29f) ? -m[q] : 0.f;
; #pragma unroll
;         for (int ss = 0; ss < 4; ++ss) s[q][ss] = (f32x4){c, c, c, c}; }
; #pragma unroll
;     for (int ss = 0; ss < 4; ++ss)
; #pragma unroll
;         for (int ks = 0; ks < NKS; ++ks) {
;             const bf16x8 kf = *(const LAS bf16x8*)(lds + k_off<DQK>(16 * ss + fr, 4 * ks + fq));
; #pragma unroll
.Lmla_nostage2:
	s_cmp_ge_u32 s49, s9
	s_cbranch_scc1 .Lmla_tail2
	ds_read_b64_tr_b16 v[220:221], v203 offset:43008
	ds_read_b64_tr_b16 v[222:223], v203 offset:45568
	ds_read_b64_tr_b16 v[224:225], v203 offset:48128
	ds_read_b64_tr_b16 v[226:227], v203 offset:50688
	ds_read_b64_tr_b16 v[228:229], v203 offset:43040
	ds_read_b64_tr_b16 v[230:231], v203 offset:45600
	ds_read_b64_tr_b16 v[232:233], v203 offset:48160
	ds_read_b64_tr_b16 v[234:235], v203 offset:50720
	ds_read_b128 v[236:239], v199
	ds_read_b128 v[240:243], v201
	ds_read_b128 v[244:247], v210
	s_waitcnt lgkmcnt(2)
	v_mfma_f32_16x16x32_bf16 v[24:27], v[236:239], v[0:3], v[204:207]
	v_exp_f32_e32 v100, v100
	v_mfma_f32_16x16x32_bf16 v[40:43], v[236:239], v[12:15], v[252:255]
	v_exp_f32_e32 v101, v101
	ds_read_b128 v[236:239], v199 offset:4096
	s_waitcnt lgkmcnt(2)
	v_mfma_f32_16x16x32_bf16 v[24:27], v[240:243], v[4:7], v[24:27]
	v_exp_f32_e32 v102, v102
	v_mfma_f32_16x16x32_bf16 v[40:43], v[240:243], v[16:19], v[40:43]
	v_exp_f32_e32 v103, v103
	ds_read_b128 v[240:243], v201 offset:4096
	s_waitcnt lgkmcnt(2)
	v_mfma_f32_16x16x32_bf16 v[24:27], v[244:247], v[8:11], v[24:27]
	v_exp_f32_e32 v104, v104
	v_mfma_f32_16x16x32_bf16 v[40:43], v[244:247], v[20:23], v[40:43]
	v_exp_f32_e32 v105, v105
	ds_read_b128 v[244:247], v210 offset:4096
	s_waitcnt lgkmcnt(2)
	v_mfma_f32_16x16x32_bf16 v[28:31], v[236:239], v[0:3], v[204:207]
	v_exp_f32_e32 v106, v106
	v_mfma_f32_16x16x32_bf16 v[44:47], v[236:239], v[12:15], v[252:255]
	v_exp_f32_e32 v107, v107
	ds_read_b128 v[236:239], v199 offset:8192
	s_waitcnt lgkmcnt(2)
	v_mfma_f32_16x16x32_bf16 v[28:31], v[240:243], v[4:7], v[28:31]
	v_exp_f32_e32 v108, v108
	v_mfma_f32_16x16x32_bf16 v[44:47], v[240:243], v[16:19], v[44:47]
	v_exp_f32_e32 v109, v109
	ds_read_b128 v[240:243], v201 offset:8192
	s_waitcnt lgkmcnt(2)
	v_mfma_f32_16x16x32_bf16 v[28:31], v[244:247], v[8:11], v[28:31]
	v_exp_f32_e32 v110, v110
	v_mfma_f32_16x16x32_bf16 v[44:47], v[244:247], v[20:23], v[44:47]
	v_exp_f32_e32 v111, v111
	ds_read_b128 v[244:247], v210 offset:8192
	s_waitcnt lgkmcnt(2)
	v_mfma_f32_16x16x32_bf16 v[32:35], v[236:239], v[0:3], v[204:207]
	v_exp_f32_e32 v112, v112
	v_mfma_f32_16x16x32_bf16 v[212:215], v[236:239], v[12:15], v[252:255]
	v_exp_f32_e32 v113, v113
	ds_read_b128 v[236:239], v199 offset:12288
	s_waitcnt lgkmcnt(2)
	v_mfma_f32_16x16x32_bf16 v[32:35], v[240:243], v[4:7], v[32:35]
	v_exp_f32_e32 v114, v114
	v_mfma_f32_16x16x32_bf16 v[212:215], v[240:243], v[16:19], v[212:215]
	v_exp_f32_e32 v115, v115
	ds_read_b128 v[240:243], v201 offset:12288
	s_waitcnt lgkmcnt(2)
	v_mfma_f32_16x16x32_bf16 v[32:35], v[244:247], v[8:11], v[32:35]
	v_cvt_pk_bf16_f32 v132, v100, v101
	v_cvt_pk_bf16_f32 v133, v102, v103
	v_mfma_f32_16x16x32_bf16 v[212:215], v[244:247], v[20:23], v[212:215]
	v_cvt_pk_bf16_f32 v134, v104, v105
	v_cvt_pk_bf16_f32 v135, v106, v107
	ds_read_b128 v[244:247], v210 offset:12288
	s_waitcnt lgkmcnt(2)
	v_mfma_f32_16x16x32_bf16 v[36:39], v[236:239], v[0:3], v[204:207]
	v_cvt_pk_bf16_f32 v136, v108, v109
	v_cvt_pk_bf16_f32 v137, v110, v111
	v_mfma_f32_16x16x32_bf16 v[216:219], v[236:239], v[12:15], v[252:255]
	v_cvt_pk_bf16_f32 v138, v112, v113
	v_cvt_pk_bf16_f32 v139, v114, v115
	ds_read_b64_tr_b16 v[236:237], v203 offset:43072
	ds_read_b64_tr_b16 v[238:239], v203 offset:45632
	s_waitcnt lgkmcnt(3)
	v_mfma_f32_16x16x32_bf16 v[36:39], v[240:243], v[4:7], v[36:39]
	v_exp_f32_e32 v116, v116
	v_mfma_f32_16x16x32_bf16 v[216:219], v[240:243], v[16:19], v[216:219]
	v_exp_f32_e32 v117, v117
	ds_read_b64_tr_b16 v[240:241], v203 offset:48192
	ds_read_b64_tr_b16 v[242:243], v203 offset:50752
	s_waitcnt lgkmcnt(4)
	v_mfma_f32_16x16x32_bf16 v[36:39], v[244:247], v[8:11], v[36:39]
	v_exp_f32_e32 v118, v118
	v_mfma_f32_16x16x32_bf16 v[216:219], v[244:247], v[20:23], v[216:219]
	v_exp_f32_e32 v119, v119
	ds_read_b64_tr_b16 v[244:245], v203 offset:43104
	ds_read_b64_tr_b16 v[246:247], v203 offset:45664
	v_exp_f32_e32 v120, v120
	v_exp_f32_e32 v121, v121
	v_exp_f32_e32 v122, v122
	v_exp_f32_e32 v123, v123
	v_exp_f32_e32 v124, v124
	v_exp_f32_e32 v125, v125
	v_exp_f32_e32 v126, v126
	v_exp_f32_e32 v127, v127
	v_exp_f32_e32 v128, v128
	v_exp_f32_e32 v129, v129
	v_exp_f32_e32 v130, v130
	v_exp_f32_e32 v131, v131
	v_cvt_pk_bf16_f32 v140, v116, v117
	v_cvt_pk_bf16_f32 v141, v118, v119
	v_cvt_pk_bf16_f32 v142, v120, v121
	v_cvt_pk_bf16_f32 v143, v122, v123
	v_cvt_pk_bf16_f32 v52, v124, v125
	v_cvt_pk_bf16_f32 v53, v126, v127
	v_cvt_pk_bf16_f32 v54, v128, v129
	v_cvt_pk_bf16_f32 v55, v130, v131
	s_waitcnt lgkmcnt(15)
	v_mfma_f32_16x16x32_bf16 v[96:99], v[220:223], v[132:135], v[96:99]
	v_add_f32_e32 v100, v100, v101
	v_add_f32_e32 v102, v102, v103
	v_mfma_f32_16x16x32_bf16 v[84:87], v[220:223], v[140:143], v[84:87]
	v_add_f32_e32 v104, v104, v105
	v_add_f32_e32 v106, v106, v107
	v_mfma_f32_16x16x32_bf16 v[96:99], v[224:227], v[136:139], v[96:99]
	v_add_f32_e32 v108, v108, v109
	v_add_f32_e32 v110, v110, v111
	v_mfma_f32_16x16x32_bf16 v[84:87], v[224:227], v[52:55], v[84:87]
	v_add_f32_e32 v112, v112, v113
	v_add_f32_e32 v114, v114, v115
	ds_read_b64_tr_b16 v[220:221], v203 offset:48224
	ds_read_b64_tr_b16 v[222:223], v203 offset:50784
	v_mfma_f32_16x16x32_bf16 v[88:91], v[228:231], v[132:135], v[88:91]
	v_add_f32_e32 v100, v100, v102
	v_add_f32_e32 v104, v104, v106
	v_mfma_f32_16x16x32_bf16 v[76:79], v[228:231], v[140:143], v[76:79]
	v_add_f32_e32 v108, v108, v110
	v_add_f32_e32 v112, v112, v114
	v_mfma_f32_16x16x32_bf16 v[88:91], v[232:235], v[136:139], v[88:91]
	v_add_f32_e32 v100, v100, v104
	v_add_f32_e32 v108, v108, v112
	v_mfma_f32_16x16x32_bf16 v[76:79], v[232:235], v[52:55], v[76:79]
	v_add_f32_e32 v100, v100, v108
	v_add_f32_e32 v165, v165, v100
	s_waitcnt lgkmcnt(0)
	v_mfma_f32_16x16x32_bf16 v[92:95], v[236:239], v[132:135], v[92:95]
	v_add_f32_e32 v116, v116, v117
	v_add_f32_e32 v118, v118, v119
	v_mfma_f32_16x16x32_bf16 v[80:83], v[236:239], v[140:143], v[80:83]
	v_add_f32_e32 v120, v120, v121
	v_add_f32_e32 v122, v122, v123
	v_mfma_f32_16x16x32_bf16 v[92:95], v[240:243], v[136:139], v[92:95]
	v_add_f32_e32 v124, v124, v125
	v_add_f32_e32 v126, v126, v127
	v_mfma_f32_16x16x32_bf16 v[80:83], v[240:243], v[52:55], v[80:83]
	v_add_f32_e32 v128, v128, v129
	v_add_f32_e32 v130, v130, v131
	v_mfma_f32_16x16x32_bf16 v[48:51], v[244:247], v[132:135], v[48:51]
	v_add_f32_e32 v116, v116, v118
	v_add_f32_e32 v120, v120, v122
	v_mfma_f32_16x16x32_bf16 v[56:59], v[244:247], v[140:143], v[56:59]
	v_add_f32_e32 v124, v124, v126
	v_add_f32_e32 v128, v128, v130
	v_mfma_f32_16x16x32_bf16 v[48:51], v[220:223], v[136:139], v[48:51]
	v_add_f32_e32 v116, v116, v120
	v_add_f32_e32 v124, v124, v128
	v_mfma_f32_16x16x32_bf16 v[56:59], v[220:223], v[52:55], v[56:59]
	v_add_f32_e32 v116, v116, v124
	v_add_f32_e32 v164, v164, v116
	s_add_i32 s32, s49, 1
	s_cmp_eq_u32 s32, s9
	s_cbranch_scc1 .Lmla_mask2

; #define LAS __attribute__((address_space(3)))
; template <int I0, int NQ, int VO> __device__ __forceinline__ void tile_y(LAS unsigned char* lds, float (&l)[2], f32x4 (&o)[2][4], f32x4 (&s)[2][4], int fr, int fq) {
;     bf16x8 pb[NQ][2];
; #pragma unroll
;     for (int q = 0; q < NQ; ++q) {
;         f32x4 (&sq)[4] = s[I0 + q];
;         f32x2_t rs2 = {0.f, 0.f};
; #pragma unroll
;         for (int ss = 0; ss < 4; ++ss) {
; #pragma unroll
;             for (int i = 0; i < 4; ++i) sq[ss][i] = __builtin_amdgcn_exp2f(sq[ss][i]);
;             rs2 += (f32x2_t){sq[ss][0], sq[ss][1]}; rs2 += (f32x2_t){sq[ss][2], sq[ss][3]};
;         }
;         l[I0 + q] += rs2.x + rs2.y;
; #pragma unroll
;         for (int j = 0; j < 2; ++j) {
;             const v4u w = (v4u){cvtpk(sq[2 * j][0], sq[2 * j][1]), cvtpk(sq[2 * j][2], sq[2 * j][3]), cvtpk(sq[2 * j + 1][0], sq[2 * j + 1][1]), cvtpk(sq[2 * j + 1][2], sq[2 * j + 1][3])};
;             pb[q][j] = __builtin_bit_cast(bf16x8, w);
;         }
;     }
; #pragma unroll
;     for (int dt = 0; dt < 4; ++dt)
; #pragma unroll
;         for (int j = 0; j < 2; ++j) {
;             LAS unsigned char* vp = lds + VO + ((32 * j + 4 * fq + (fr >> 2)) * VSTR + 16 * dt + 4 * (fr & 3)) * 2;
;             const s16x4 lo = __builtin_bit_cast(s16x4, __builtin_amdgcn_ds_read_tr16_b64_v4i16((LAS v4i16_t*)vp));
;             const s16x4 hi = __builtin_bit_cast(s16x4, __builtin_amdgcn_ds_read_tr16_b64_v4i16((LAS v4i16_t*)(vp + 16 * VSTR * 2)));
;             const bf16x8 vf = (bf16x8){lo[0], lo[1], lo[2], lo[3], hi[0], hi[1], hi[2], hi[3]};
; #pragma unroll
;             for (int q = 0; q < NQ; ++q) o[I0 + q][dt] = __builtin_amdgcn_mfma_f32_16x16x32_bf16(vf, pb[q][j], o[I0 + q][dt], 0, 0, 0);
;         }
; }
; template <int DQK> __device__ __forceinline__ void x1_tile(LAS unsigned char* lds, const bf16x8 (&qf)[2][DQK / 32], const float (&m)[2], f32x4 (&s)[2][4], int fr, int fq) {
;     constexpr int NKS = DQK / 32;
; #pragma unroll
;     for (int q = 0; q < 2; ++q) { const float c = (m[q] > -1e29f) ? -m[q] : 0.f;
; #pragma unroll
;         for (int ss = 0; ss < 4; ++ss) s[q][ss] = (f32x4){c, c, c, c}; }
; #pragma unroll
;     for (int ss = 0; ss < 4; ++ss)
; #pragma unroll
;         for (int ks = 0; ks < NKS; ++ks) {
;             const bf16x8 kf = *(const LAS bf16x8*)(lds + k_off<DQK>(16 * ss + fr, 4 * ks + fq));
; #pragma unroll
.Lmla_nostage3:
	s_cmp_ge_u32 s49, s9
	s_cbranch_scc1 .Lmla_tail3
	ds_read_b64_tr_b16 v[220:221], v251 offset:16384
	ds_read_b64_tr_b16 v[222:223], v251 offset:18944
	ds_read_b64_tr_b16 v[224:225], v251 offset:21504
	ds_read_b64_tr_b16 v[226:227], v251 offset:24064
	ds_read_b64_tr_b16 v[228:229], v251 offset:16416
	ds_read_b64_tr_b16 v[230:231], v251 offset:18976
	ds_read_b64_tr_b16 v[232:233], v251 offset:21536
	ds_read_b64_tr_b16 v[234:235], v251 offset:24096
	ds_read_b128 v[236:239], v195
	ds_read_b128 v[240:243], v196
	ds_read_b128 v[244:247], v202
	s_waitcnt lgkmcnt(2)
	v_mfma_f32_16x16x32_bf16 v[100:103], v[236:239], v[0:3], v[204:207]
	v_exp_f32_e32 v24, v24
	v_mfma_f32_16x16x32_bf16 v[116:119], v[236:239], v[12:15], v[252:255]
	v_exp_f32_e32 v25, v25
	ds_read_b128 v[236:239], v195 offset:4096
	s_waitcnt lgkmcnt(2)
	v_mfma_f32_16x16x32_bf16 v[100:103], v[240:243], v[4:7], v[100:103]
	v_exp_f32_e32 v26, v26
	v_mfma_f32_16x16x32_bf16 v[116:119], v[240:243], v[16:19], v[116:119]
	v_exp_f32_e32 v27, v27
	ds_read_b128 v[240:243], v196 offset:4096
	s_waitcnt lgkmcnt(2)
	v_mfma_f32_16x16x32_bf16 v[100:103], v[244:247], v[8:11], v[100:103]
	v_exp_f32_e32 v28, v28
	v_mfma_f32_16x16x32_bf16 v[116:119], v[244:247], v[20:23], v[116:119]
	v_exp_f32_e32 v29, v29
	ds_read_b128 v[244:247], v202 offset:4096
	s_waitcnt lgkmcnt(2)
	v_mfma_f32_16x16x32_bf16 v[104:107], v[236:239], v[0:3], v[204:207]
	v_exp_f32_e32 v30, v30
	v_mfma_f32_16x16x32_bf16 v[120:123], v[236:239], v[12:15], v[252:255]
	v_exp_f32_e32 v31, v31
	ds_read_b128 v[236:239], v195 offset:8192
	s_waitcnt lgkmcnt(2)
	v_mfma_f32_16x16x32_bf16 v[104:107], v[240:243], v[4:7], v[104:107]
	v_exp_f32_e32 v32, v32
	v_mfma_f32_16x16x32_bf16 v[120:123], v[240:243], v[16:19], v[120:123]
	v_exp_f32_e32 v33, v33
	ds_read_b128 v[240:243], v196 offset:8192
	s_waitcnt lgkmcnt(2)
	v_mfma_f32_16x16x32_bf16 v[104:107], v[244:247], v[8:11], v[104:107]
	v_exp_f32_e32 v34, v34
	v_mfma_f32_16x16x32_bf16 v[120:123], v[244:247], v[20:23], v[120:123]
	v_exp_f32_e32 v35, v35
	ds_read_b128 v[244:247], v202 offset:8192
	s_waitcnt lgkmcnt(2)
	v_mfma_f32_16x16x32_bf16 v[108:111], v[236:239], v[0:3], v[204:207]
	v_exp_f32_e32 v36, v36
	v_mfma_f32_16x16x32_bf16 v[124:127], v[236:239], v[12:15], v[252:255]
	v_exp_f32_e32 v37, v37
	ds_read_b128 v[236:239], v195 offset:12288
	s_waitcnt lgkmcnt(2)
	v_mfma_f32_16x16x32_bf16 v[108:111], v[240:243], v[4:7], v[108:111]
	v_exp_f32_e32 v38, v38
	v_mfma_f32_16x16x32_bf16 v[124:127], v[240:243], v[16:19], v[124:127]
	v_exp_f32_e32 v39, v39
	ds_read_b128 v[240:243], v196 offset:12288
	s_waitcnt lgkmcnt(2)
	v_mfma_f32_16x16x32_bf16 v[108:111], v[244:247], v[8:11], v[108:111]
	v_cvt_pk_bf16_f32 v132, v24, v25
	v_cvt_pk_bf16_f32 v133, v26, v27
	v_mfma_f32_16x16x32_bf16 v[124:127], v[244:247], v[20:23], v[124:127]
	v_cvt_pk_bf16_f32 v134, v28, v29
	v_cvt_pk_bf16_f32 v135, v30, v31
	ds_read_b128 v[244:247], v202 offset:12288
	s_waitcnt lgkmcnt(2)
	v_mfma_f32_16x16x32_bf16 v[112:115], v[236:239], v[0:3], v[204:207]
	v_cvt_pk_bf16_f32 v136, v32, v33
	v_cvt_pk_bf16_f32 v137, v34, v35
	v_mfma_f32_16x16x32_bf16 v[128:131], v[236:239], v[12:15], v[252:255]
	v_cvt_pk_bf16_f32 v138, v36, v37
	v_cvt_pk_bf16_f32 v139, v38, v39
	ds_read_b64_tr_b16 v[236:237], v251 offset:16448
	ds_read_b64_tr_b16 v[238:239], v251 offset:19008
	s_waitcnt lgkmcnt(3)
	v_mfma_f32_16x16x32_bf16 v[112:115], v[240:243], v[4:7], v[112:115]
	v_exp_f32_e32 v40, v40
	v_mfma_f32_16x16x32_bf16 v[128:131], v[240:243], v[16:19], v[128:131]
	v_exp_f32_e32 v41, v41
	ds_read_b64_tr_b16 v[240:241], v251 offset:21568
	ds_read_b64_tr_b16 v[242:243], v251 offset:24128
	s_waitcnt lgkmcnt(4)
	v_mfma_f32_16x16x32_bf16 v[112:115], v[244:247], v[8:11], v[112:115]
	v_exp_f32_e32 v42, v42
	v_mfma_f32_16x16x32_bf16 v[128:131], v[244:247], v[20:23], v[128:131]
	v_exp_f32_e32 v43, v43
	ds_read_b64_tr_b16 v[244:245], v251 offset:16480
	ds_read_b64_tr_b16 v[246:247], v251 offset:19040
	v_exp_f32_e32 v44, v44
	v_exp_f32_e32 v45, v45
	v_exp_f32_e32 v46, v46
	v_exp_f32_e32 v47, v47
	v_exp_f32_e32 v212, v212
	v_exp_f32_e32 v213, v213
	v_exp_f32_e32 v214, v214
	v_exp_f32_e32 v215, v215
	v_exp_f32_e32 v216, v216
	v_exp_f32_e32 v217, v217
	v_exp_f32_e32 v218, v218
	v_exp_f32_e32 v219, v219
	v_cvt_pk_bf16_f32 v140, v40, v41
	v_cvt_pk_bf16_f32 v141, v42, v43
	v_cvt_pk_bf16_f32 v142, v44, v45
	v_cvt_pk_bf16_f32 v143, v46, v47
	v_cvt_pk_bf16_f32 v52, v212, v213
	v_cvt_pk_bf16_f32 v53, v214, v215
	v_cvt_pk_bf16_f32 v54, v216, v217
	v_cvt_pk_bf16_f32 v55, v218, v219
	s_waitcnt lgkmcnt(15)
	v_mfma_f32_16x16x32_bf16 v[96:99], v[220:223], v[132:135], v[96:99]
	v_add_f32_e32 v24, v24, v25
	v_add_f32_e32 v26, v26, v27
	v_mfma_f32_16x16x32_bf16 v[84:87], v[220:223], v[140:143], v[84:87]
	v_add_f32_e32 v28, v28, v29
	v_add_f32_e32 v30, v30, v31
	v_mfma_f32_16x16x32_bf16 v[96:99], v[224:227], v[136:139], v[96:99]
	v_add_f32_e32 v32, v32, v33
	v_add_f32_e32 v34, v34, v35
	v_mfma_f32_16x16x32_bf16 v[84:87], v[224:227], v[52:55], v[84:87]
	v_add_f32_e32 v36, v36, v37
	v_add_f32_e32 v38, v38, v39
	ds_read_b64_tr_b16 v[220:221], v251 offset:21600
	ds_read_b64_tr_b16 v[222:223], v251 offset:24160
	v_mfma_f32_16x16x32_bf16 v[88:91], v[228:231], v[132:135], v[88:91]
	v_add_f32_e32 v24, v24, v26
	v_add_f32_e32 v28, v28, v30
	v_mfma_f32_16x16x32_bf16 v[76:79], v[228:231], v[140:143], v[76:79]
	v_add_f32_e32 v32, v32, v34
	v_add_f32_e32 v36, v36, v38
	v_mfma_f32_16x16x32_bf16 v[88:91], v[232:235], v[136:139], v[88:91]
	v_add_f32_e32 v24, v24, v28
	v_add_f32_e32 v32, v32, v36
	v_mfma_f32_16x16x32_bf16 v[76:79], v[232:235], v[52:55], v[76:79]
	v_add_f32_e32 v24, v24, v32
	v_add_f32_e32 v165, v165, v24
	s_waitcnt lgkmcnt(0)
	v_mfma_f32_16x16x32_bf16 v[92:95], v[236:239], v[132:135], v[92:95]
	v_add_f32_e32 v40, v40, v41
	v_add_f32_e32 v42, v42, v43
	v_mfma_f32_16x16x32_bf16 v[80:83], v[236:239], v[140:143], v[80:83]
	v_add_f32_e32 v44, v44, v45
	v_add_f32_e32 v46, v46, v47
	v_mfma_f32_16x16x32_bf16 v[92:95], v[240:243], v[136:139], v[92:95]
	v_add_f32_e32 v212, v212, v213
	v_add_f32_e32 v214, v214, v215
	v_mfma_f32_16x16x32_bf16 v[80:83], v[240:243], v[52:55], v[80:83]
	v_add_f32_e32 v216, v216, v217
	v_add_f32_e32 v218, v218, v219
	v_mfma_f32_16x16x32_bf16 v[48:51], v[244:247], v[132:135], v[48:51]
	v_add_f32_e32 v40, v40, v42
	v_add_f32_e32 v44, v44, v46
	v_mfma_f32_16x16x32_bf16 v[56:59], v[244:247], v[140:143], v[56:59]
	v_add_f32_e32 v212, v212, v214
	v_add_f32_e32 v216, v216, v218
	v_mfma_f32_16x16x32_bf16 v[48:51], v[220:223], v[136:139], v[48:51]
	v_add_f32_e32 v40, v40, v44
	v_add_f32_e32 v212, v212, v216
	v_mfma_f32_16x16x32_bf16 v[56:59], v[220:223], v[52:55], v[56:59]
	v_add_f32_e32 v40, v40, v212
	v_add_f32_e32 v164, v164, v40
	s_add_i32 s32, s49, 1
	s_cmp_eq_u32 s32, s9
	s_cbranch_scc1 .Lmla_mask3

; #define LAS __attribute__((address_space(3)))
; template <int I0, int NQ, int VO> __device__ __forceinline__ void tile_y(LAS unsigned char* lds, float (&l)[2], f32x4 (&o)[2][4], f32x4 (&s)[2][4], int fr, int fq) {
;     bf16x8 pb[NQ][2];
; #pragma unroll
;     for (int q = 0; q < NQ; ++q) {
;         f32x4 (&sq)[4] = s[I0 + q];
;         f32x2_t rs2 = {0.f, 0.f};
; #pragma unroll
;         for (int ss = 0; ss < 4; ++ss) {
; #pragma unroll
;             for (int i = 0; i < 4; ++i) sq[ss][i] = __builtin_amdgcn_exp2f(sq[ss][i]);
;             rs2 += (f32x2_t){sq[ss][0], sq[ss][1]}; rs2 += (f32x2_t){sq[ss][2], sq[ss][3]};
;         }
;         l[I0 + q] += rs2.x + rs2.y;
; #pragma unroll
;         for (int j = 0; j < 2; ++j) {
;             const v4u w = (v4u){cvtpk(sq[2 * j][0], sq[2 * j][1]), cvtpk(sq[2 * j][2], sq[2 * j][3]), cvtpk(sq[2 * j + 1][0], sq[2 * j + 1][1]), cvtpk(sq[2 * j + 1][2], sq[2 * j + 1][3])};
;             pb[q][j] = __builtin_bit_cast(bf16x8, w);
;         }
;     }
; #pragma unroll
;     for (int dt = 0; dt < 4; ++dt)
; #pragma unroll
;         for (int j = 0; j < 2; ++j) {
;             LAS unsigned char* vp = lds + VO + ((32 * j + 4 * fq + (fr >> 2)) * VSTR + 16 * dt + 4 * (fr & 3)) * 2;
;             const s16x4 lo = __builtin_bit_cast(s16x4, __builtin_amdgcn_ds_read_tr16_b64_v4i16((LAS v4i16_t*)vp));
;             const s16x4 hi = __builtin_bit_cast(s16x4, __builtin_amdgcn_ds_read_tr16_b64_v4i16((LAS v4i16_t*)(vp + 16 * VSTR * 2)));
;             const bf16x8 vf = (bf16x8){lo[0], lo[1], lo[2], lo[3], hi[0], hi[1], hi[2], hi[3]};
; #pragma unroll
;             for (int q = 0; q < NQ; ++q) o[I0 + q][dt] = __builtin_amdgcn_mfma_f32_16x16x32_bf16(vf, pb[q][j], o[I0 + q][dt], 0, 0, 0);
;         }
; }
; template <int DQK> __device__ __forceinline__ void x1_tile(LAS unsigned char* lds, const bf16x8 (&qf)[2][DQK / 32], const float (&m)[2], f32x4 (&s)[2][4], int fr, int fq) {
;     constexpr int NKS = DQK / 32;
; #pragma unroll
;     for (int q = 0; q < 2; ++q) { const float c = (m[q] > -1e29f) ? -m[q] : 0.f;
; #pragma unroll
;         for (int ss = 0; ss < 4; ++ss) s[q][ss] = (f32x4){c, c, c, c}; }
; #pragma unroll
;     for (int ss = 0; ss < 4; ++ss)
; #pragma unroll
;         for (int ks = 0; ks < NKS; ++ks) {
;             const bf16x8 kf = *(const LAS bf16x8*)(lds + k_off<DQK>(16 * ss + fr, 4 * ks + fq));
; #pragma unroll
.Lmla_nostage4:
	s_cmp_ge_u32 s49, s9
	s_cbranch_scc1 .Lmla_tail4
	ds_read_b64_tr_b16 v[220:221], v203 offset:16384
	ds_read_b64_tr_b16 v[222:223], v203 offset:18944
	ds_read_b64_tr_b16 v[224:225], v203 offset:21504
	ds_read_b64_tr_b16 v[226:227], v203 offset:24064
	ds_read_b64_tr_b16 v[228:229], v203 offset:16416
	ds_read_b64_tr_b16 v[230:231], v203 offset:18976
	ds_read_b64_tr_b16 v[232:233], v203 offset:21536
	ds_read_b64_tr_b16 v[234:235], v203 offset:24096
	ds_read_b128 v[236:239], v195 offset:26624
	ds_read_b128 v[240:243], v196 offset:26624
	ds_read_b128 v[244:247], v202 offset:26624
	s_waitcnt lgkmcnt(2)
	v_mfma_f32_16x16x32_bf16 v[24:27], v[236:239], v[0:3], v[204:207]
	v_exp_f32_e32 v100, v100
	v_mfma_f32_16x16x32_bf16 v[40:43], v[236:239], v[12:15], v[252:255]
	v_exp_f32_e32 v101, v101
	ds_read_b128 v[236:239], v195 offset:30720
	s_waitcnt lgkmcnt(2)
	v_mfma_f32_16x16x32_bf16 v[24:27], v[240:243], v[4:7], v[24:27]
	v_exp_f32_e32 v102, v102
	v_mfma_f32_16x16x32_bf16 v[40:43], v[240:243], v[16:19], v[40:43]
	v_exp_f32_e32 v103, v103
	ds_read_b128 v[240:243], v196 offset:30720
	s_waitcnt lgkmcnt(2)
	v_mfma_f32_16x16x32_bf16 v[24:27], v[244:247], v[8:11], v[24:27]
	v_exp_f32_e32 v104, v104
	v_mfma_f32_16x16x32_bf16 v[40:43], v[244:247], v[20:23], v[40:43]
	v_exp_f32_e32 v105, v105
	ds_read_b128 v[244:247], v202 offset:30720
	s_waitcnt lgkmcnt(2)
	v_mfma_f32_16x16x32_bf16 v[28:31], v[236:239], v[0:3], v[204:207]
	v_exp_f32_e32 v106, v106
	v_mfma_f32_16x16x32_bf16 v[44:47], v[236:239], v[12:15], v[252:255]
	v_exp_f32_e32 v107, v107
	ds_read_b128 v[236:239], v195 offset:34816
	s_waitcnt lgkmcnt(2)
	v_mfma_f32_16x16x32_bf16 v[28:31], v[240:243], v[4:7], v[28:31]
	v_exp_f32_e32 v108, v108
	v_mfma_f32_16x16x32_bf16 v[44:47], v[240:243], v[16:19], v[44:47]
	v_exp_f32_e32 v109, v109
	ds_read_b128 v[240:243], v196 offset:34816
	s_waitcnt lgkmcnt(2)
	v_mfma_f32_16x16x32_bf16 v[28:31], v[244:247], v[8:11], v[28:31]
	v_exp_f32_e32 v110, v110
	v_mfma_f32_16x16x32_bf16 v[44:47], v[244:247], v[20:23], v[44:47]
	v_exp_f32_e32 v111, v111
	ds_read_b128 v[244:247], v202 offset:34816
	s_waitcnt lgkmcnt(2)
	v_mfma_f32_16x16x32_bf16 v[32:35], v[236:239], v[0:3], v[204:207]
	v_exp_f32_e32 v112, v112
	v_mfma_f32_16x16x32_bf16 v[212:215], v[236:239], v[12:15], v[252:255]
	v_exp_f32_e32 v113, v113
	ds_read_b128 v[236:239], v195 offset:38912
	s_waitcnt lgkmcnt(2)
	v_mfma_f32_16x16x32_bf16 v[32:35], v[240:243], v[4:7], v[32:35]
	v_exp_f32_e32 v114, v114
	v_mfma_f32_16x16x32_bf16 v[212:215], v[240:243], v[16:19], v[212:215]
	v_exp_f32_e32 v115, v115
	ds_read_b128 v[240:243], v196 offset:38912
	s_waitcnt lgkmcnt(2)
	v_mfma_f32_16x16x32_bf16 v[32:35], v[244:247], v[8:11], v[32:35]
	v_cvt_pk_bf16_f32 v132, v100, v101
	v_cvt_pk_bf16_f32 v133, v102, v103
	v_mfma_f32_16x16x32_bf16 v[212:215], v[244:247], v[20:23], v[212:215]
	v_cvt_pk_bf16_f32 v134, v104, v105
	v_cvt_pk_bf16_f32 v135, v106, v107
	ds_read_b128 v[244:247], v202 offset:38912
	s_waitcnt lgkmcnt(2)
	v_mfma_f32_16x16x32_bf16 v[36:39], v[236:239], v[0:3], v[204:207]
	v_cvt_pk_bf16_f32 v136, v108, v109
	v_cvt_pk_bf16_f32 v137, v110, v111
	v_mfma_f32_16x16x32_bf16 v[216:219], v[236:239], v[12:15], v[252:255]
	v_cvt_pk_bf16_f32 v138, v112, v113
	v_cvt_pk_bf16_f32 v139, v114, v115
	ds_read_b64_tr_b16 v[236:237], v203 offset:16448
	ds_read_b64_tr_b16 v[238:239], v203 offset:19008
	s_waitcnt lgkmcnt(3)
	v_mfma_f32_16x16x32_bf16 v[36:39], v[240:243], v[4:7], v[36:39]
	v_exp_f32_e32 v116, v116
	v_mfma_f32_16x16x32_bf16 v[216:219], v[240:243], v[16:19], v[216:219]
	v_exp_f32_e32 v117, v117
	ds_read_b64_tr_b16 v[240:241], v203 offset:21568
	ds_read_b64_tr_b16 v[242:243], v203 offset:24128
	s_waitcnt lgkmcnt(4)
	v_mfma_f32_16x16x32_bf16 v[36:39], v[244:247], v[8:11], v[36:39]
	v_exp_f32_e32 v118, v118
	v_mfma_f32_16x16x32_bf16 v[216:219], v[244:247], v[20:23], v[216:219]
	v_exp_f32_e32 v119, v119
	ds_read_b64_tr_b16 v[244:245], v203 offset:16480
	ds_read_b64_tr_b16 v[246:247], v203 offset:19040
	v_exp_f32_e32 v120, v120
	v_exp_f32_e32 v121, v121
	v_exp_f32_e32 v122, v122
	v_exp_f32_e32 v123, v123
	v_exp_f32_e32 v124, v124
	v_exp_f32_e32 v125, v125
	v_exp_f32_e32 v126, v126
	v_exp_f32_e32 v127, v127
	v_exp_f32_e32 v128, v128
	v_exp_f32_e32 v129, v129
	v_exp_f32_e32 v130, v130
	v_exp_f32_e32 v131, v131
	v_cvt_pk_bf16_f32 v140, v116, v117
	v_cvt_pk_bf16_f32 v141, v118, v119
	v_cvt_pk_bf16_f32 v142, v120, v121
	v_cvt_pk_bf16_f32 v143, v122, v123
	v_cvt_pk_bf16_f32 v52, v124, v125
	v_cvt_pk_bf16_f32 v53, v126, v127
	v_cvt_pk_bf16_f32 v54, v128, v129
	v_cvt_pk_bf16_f32 v55, v130, v131
	s_waitcnt lgkmcnt(15)
	v_mfma_f32_16x16x32_bf16 v[96:99], v[220:223], v[132:135], v[96:99]
	v_add_f32_e32 v100, v100, v101
	v_add_f32_e32 v102, v102, v103
	v_mfma_f32_16x16x32_bf16 v[84:87], v[220:223], v[140:143], v[84:87]
	v_add_f32_e32 v104, v104, v105
	v_add_f32_e32 v106, v106, v107
	v_mfma_f32_16x16x32_bf16 v[96:99], v[224:227], v[136:139], v[96:99]
	v_add_f32_e32 v108, v108, v109
	v_add_f32_e32 v110, v110, v111
	v_mfma_f32_16x16x32_bf16 v[84:87], v[224:227], v[52:55], v[84:87]
	v_add_f32_e32 v112, v112, v113
	v_add_f32_e32 v114, v114, v115
	ds_read_b64_tr_b16 v[220:221], v203 offset:21600
	ds_read_b64_tr_b16 v[222:223], v203 offset:24160
	v_mfma_f32_16x16x32_bf16 v[88:91], v[228:231], v[132:135], v[88:91]
	v_add_f32_e32 v100, v100, v102
	v_add_f32_e32 v104, v104, v106
	v_mfma_f32_16x16x32_bf16 v[76:79], v[228:231], v[140:143], v[76:79]
	v_add_f32_e32 v108, v108, v110
	v_add_f32_e32 v112, v112, v114
	v_mfma_f32_16x16x32_bf16 v[88:91], v[232:235], v[136:139], v[88:91]
	v_add_f32_e32 v100, v100, v104
	v_add_f32_e32 v108, v108, v112
	v_mfma_f32_16x16x32_bf16 v[76:79], v[232:235], v[52:55], v[76:79]
	v_add_f32_e32 v100, v100, v108
	v_add_f32_e32 v165, v165, v100
	s_waitcnt lgkmcnt(0)
	v_mfma_f32_16x16x32_bf16 v[92:95], v[236:239], v[132:135], v[92:95]
	v_add_f32_e32 v116, v116, v117
	v_add_f32_e32 v118, v118, v119
	v_mfma_f32_16x16x32_bf16 v[80:83], v[236:239], v[140:143], v[80:83]
	v_add_f32_e32 v120, v120, v121
	v_add_f32_e32 v122, v122, v123
	v_mfma_f32_16x16x32_bf16 v[92:95], v[240:243], v[136:139], v[92:95]
	v_add_f32_e32 v124, v124, v125
	v_add_f32_e32 v126, v126, v127
	v_mfma_f32_16x16x32_bf16 v[80:83], v[240:243], v[52:55], v[80:83]
	v_add_f32_e32 v128, v128, v129
	v_add_f32_e32 v130, v130, v131
	v_mfma_f32_16x16x32_bf16 v[48:51], v[244:247], v[132:135], v[48:51]
	v_add_f32_e32 v116, v116, v118
	v_add_f32_e32 v120, v120, v122
	v_mfma_f32_16x16x32_bf16 v[56:59], v[244:247], v[140:143], v[56:59]
	v_add_f32_e32 v124, v124, v126
	v_add_f32_e32 v128, v128, v130
	v_mfma_f32_16x16x32_bf16 v[48:51], v[220:223], v[136:139], v[48:51]
	v_add_f32_e32 v116, v116, v120
	v_add_f32_e32 v124, v124, v128
	v_mfma_f32_16x16x32_bf16 v[56:59], v[220:223], v[52:55], v[56:59]
	v_add_f32_e32 v116, v116, v124
	v_add_f32_e32 v164, v164, v116
	s_add_i32 s32, s49, 1
	s_cmp_eq_u32 s32, s9
	s_cbranch_scc1 .Lmla_mask4

; #define LAS __attribute__((address_space(3)))
; template <int I0, int NQ, int VO> __device__ __forceinline__ void tile_y(LAS unsigned char* lds, float (&l)[2], f32x4 (&o)[2][4], f32x4 (&s)[2][4], int fr, int fq) {
;     bf16x8 pb[NQ][2];
; #pragma unroll
;     for (int q = 0; q < NQ; ++q) {
;         f32x4 (&sq)[4] = s[I0 + q];
;         f32x2_t rs2 = {0.f, 0.f};
; #pragma unroll
;         for (int ss = 0; ss < 4; ++ss) {
; #pragma unroll
;             for (int i = 0; i < 4; ++i) sq[ss][i] = __builtin_amdgcn_exp2f(sq[ss][i]);
;             rs2 += (f32x2_t){sq[ss][0], sq[ss][1]}; rs2 += (f32x2_t){sq[ss][2], sq[ss][3]};
;         }
;         l[I0 + q] += rs2.x + rs2.y;
; #pragma unroll
;         for (int j = 0; j < 2; ++j) {
;             const v4u w = (v4u){cvtpk(sq[2 * j][0], sq[2 * j][1]), cvtpk(sq[2 * j][2], sq[2 * j][3]), cvtpk(sq[2 * j + 1][0], sq[2 * j + 1][1]), cvtpk(sq[2 * j + 1][2], sq[2 * j + 1][3])};
;             pb[q][j] = __builtin_bit_cast(bf16x8, w);
;         }
;     }
; #pragma unroll
;     for (int dt = 0; dt < 4; ++dt)
; #pragma unroll
;         for (int j = 0; j < 2; ++j) {
;             LAS unsigned char* vp = lds + VO + ((32 * j + 4 * fq + (fr >> 2)) * VSTR + 16 * dt + 4 * (fr & 3)) * 2;
;             const s16x4 lo = __builtin_bit_cast(s16x4, __builtin_amdgcn_ds_read_tr16_b64_v4i16((LAS v4i16_t*)vp));
;             const s16x4 hi = __builtin_bit_cast(s16x4, __builtin_amdgcn_ds_read_tr16_b64_v4i16((LAS v4i16_t*)(vp + 16 * VSTR * 2)));
;             const bf16x8 vf = (bf16x8){lo[0], lo[1], lo[2], lo[3], hi[0], hi[1], hi[2], hi[3]};
; #pragma unroll
;             for (int q = 0; q < NQ; ++q) o[I0 + q][dt] = __builtin_amdgcn_mfma_f32_16x16x32_bf16(vf, pb[q][j], o[I0 + q][dt], 0, 0, 0);
;         }
; }
; template <int DQK> __device__ __forceinline__ void x1_tile(LAS unsigned char* lds, const bf16x8 (&qf)[2][DQK / 32], const float (&m)[2], f32x4 (&s)[2][4], int fr, int fq) {
;     constexpr int NKS = DQK / 32;
; #pragma unroll
;     for (int q = 0; q < 2; ++q) { const float c = (m[q] > -1e29f) ? -m[q] : 0.f;
; #pragma unroll
;         for (int ss = 0; ss < 4; ++ss) s[q][ss] = (f32x4){c, c, c, c}; }
; #pragma unroll
;     for (int ss = 0; ss < 4; ++ss)
; #pragma unroll
;         for (int ks = 0; ks < NKS; ++ks) {
;             const bf16x8 kf = *(const LAS bf16x8*)(lds + k_off<DQK>(16 * ss + fr, 4 * ks + fq));
; #pragma unroll
.Lmla_nostage5:
	s_cmp_ge_u32 s49, s9
	s_cbranch_scc1 .Lmla_tail5
	ds_read_b64_tr_b16 v[220:221], v203 offset:43008
	ds_read_b64_tr_b16 v[222:223], v203 offset:45568
	ds_read_b64_tr_b16 v[224:225], v203 offset:48128
	ds_read_b64_tr_b16 v[226:227], v203 offset:50688
	ds_read_b64_tr_b16 v[228:229], v203 offset:43040
	ds_read_b64_tr_b16 v[230:231], v203 offset:45600
	ds_read_b64_tr_b16 v[232:233], v203 offset:48160
	ds_read_b64_tr_b16 v[234:235], v203 offset:50720
	ds_read_b128 v[236:239], v199
	ds_read_b128 v[240:243], v201
	ds_read_b128 v[244:247], v210
	s_waitcnt lgkmcnt(2)
	v_mfma_f32_16x16x32_bf16 v[100:103], v[236:239], v[0:3], v[204:207]
	v_exp_f32_e32 v24, v24
	v_mfma_f32_16x16x32_bf16 v[116:119], v[236:239], v[12:15], v[252:255]
	v_exp_f32_e32 v25, v25
	ds_read_b128 v[236:239], v199 offset:4096
	s_waitcnt lgkmcnt(2)
	v_mfma_f32_16x16x32_bf16 v[100:103], v[240:243], v[4:7], v[100:103]
	v_exp_f32_e32 v26, v26
	v_mfma_f32_16x16x32_bf16 v[116:119], v[240:243], v[16:19], v[116:119]
	v_exp_f32_e32 v27, v27
	ds_read_b128 v[240:243], v201 offset:4096
	s_waitcnt lgkmcnt(2)
	v_mfma_f32_16x16x32_bf16 v[100:103], v[244:247], v[8:11], v[100:103]
	v_exp_f32_e32 v28, v28
	v_mfma_f32_16x16x32_bf16 v[116:119], v[244:247], v[20:23], v[116:119]
	v_exp_f32_e32 v29, v29
	ds_read_b128 v[244:247], v210 offset:4096
	s_waitcnt lgkmcnt(2)
	v_mfma_f32_16x16x32_bf16 v[104:107], v[236:239], v[0:3], v[204:207]
	v_exp_f32_e32 v30, v30
	v_mfma_f32_16x16x32_bf16 v[120:123], v[236:239], v[12:15], v[252:255]
	v_exp_f32_e32 v31, v31
	ds_read_b128 v[236:239], v199 offset:8192
	s_waitcnt lgkmcnt(2)
	v_mfma_f32_16x16x32_bf16 v[104:107], v[240:243], v[4:7], v[104:107]
	v_exp_f32_e32 v32, v32
	v_mfma_f32_16x16x32_bf16 v[120:123], v[240:243], v[16:19], v[120:123]
	v_exp_f32_e32 v33, v33
	ds_read_b128 v[240:243], v201 offset:8192
	s_waitcnt lgkmcnt(2)
	v_mfma_f32_16x16x32_bf16 v[104:107], v[244:247], v[8:11], v[104:107]
	v_exp_f32_e32 v34, v34
	v_mfma_f32_16x16x32_bf16 v[120:123], v[244:247], v[20:23], v[120:123]
	v_exp_f32_e32 v35, v35
	ds_read_b128 v[244:247], v210 offset:8192
	s_waitcnt lgkmcnt(2)
	v_mfma_f32_16x16x32_bf16 v[108:111], v[236:239], v[0:3], v[204:207]
	v_exp_f32_e32 v36, v36
	v_mfma_f32_16x16x32_bf16 v[124:127], v[236:239], v[12:15], v[252:255]
	v_exp_f32_e32 v37, v37
	ds_read_b128 v[236:239], v199 offset:12288
	s_waitcnt lgkmcnt(2)
	v_mfma_f32_16x16x32_bf16 v[108:111], v[240:243], v[4:7], v[108:111]
	v_exp_f32_e32 v38, v38
	v_mfma_f32_16x16x32_bf16 v[124:127], v[240:243], v[16:19], v[124:127]
	v_exp_f32_e32 v39, v39
	ds_read_b128 v[240:243], v201 offset:12288
	s_waitcnt lgkmcnt(2)
	v_mfma_f32_16x16x32_bf16 v[108:111], v[244:247], v[8:11], v[108:111]
	v_cvt_pk_bf16_f32 v132, v24, v25
	v_cvt_pk_bf16_f32 v133, v26, v27
	v_mfma_f32_16x16x32_bf16 v[124:127], v[244:247], v[20:23], v[124:127]
	v_cvt_pk_bf16_f32 v134, v28, v29
	v_cvt_pk_bf16_f32 v135, v30, v31
	ds_read_b128 v[244:247], v210 offset:12288
	s_waitcnt lgkmcnt(2)
	v_mfma_f32_16x16x32_bf16 v[112:115], v[236:239], v[0:3], v[204:207]
	v_cvt_pk_bf16_f32 v136, v32, v33
	v_cvt_pk_bf16_f32 v137, v34, v35
	v_mfma_f32_16x16x32_bf16 v[128:131], v[236:239], v[12:15], v[252:255]
	v_cvt_pk_bf16_f32 v138, v36, v37
	v_cvt_pk_bf16_f32 v139, v38, v39
	ds_read_b64_tr_b16 v[236:237], v203 offset:43072
	ds_read_b64_tr_b16 v[238:239], v203 offset:45632
	s_waitcnt lgkmcnt(3)
	v_mfma_f32_16x16x32_bf16 v[112:115], v[240:243], v[4:7], v[112:115]
	v_exp_f32_e32 v40, v40
	v_mfma_f32_16x16x32_bf16 v[128:131], v[240:243], v[16:19], v[128:131]
	v_exp_f32_e32 v41, v41
	ds_read_b64_tr_b16 v[240:241], v203 offset:48192
	ds_read_b64_tr_b16 v[242:243], v203 offset:50752
	s_waitcnt lgkmcnt(4)
	v_mfma_f32_16x16x32_bf16 v[112:115], v[244:247], v[8:11], v[112:115]
	v_exp_f32_e32 v42, v42
	v_mfma_f32_16x16x32_bf16 v[128:131], v[244:247], v[20:23], v[128:131]
	v_exp_f32_e32 v43, v43
	ds_read_b64_tr_b16 v[244:245], v203 offset:43104
	ds_read_b64_tr_b16 v[246:247], v203 offset:45664
	v_exp_f32_e32 v44, v44
	v_exp_f32_e32 v45, v45
	v_exp_f32_e32 v46, v46
	v_exp_f32_e32 v47, v47
	v_exp_f32_e32 v212, v212
	v_exp_f32_e32 v213, v213
	v_exp_f32_e32 v214, v214
	v_exp_f32_e32 v215, v215
	v_exp_f32_e32 v216, v216
	v_exp_f32_e32 v217, v217
	v_exp_f32_e32 v218, v218
	v_exp_f32_e32 v219, v219
	v_cvt_pk_bf16_f32 v140, v40, v41
	v_cvt_pk_bf16_f32 v141, v42, v43
	v_cvt_pk_bf16_f32 v142, v44, v45
	v_cvt_pk_bf16_f32 v143, v46, v47
	v_cvt_pk_bf16_f32 v52, v212, v213
	v_cvt_pk_bf16_f32 v53, v214, v215
	v_cvt_pk_bf16_f32 v54, v216, v217
	v_cvt_pk_bf16_f32 v55, v218, v219
	s_waitcnt lgkmcnt(15)
	v_mfma_f32_16x16x32_bf16 v[96:99], v[220:223], v[132:135], v[96:99]
	v_add_f32_e32 v24, v24, v25
	v_add_f32_e32 v26, v26, v27
	v_mfma_f32_16x16x32_bf16 v[84:87], v[220:223], v[140:143], v[84:87]
	v_add_f32_e32 v28, v28, v29
	v_add_f32_e32 v30, v30, v31
	v_mfma_f32_16x16x32_bf16 v[96:99], v[224:227], v[136:139], v[96:99]
	v_add_f32_e32 v32, v32, v33
	v_add_f32_e32 v34, v34, v35
	v_mfma_f32_16x16x32_bf16 v[84:87], v[224:227], v[52:55], v[84:87]
	v_add_f32_e32 v36, v36, v37
	v_add_f32_e32 v38, v38, v39
	ds_read_b64_tr_b16 v[220:221], v203 offset:48224
	ds_read_b64_tr_b16 v[222:223], v203 offset:50784
	v_mfma_f32_16x16x32_bf16 v[88:91], v[228:231], v[132:135], v[88:91]
	v_add_f32_e32 v24, v24, v26
	v_add_f32_e32 v28, v28, v30
	v_mfma_f32_16x16x32_bf16 v[76:79], v[228:231], v[140:143], v[76:79]
	v_add_f32_e32 v32, v32, v34
	v_add_f32_e32 v36, v36, v38
	v_mfma_f32_16x16x32_bf16 v[88:91], v[232:235], v[136:139], v[88:91]
	v_add_f32_e32 v24, v24, v28
	v_add_f32_e32 v32, v32, v36
	v_mfma_f32_16x16x32_bf16 v[76:79], v[232:235], v[52:55], v[76:79]
	v_add_f32_e32 v24, v24, v32
	v_add_f32_e32 v165, v165, v24
	s_waitcnt lgkmcnt(0)
	v_mfma_f32_16x16x32_bf16 v[92:95], v[236:239], v[132:135], v[92:95]
	v_add_f32_e32 v40, v40, v41
	v_add_f32_e32 v42, v42, v43
	v_mfma_f32_16x16x32_bf16 v[80:83], v[236:239], v[140:143], v[80:83]
	v_add_f32_e32 v44, v44, v45
	v_add_f32_e32 v46, v46, v47
	v_mfma_f32_16x16x32_bf16 v[92:95], v[240:243], v[136:139], v[92:95]
	v_add_f32_e32 v212, v212, v213
	v_add_f32_e32 v214, v214, v215
	v_mfma_f32_16x16x32_bf16 v[80:83], v[240:243], v[52:55], v[80:83]
	v_add_f32_e32 v216, v216, v217
	v_add_f32_e32 v218, v218, v219
	v_mfma_f32_16x16x32_bf16 v[48:51], v[244:247], v[132:135], v[48:51]
	v_add_f32_e32 v40, v40, v42
	v_add_f32_e32 v44, v44, v46
	v_mfma_f32_16x16x32_bf16 v[56:59], v[244:247], v[140:143], v[56:59]
	v_add_f32_e32 v212, v212, v214
	v_add_f32_e32 v216, v216, v218
	v_mfma_f32_16x16x32_bf16 v[48:51], v[220:223], v[136:139], v[48:51]
	v_add_f32_e32 v40, v40, v44
	v_add_f32_e32 v212, v212, v216
	v_mfma_f32_16x16x32_bf16 v[56:59], v[220:223], v[52:55], v[56:59]
	v_add_f32_e32 v40, v40, v212
	v_add_f32_e32 v164, v164, v40
	s_add_i32 s32, s49, 1
	s_cmp_eq_u32 s32, s9
	s_cbranch_scc1 .Lmla_mask5

; #define PG8_STAGE(bufoff, gbase, voff) do { _Pragma("unroll") for (int _i = 0; _i < 2; ++_i) \
;         __builtin_amdgcn_global_load_lds((const unsigned*)((const char*)(gbase) + (voff)[_i]), (PG8_LAS unsigned*)(lds + (bufoff) + ldsw + _i * 8192), 16, 0, 0); } while (0)
; #define PG8_LDA(dst, b, h) do { _Pragma("unroll") for (int m = 0; m < 4; ++m) _Pragma("unroll") for (int k = 0; k < 2; ++k) dst[m][k] = *(const PG8_LAS bf16x8*)(lds + PG8_SA(b, h) + aoff + m * 2048 + k * 1024); } while (0)
; #define PG8_LDB(dst, b, h) do { _Pragma("unroll") for (int n = 0; n < 2; ++n) _Pragma("unroll") for (int k = 0; k < 2; ++k) dst[n][k] = *(const PG8_LAS bf16x8*)(lds + PG8_SB(b, h) + boff + n * 2048 + k * 1024); } while (0)
; #define PG8_MMA(ai, bj, At, Bt) do { __builtin_amdgcn_s_setprio(1); _Pragma("unroll") for (int m = 0; m < 4; ++m) _Pragma("unroll") for (int n = 0; n < 2; ++n) _Pragma("unroll") for (int k = 0; k < 2; ++k) \
;         acc[ai][bj][m][n] = __builtin_amdgcn_mfma_f32_16x16x32_bf16(Bt[n][k], At[m][k], acc[ai][bj][m][n], 0, 0, 0); __builtin_amdgcn_s_setprio(0); } while (0)
; #define PG8_WAIT_V(n) asm volatile("s_waitcnt vmcnt(" #n ")" ::: "memory")
; #define PG8_WAIT_L(n) asm volatile("s_waitcnt lgkmcnt(" #n ")" ::: "memory")
; #define PG8_BAR __builtin_amdgcn_s_barrier()
; #define PG8_SCHED __builtin_amdgcn_sched_barrier(0)
; template <class Epi, class Sched, bool ALIGN_EPI = false, bool SP2 = false>
; __device__ __forceinline__ void gemm_phase(PG8_LAS unsigned char* lds, const Gemm g, const Sched& S, const Epi& E) {
;     ...
;         for (int t = 0; t < nt; t += 2) {
;             const bool last = (t == nt - 2);
;             const char* a1 = cA + (size_t)(t + 1) * kstep;
;             const char* a2 = last ? nA : cA + (size_t)(t + 2) * kstep; const char* b2 = last ? nB : cB + (size_t)(t + 2) * kstep;
;             const char* a3 = a2 + kstep; const char* b3 = b2 + kstep;
;             if (last && has_next) S.a_ready(nxt);
;             if constexpr (SP2) {
;             PG8_LDB(B0, 0, 0); PG8_LDB(B1, 0, 1); PG8_SCHED; PG8_LDA(At, 0, 0); PG8_STAGE(PG8_SA(1, 1), a1 + hstep, voffA);
;             PG8_WAIT_V(8); PG8_WAIT_L(0); PG8_BAR; PG8_MMA(0, 0, At, B0); PG8_MMA(0, 1, At, B1); PG8_BAR; PG8_SCHED;
;             PG8_LDA(At, 0, 1); PG8_STAGE(PG8_SB(0, 0), b2, voffB); PG8_STAGE(PG8_SB(0, 1), b2 + hstep, voffB); PG8_STAGE(PG8_SA(0, 0), a2, voffA);
.LBB0_1295:
	v_add_u32_e32 v5, s62, v152
	ds_read_b128 v[154:157], v5
	ds_read_b128 v[158:161], v5 offset:1024
	ds_read_b128 v[162:165], v5 offset:2048
	ds_read_b128 v[166:169], v5 offset:3072
	v_add_u32_e32 v5, s63, v152
	ds_read_b128 v[170:173], v5
	ds_read_b128 v[180:183], v5 offset:1024
	ds_read_b128 v[184:187], v5 offset:2048
	ds_read_b128 v[188:191], v5 offset:3072
	s_add_i32 s70, s44, 2
	s_add_u32 s71, s42, 0x80
	s_addc_u32 s45, s43, 0
	s_cmp_eq_u32 s61, s44
	s_cselect_b32 s44, s10, s71
	s_cselect_b32 s45, s11, s45
	s_cselect_b32 s73, s41, s69
	s_cselect_b32 s72, s40, s68
	v_lshl_add_u64 v[6:7], s[42:43], 0, v[146:147]
	s_add_i32 m0, s53, 0xc000
	ds_read_b128 v[192:195], v153
	ds_read_b128 v[196:199], v153 offset:1024
	ds_read_b128 v[200:203], v153 offset:2048
	ds_read_b128 v[204:207], v153 offset:3072
	ds_read_b128 v[208:211], v153 offset:4096
	ds_read_b128 v[212:215], v153 offset:5120
	ds_read_b128 v[216:219], v153 offset:6144
	ds_read_b128 v[220:223], v153 offset:7168
	global_load_lds_dwordx4 v[6:7], off
	v_lshl_add_u64 v[6:7], s[42:43], 0, v[142:143]
	s_add_i32 m0, s53, 0xe000
	s_nop 0
	global_load_lds_dwordx4 v[6:7], off
	s_waitcnt vmcnt(8)
	s_waitcnt lgkmcnt(0)
	s_barrier
	s_setprio 1
	s_waitcnt lgkmcnt(0)
	v_mfma_f32_16x16x32_bf16 v[92:95], v[154:157], v[192:195], v[92:95]
	v_mfma_f32_16x16x32_bf16 v[64:67], v[162:165], v[192:195], v[64:67]
	v_mfma_f32_16x16x32_bf16 v[100:103], v[154:157], v[200:203], v[100:103]
	v_mfma_f32_16x16x32_bf16 v[68:71], v[162:165], v[200:203], v[68:71]
	v_mfma_f32_16x16x32_bf16 v[104:107], v[154:157], v[208:211], v[104:107]
	v_mfma_f32_16x16x32_bf16 v[72:75], v[162:165], v[208:211], v[72:75]
	v_mfma_f32_16x16x32_bf16 v[112:115], v[154:157], v[216:219], v[112:115]
	v_mfma_f32_16x16x32_bf16 v[80:83], v[162:165], v[216:219], v[80:83]
	v_mfma_f32_16x16x32_bf16 v[92:95], v[158:161], v[196:199], v[92:95]
	v_mfma_f32_16x16x32_bf16 v[64:67], v[166:169], v[196:199], v[64:67]
	v_mfma_f32_16x16x32_bf16 v[100:103], v[158:161], v[204:207], v[100:103]
	v_mfma_f32_16x16x32_bf16 v[68:71], v[166:169], v[204:207], v[68:71]
	v_mfma_f32_16x16x32_bf16 v[104:107], v[158:161], v[212:215], v[104:107]
	v_mfma_f32_16x16x32_bf16 v[72:75], v[166:169], v[212:215], v[72:75]
	v_mfma_f32_16x16x32_bf16 v[112:115], v[158:161], v[220:223], v[112:115]
	v_mfma_f32_16x16x32_bf16 v[80:83], v[166:169], v[220:223], v[80:83]
	s_setprio 0
	s_setprio 1
	v_mfma_f32_16x16x32_bf16 v[32:35], v[170:173], v[192:195], v[32:35]
	v_mfma_f32_16x16x32_bf16 v[132:135], v[184:187], v[192:195], v[132:135]
	v_mfma_f32_16x16x32_bf16 v[36:39], v[170:173], v[200:203], v[36:39]
	v_mfma_f32_16x16x32_bf16 v[6:9], v[184:187], v[200:203], v[8:11]
	v_mfma_f32_16x16x32_bf16 v[40:43], v[170:173], v[208:211], v[40:43]
	v_mfma_f32_16x16x32_bf16 v[10:13], v[184:187], v[208:211], v[12:15]
	v_mfma_f32_16x16x32_bf16 v[48:51], v[170:173], v[216:219], v[48:51]
	v_mfma_f32_16x16x32_bf16 v[16:19], v[184:187], v[216:219], v[16:19]
	v_mfma_f32_16x16x32_bf16 v[32:35], v[180:183], v[196:199], v[32:35]
	v_mfma_f32_16x16x32_bf16 v[132:135], v[188:191], v[196:199], v[132:135]
	v_mfma_f32_16x16x32_bf16 v[36:39], v[180:183], v[204:207], v[36:39]
	v_mfma_f32_16x16x32_bf16 v[6:9], v[188:191], v[204:207], v[6:9]
	v_mfma_f32_16x16x32_bf16 v[40:43], v[180:183], v[212:215], v[40:43]
	v_mfma_f32_16x16x32_bf16 v[12:15], v[188:191], v[212:215], v[10:13]
	v_mfma_f32_16x16x32_bf16 v[48:51], v[180:183], v[220:223], v[48:51]
	v_mfma_f32_16x16x32_bf16 v[16:19], v[188:191], v[220:223], v[16:19]
	s_setprio 0
	s_barrier
	s_add_i32 s71, s62, s52
	v_lshl_add_u64 v[174:175], s[72:73], 0, v[136:137]
	s_mov_b32 m0, s71
	ds_read_b128 v[192:195], v153 offset:16384
	ds_read_b128 v[196:199], v153 offset:17408
	ds_read_b128 v[200:203], v153 offset:18432
	ds_read_b128 v[204:207], v153 offset:19456
	ds_read_b128 v[208:211], v153 offset:20480
	ds_read_b128 v[212:215], v153 offset:21504
	ds_read_b128 v[216:219], v153 offset:22528
	ds_read_b128 v[220:223], v153 offset:23552
	global_load_lds_dwordx4 v[174:175], off
	s_add_i32 m0, s71, 0x2000
	v_lshl_add_u64 v[224:225], s[72:73], 0, v[140:141]
	s_add_u32 s72, s72, s16
	s_addc_u32 s73, s73, s17
	s_add_i32 s71, s63, s52
	global_load_lds_dwordx4 v[224:225], off
	v_lshl_add_u64 v[226:227], s[72:73], 0, v[136:137]
	s_mov_b32 m0, s71
	v_lshl_add_u64 v[228:229], s[72:73], 0, v[140:141]
	global_load_lds_dwordx4 v[226:227], off
	s_add_i32 m0, s71, 0x2000
	v_lshl_add_u64 v[230:231], s[44:45], 0, v[136:137]
	global_load_lds_dwordx4 v[228:229], off
	s_mov_b32 m0, s53
	v_lshl_add_u64 v[232:233], s[44:45], 0, v[140:141]
	global_load_lds_dwordx4 v[230:231], off
	s_mov_b32 m0, s54
	s_nop 0
	global_load_lds_dwordx4 v[232:233], off
	s_waitcnt vmcnt(8)
	s_waitcnt lgkmcnt(0)
	s_barrier
; #define PG8_STAGE(bufoff, gbase, voff) do { _Pragma("unroll") for (int _i = 0; _i < 2; ++_i) \
;         __builtin_amdgcn_global_load_lds((const unsigned*)((const char*)(gbase) + (voff)[_i]), (PG8_LAS unsigned*)(lds + (bufoff) + ldsw + _i * 8192), 16, 0, 0); } while (0)
; #define PG8_LDA(dst, b, h) do { _Pragma("unroll") for (int m = 0; m < 4; ++m) _Pragma("unroll") for (int k = 0; k < 2; ++k) dst[m][k] = *(const PG8_LAS bf16x8*)(lds + PG8_SA(b, h) + aoff + m * 2048 + k * 1024); } while (0)
; #define PG8_LDB(dst, b, h) do { _Pragma("unroll") for (int n = 0; n < 2; ++n) _Pragma("unroll") for (int k = 0; k < 2; ++k) dst[n][k] = *(const PG8_LAS bf16x8*)(lds + PG8_SB(b, h) + boff + n * 2048 + k * 1024); } while (0)
; #define PG8_MMA(ai, bj, At, Bt) do { __builtin_amdgcn_s_setprio(1); _Pragma("unroll") for (int m = 0; m < 4; ++m) _Pragma("unroll") for (int n = 0; n < 2; ++n) _Pragma("unroll") for (int k = 0; k < 2; ++k) \
;         acc[ai][bj][m][n] = __builtin_amdgcn_mfma_f32_16x16x32_bf16(Bt[n][k], At[m][k], acc[ai][bj][m][n], 0, 0, 0); __builtin_amdgcn_s_setprio(0); } while (0)
; #define PG8_WAIT_V(n) asm volatile("s_waitcnt vmcnt(" #n ")" ::: "memory")
; #define PG8_WAIT_L(n) asm volatile("s_waitcnt lgkmcnt(" #n ")" ::: "memory")
; #define PG8_BAR __builtin_amdgcn_s_barrier()
; #define PG8_SCHED __builtin_amdgcn_sched_barrier(0)
; template <class Epi, class Sched, bool ALIGN_EPI = false, bool SP2 = false>
; __device__ __forceinline__ void gemm_phase(PG8_LAS unsigned char* lds, const Gemm g, const Sched& S, const Epi& E) {
;     ...
;             PG8_WAIT_V(8); PG8_WAIT_L(0); PG8_BAR; PG8_MMA(1, 0, At, B0); PG8_MMA(1, 1, At, B1); PG8_BAR; PG8_SCHED;
;             PG8_LDB(B0, 1, 0); PG8_LDB(B1, 1, 1); PG8_SCHED; PG8_LDA(At, 1, 0); PG8_STAGE(PG8_SA(0, 1), a2 + hstep, voffA);
;             PG8_WAIT_V(8); PG8_WAIT_L(0); PG8_BAR; PG8_MMA(0, 0, At, B0); PG8_MMA(0, 1, At, B1); PG8_BAR; PG8_SCHED;
	s_setprio 1
	s_waitcnt lgkmcnt(0)
	v_mfma_f32_16x16x32_bf16 v[116:119], v[154:157], v[192:195], v[116:119]
	v_mfma_f32_16x16x32_bf16 v[84:87], v[162:165], v[192:195], v[84:87]
	v_mfma_f32_16x16x32_bf16 v[120:123], v[154:157], v[200:203], v[120:123]
	v_mfma_f32_16x16x32_bf16 v[88:91], v[162:165], v[200:203], v[88:91]
	v_mfma_f32_16x16x32_bf16 v[124:127], v[154:157], v[208:211], v[124:127]
	v_mfma_f32_16x16x32_bf16 v[96:99], v[162:165], v[208:211], v[96:99]
	v_mfma_f32_16x16x32_bf16 v[128:131], v[154:157], v[216:219], v[128:131]
	v_mfma_f32_16x16x32_bf16 v[108:111], v[162:165], v[216:219], v[108:111]
	v_mfma_f32_16x16x32_bf16 v[116:119], v[158:161], v[196:199], v[116:119]
	v_mfma_f32_16x16x32_bf16 v[84:87], v[166:169], v[196:199], v[84:87]
	v_mfma_f32_16x16x32_bf16 v[120:123], v[158:161], v[204:207], v[120:123]
	v_mfma_f32_16x16x32_bf16 v[88:91], v[166:169], v[204:207], v[88:91]
	v_mfma_f32_16x16x32_bf16 v[124:127], v[158:161], v[212:215], v[124:127]
	v_mfma_f32_16x16x32_bf16 v[96:99], v[166:169], v[212:215], v[96:99]
	v_mfma_f32_16x16x32_bf16 v[128:131], v[158:161], v[220:223], v[128:131]
	v_mfma_f32_16x16x32_bf16 v[108:111], v[166:169], v[220:223], v[108:111]
	s_setprio 0
	s_setprio 1
	v_mfma_f32_16x16x32_bf16 v[52:55], v[170:173], v[192:195], v[52:55]
	v_mfma_f32_16x16x32_bf16 v[20:23], v[184:187], v[192:195], v[20:23]
	v_mfma_f32_16x16x32_bf16 v[56:59], v[170:173], v[200:203], v[56:59]
	v_mfma_f32_16x16x32_bf16 v[24:27], v[184:187], v[200:203], v[24:27]
	v_mfma_f32_16x16x32_bf16 v[60:63], v[170:173], v[208:211], v[60:63]
	v_mfma_f32_16x16x32_bf16 v[28:31], v[184:187], v[208:211], v[28:31]
	v_mfma_f32_16x16x32_bf16 v[76:79], v[170:173], v[216:219], v[76:79]
	v_mfma_f32_16x16x32_bf16 v[44:47], v[184:187], v[216:219], v[44:47]
	v_mfma_f32_16x16x32_bf16 v[52:55], v[180:183], v[196:199], v[52:55]
	v_mfma_f32_16x16x32_bf16 v[20:23], v[188:191], v[196:199], v[20:23]
	v_mfma_f32_16x16x32_bf16 v[56:59], v[180:183], v[204:207], v[56:59]
	v_mfma_f32_16x16x32_bf16 v[24:27], v[188:191], v[204:207], v[24:27]
	v_mfma_f32_16x16x32_bf16 v[60:63], v[180:183], v[212:215], v[60:63]
	v_mfma_f32_16x16x32_bf16 v[28:31], v[188:191], v[212:215], v[28:31]
	v_mfma_f32_16x16x32_bf16 v[76:79], v[180:183], v[220:223], v[76:79]
	v_mfma_f32_16x16x32_bf16 v[44:47], v[188:191], v[220:223], v[44:47]
	s_setprio 0
	s_barrier
	s_add_i32 s71, 0, 0x18000
	v_add_u32_e32 v5, s71, v152
	s_add_i32 s72, 0, 0x1c000
	ds_read_b128 v[154:157], v5
	ds_read_b128 v[158:161], v5 offset:1024
	ds_read_b128 v[162:165], v5 offset:2048
	ds_read_b128 v[166:169], v5 offset:3072
	v_add_u32_e32 v5, s72, v152
	ds_read_b128 v[170:173], v5
	ds_read_b128 v[180:183], v5 offset:1024
	ds_read_b128 v[184:187], v5 offset:2048
	ds_read_b128 v[188:191], v5 offset:3072
	s_add_u32 s44, s44, s16
	s_addc_u32 s45, s45, s17
	s_mov_b32 m0, s55
	v_lshl_add_u64 v[10:11], s[44:45], 0, v[136:137]
	ds_read_b128 v[192:195], v153 offset:32768
	ds_read_b128 v[196:199], v153 offset:33792
	ds_read_b128 v[200:203], v153 offset:34816
	ds_read_b128 v[204:207], v153 offset:35840
	ds_read_b128 v[208:211], v153 offset:36864
	ds_read_b128 v[212:215], v153 offset:37888
	ds_read_b128 v[216:219], v153 offset:38912
	ds_read_b128 v[220:223], v153 offset:39936
	global_load_lds_dwordx4 v[10:11], off
	v_lshl_add_u64 v[10:11], s[44:45], 0, v[140:141]
	s_mov_b32 m0, s56
	s_nop 0
	global_load_lds_dwordx4 v[10:11], off
	s_waitcnt vmcnt(8)
	s_waitcnt lgkmcnt(0)
	s_barrier
	s_setprio 1
	s_waitcnt lgkmcnt(0)
	v_mfma_f32_16x16x32_bf16 v[92:95], v[154:157], v[192:195], v[92:95]
	v_mfma_f32_16x16x32_bf16 v[64:67], v[162:165], v[192:195], v[64:67]
	v_mfma_f32_16x16x32_bf16 v[100:103], v[154:157], v[200:203], v[100:103]
	v_mfma_f32_16x16x32_bf16 v[68:71], v[162:165], v[200:203], v[68:71]
	v_mfma_f32_16x16x32_bf16 v[104:107], v[154:157], v[208:211], v[104:107]
	v_mfma_f32_16x16x32_bf16 v[72:75], v[162:165], v[208:211], v[72:75]
	v_mfma_f32_16x16x32_bf16 v[112:115], v[154:157], v[216:219], v[112:115]
	v_mfma_f32_16x16x32_bf16 v[80:83], v[162:165], v[216:219], v[80:83]
	v_mfma_f32_16x16x32_bf16 v[92:95], v[158:161], v[196:199], v[92:95]
	v_mfma_f32_16x16x32_bf16 v[64:67], v[166:169], v[196:199], v[64:67]
	v_mfma_f32_16x16x32_bf16 v[100:103], v[158:161], v[204:207], v[100:103]
	v_mfma_f32_16x16x32_bf16 v[68:71], v[166:169], v[204:207], v[68:71]
	v_mfma_f32_16x16x32_bf16 v[104:107], v[158:161], v[212:215], v[104:107]
	v_mfma_f32_16x16x32_bf16 v[72:75], v[166:169], v[212:215], v[72:75]
	v_mfma_f32_16x16x32_bf16 v[112:115], v[158:161], v[220:223], v[112:115]
	v_mfma_f32_16x16x32_bf16 v[80:83], v[166:169], v[220:223], v[80:83]
	s_setprio 0
	s_setprio 1
	v_mfma_f32_16x16x32_bf16 v[32:35], v[170:173], v[192:195], v[32:35]
	v_mfma_f32_16x16x32_bf16 v[132:135], v[184:187], v[192:195], v[132:135]
	v_mfma_f32_16x16x32_bf16 v[36:39], v[170:173], v[200:203], v[36:39]
	v_mfma_f32_16x16x32_bf16 v[6:9], v[184:187], v[200:203], v[6:9]
	v_mfma_f32_16x16x32_bf16 v[40:43], v[170:173], v[208:211], v[40:43]
	v_mfma_f32_16x16x32_bf16 v[12:15], v[184:187], v[208:211], v[12:15]
	v_mfma_f32_16x16x32_bf16 v[48:51], v[170:173], v[216:219], v[48:51]
	v_mfma_f32_16x16x32_bf16 v[16:19], v[184:187], v[216:219], v[16:19]
	v_mfma_f32_16x16x32_bf16 v[32:35], v[180:183], v[196:199], v[32:35]
	v_mfma_f32_16x16x32_bf16 v[132:135], v[188:191], v[196:199], v[132:135]
	v_mfma_f32_16x16x32_bf16 v[36:39], v[180:183], v[204:207], v[36:39]
	v_mfma_f32_16x16x32_bf16 v[8:11], v[188:191], v[204:207], v[6:9]
	v_mfma_f32_16x16x32_bf16 v[40:43], v[180:183], v[212:215], v[40:43]
	v_mfma_f32_16x16x32_bf16 v[12:15], v[188:191], v[212:215], v[12:15]
	v_mfma_f32_16x16x32_bf16 v[48:51], v[180:183], v[220:223], v[48:51]
	v_mfma_f32_16x16x32_bf16 v[16:19], v[188:191], v[220:223], v[16:19]
	s_setprio 0
	s_barrier
; #define PG8_STAGE(bufoff, gbase, voff) do { _Pragma("unroll") for (int _i = 0; _i < 2; ++_i) \
;         __builtin_amdgcn_global_load_lds((const unsigned*)((const char*)(gbase) + (voff)[_i]), (PG8_LAS unsigned*)(lds + (bufoff) + ldsw + _i * 8192), 16, 0, 0); } while (0)
; #define PG8_LDA(dst, b, h) do { _Pragma("unroll") for (int m = 0; m < 4; ++m) _Pragma("unroll") for (int k = 0; k < 2; ++k) dst[m][k] = *(const PG8_LAS bf16x8*)(lds + PG8_SA(b, h) + aoff + m * 2048 + k * 1024); } while (0)
; #define PG8_MMA(ai, bj, At, Bt) do { __builtin_amdgcn_s_setprio(1); _Pragma("unroll") for (int m = 0; m < 4; ++m) _Pragma("unroll") for (int n = 0; n < 2; ++n) _Pragma("unroll") for (int k = 0; k < 2; ++k) \
;         acc[ai][bj][m][n] = __builtin_amdgcn_mfma_f32_16x16x32_bf16(Bt[n][k], At[m][k], acc[ai][bj][m][n], 0, 0, 0); __builtin_amdgcn_s_setprio(0); } while (0)
; #define PG8_WAIT_V(n) asm volatile("s_waitcnt vmcnt(" #n ")" ::: "memory")
; #define PG8_WAIT_L(n) asm volatile("s_waitcnt lgkmcnt(" #n ")" ::: "memory")
; #define PG8_BAR __builtin_amdgcn_s_barrier()
; #define PG8_SCHED __builtin_amdgcn_sched_barrier(0)
; template <class Epi, class Sched, bool ALIGN_EPI = false, bool SP2 = false>
; __device__ __forceinline__ void gemm_phase(PG8_LAS unsigned char* lds, const Gemm g, const Sched& S, const Epi& E) {
;     ...
;             PG8_LDA(At, 1, 1); PG8_STAGE(PG8_SB(1, 0), b3, voffB); PG8_STAGE(PG8_SB(1, 1), b3 + hstep, voffB); PG8_STAGE(PG8_SA(1, 0), a3, voffA);
;             PG8_WAIT_V(8); PG8_WAIT_L(0); PG8_BAR; PG8_MMA(1, 0, At, B0); PG8_MMA(1, 1, At, B1); PG8_BAR; PG8_SCHED;
	s_add_i32 s44, s71, s52
	v_lshl_add_u64 v[6:7], v[174:175], 0, s[36:37]
	s_mov_b32 m0, s44
	ds_read_b128 v[192:195], v153 offset:49152
	ds_read_b128 v[196:199], v153 offset:50176
	ds_read_b128 v[200:203], v153 offset:51200
	ds_read_b128 v[204:207], v153 offset:52224
	ds_read_b128 v[208:211], v153 offset:53248
	ds_read_b128 v[212:215], v153 offset:54272
	ds_read_b128 v[216:219], v153 offset:55296
	ds_read_b128 v[220:223], v153 offset:56320
	global_load_lds_dwordx4 v[6:7], off
	v_lshl_add_u64 v[6:7], v[224:225], 0, s[36:37]
	s_add_i32 m0, s44, 0x2000
	s_add_i32 s44, s72, s52
	global_load_lds_dwordx4 v[6:7], off
	v_lshl_add_u64 v[6:7], v[226:227], 0, s[36:37]
	s_mov_b32 m0, s44
	s_nop 0
	global_load_lds_dwordx4 v[6:7], off
	v_lshl_add_u64 v[6:7], v[228:229], 0, s[36:37]
	s_add_i32 m0, s44, 0x2000
	s_nop 0
	global_load_lds_dwordx4 v[6:7], off
	v_lshl_add_u64 v[6:7], v[230:231], 0, s[36:37]
	s_mov_b32 m0, s58
	s_nop 0
	global_load_lds_dwordx4 v[6:7], off
	v_lshl_add_u64 v[6:7], v[232:233], 0, s[36:37]
	s_mov_b32 m0, s59
	s_nop 0
	global_load_lds_dwordx4 v[6:7], off
	s_waitcnt vmcnt(8)
	s_waitcnt lgkmcnt(0)
	s_barrier
	s_setprio 1
	s_waitcnt lgkmcnt(0)
	v_mfma_f32_16x16x32_bf16 v[116:119], v[154:157], v[192:195], v[116:119]
	v_mfma_f32_16x16x32_bf16 v[84:87], v[162:165], v[192:195], v[84:87]
	v_mfma_f32_16x16x32_bf16 v[120:123], v[154:157], v[200:203], v[120:123]
	v_mfma_f32_16x16x32_bf16 v[88:91], v[162:165], v[200:203], v[88:91]
	v_mfma_f32_16x16x32_bf16 v[124:127], v[154:157], v[208:211], v[124:127]
	v_mfma_f32_16x16x32_bf16 v[96:99], v[162:165], v[208:211], v[96:99]
	v_mfma_f32_16x16x32_bf16 v[128:131], v[154:157], v[216:219], v[128:131]
	v_mfma_f32_16x16x32_bf16 v[108:111], v[162:165], v[216:219], v[108:111]
	v_mfma_f32_16x16x32_bf16 v[116:119], v[158:161], v[196:199], v[116:119]
	v_mfma_f32_16x16x32_bf16 v[84:87], v[166:169], v[196:199], v[84:87]
	v_mfma_f32_16x16x32_bf16 v[120:123], v[158:161], v[204:207], v[120:123]
	v_mfma_f32_16x16x32_bf16 v[88:91], v[166:169], v[204:207], v[88:91]
	v_mfma_f32_16x16x32_bf16 v[124:127], v[158:161], v[212:215], v[124:127]
	v_mfma_f32_16x16x32_bf16 v[96:99], v[166:169], v[212:215], v[96:99]
	v_mfma_f32_16x16x32_bf16 v[128:131], v[158:161], v[220:223], v[128:131]
	v_mfma_f32_16x16x32_bf16 v[108:111], v[166:169], v[220:223], v[108:111]
	s_setprio 0
	s_setprio 1
	v_mfma_f32_16x16x32_bf16 v[52:55], v[170:173], v[192:195], v[52:55]
	v_mfma_f32_16x16x32_bf16 v[20:23], v[184:187], v[192:195], v[20:23]
	v_mfma_f32_16x16x32_bf16 v[56:59], v[170:173], v[200:203], v[56:59]
	v_mfma_f32_16x16x32_bf16 v[24:27], v[184:187], v[200:203], v[24:27]
	v_mfma_f32_16x16x32_bf16 v[60:63], v[170:173], v[208:211], v[60:63]
	v_mfma_f32_16x16x32_bf16 v[28:31], v[184:187], v[208:211], v[28:31]
	v_mfma_f32_16x16x32_bf16 v[76:79], v[170:173], v[216:219], v[76:79]
	v_mfma_f32_16x16x32_bf16 v[44:47], v[184:187], v[216:219], v[44:47]
	v_mfma_f32_16x16x32_bf16 v[52:55], v[180:183], v[196:199], v[52:55]
	v_mfma_f32_16x16x32_bf16 v[20:23], v[188:191], v[196:199], v[20:23]
	v_mfma_f32_16x16x32_bf16 v[56:59], v[180:183], v[204:207], v[56:59]
	v_mfma_f32_16x16x32_bf16 v[24:27], v[188:191], v[204:207], v[24:27]
	v_mfma_f32_16x16x32_bf16 v[60:63], v[180:183], v[212:215], v[60:63]
	v_mfma_f32_16x16x32_bf16 v[28:31], v[188:191], v[212:215], v[28:31]
	v_mfma_f32_16x16x32_bf16 v[76:79], v[180:183], v[220:223], v[76:79]
	v_mfma_f32_16x16x32_bf16 v[44:47], v[188:191], v[220:223], v[44:47]
	s_setprio 0
	s_add_u32 s68, s68, 0x100
	s_addc_u32 s69, s69, 0
	s_add_u32 s42, s42, 0x100
	s_addc_u32 s43, s43, 0
	s_cmp_ge_i32 s70, s60
	s_mov_b32 s44, s70
	s_barrier
	s_cbranch_scc0 .LBB0_1295

; #define PG8_STAGE(bufoff, gbase, voff) do { _Pragma("unroll") for (int _i = 0; _i < 2; ++_i) \
;         __builtin_amdgcn_global_load_lds((const unsigned*)((const char*)(gbase) + (voff)[_i]), (PG8_LAS unsigned*)(lds + (bufoff) + ldsw + _i * 8192), 16, 0, 0); } while (0)
; #define PG8_LDA(dst, b, h) do { _Pragma("unroll") for (int m = 0; m < 4; ++m) _Pragma("unroll") for (int k = 0; k < 2; ++k) dst[m][k] = *(const PG8_LAS bf16x8*)(lds + PG8_SA(b, h) + aoff + m * 2048 + k * 1024); } while (0)
; #define PG8_LDB(dst, b, h) do { _Pragma("unroll") for (int n = 0; n < 2; ++n) _Pragma("unroll") for (int k = 0; k < 2; ++k) dst[n][k] = *(const PG8_LAS bf16x8*)(lds + PG8_SB(b, h) + boff + n * 2048 + k * 1024); } while (0)
; #define PG8_MMA(ai, bj, At, Bt) do { __builtin_amdgcn_s_setprio(1); _Pragma("unroll") for (int m = 0; m < 4; ++m) _Pragma("unroll") for (int n = 0; n < 2; ++n) _Pragma("unroll") for (int k = 0; k < 2; ++k) \
;         acc[ai][bj][m][n] = __builtin_amdgcn_mfma_f32_16x16x32_bf16(Bt[n][k], At[m][k], acc[ai][bj][m][n], 0, 0, 0); __builtin_amdgcn_s_setprio(0); } while (0)
; #define PG8_WAIT_V(n) asm volatile("s_waitcnt vmcnt(" #n ")" ::: "memory")
; #define PG8_WAIT_L(n) asm volatile("s_waitcnt lgkmcnt(" #n ")" ::: "memory")
; #define PG8_BAR __builtin_amdgcn_s_barrier()
; #define PG8_SCHED __builtin_amdgcn_sched_barrier(0)
; template <class Epi, class Sched, bool ALIGN_EPI = false, bool SP2 = false>
; __device__ __forceinline__ void gemm_phase(PG8_LAS unsigned char* lds, const Gemm g, const Sched& S, const Epi& E) {
;     ...
;         for (int t = 0; t < nt; t += 2) {
;             const bool last = (t == nt - 2);
;             const char* a1 = cA + (size_t)(t + 1) * kstep;
;             const char* a2 = last ? nA : cA + (size_t)(t + 2) * kstep; const char* b2 = last ? nB : cB + (size_t)(t + 2) * kstep;
;             const char* a3 = a2 + kstep; const char* b3 = b2 + kstep;
;             if (last && has_next) S.a_ready(nxt);
;             if constexpr (SP2) {
;             PG8_LDB(B0, 0, 0); PG8_LDB(B1, 0, 1); PG8_SCHED; PG8_LDA(At, 0, 0); PG8_STAGE(PG8_SA(1, 1), a1 + hstep, voffA);
;             PG8_WAIT_V(8); PG8_WAIT_L(0); PG8_BAR; PG8_MMA(0, 0, At, B0); PG8_MMA(0, 1, At, B1); PG8_BAR; PG8_SCHED;
;             PG8_LDA(At, 0, 1); PG8_STAGE(PG8_SB(0, 0), b2, voffB); PG8_STAGE(PG8_SB(0, 1), b2 + hstep, voffB); PG8_STAGE(PG8_SA(0, 0), a2, voffA);
.LBB0_1406:
	ds_read_b128 v[154:157], v151
	ds_read_b128 v[158:161], v151 offset:1024
	ds_read_b128 v[162:165], v151 offset:2048
	ds_read_b128 v[166:169], v151 offset:3072
	ds_read_b128 v[170:173], v152
	ds_read_b128 v[174:177], v152 offset:1024
	ds_read_b128 v[178:181], v152 offset:2048
	ds_read_b128 v[182:185], v152 offset:3072
	s_add_i32 s66, s38, 2
	s_add_u32 s67, s36, 0x80
	s_addc_u32 s39, s37, 0
	s_cmp_eq_u32 s54, s38
	s_cselect_b32 s38, s8, s67
	s_cselect_b32 s39, s9, s39
	s_cselect_b32 s69, s35, s65
	s_cselect_b32 s68, s34, s64
	v_lshl_add_u64 v[146:147], s[36:37], 0, v[138:139]
	s_add_i32 m0, s46, 0xc000
	ds_read_b128 v[186:189], v153
	ds_read_b128 v[190:193], v153 offset:1024
	ds_read_b128 v[194:197], v153 offset:2048
	ds_read_b128 v[198:201], v153 offset:3072
	ds_read_b128 v[202:205], v153 offset:4096
	ds_read_b128 v[206:209], v153 offset:5120
	ds_read_b128 v[210:213], v153 offset:6144
	ds_read_b128 v[214:217], v153 offset:7168
	global_load_lds_dwordx4 v[146:147], off
	v_lshl_add_u64 v[146:147], s[36:37], 0, v[136:137]
	s_add_i32 m0, s46, 0xe000
	s_nop 0
	global_load_lds_dwordx4 v[146:147], off
	s_waitcnt vmcnt(8)
	s_waitcnt lgkmcnt(0)
	s_barrier
	s_setprio 1
	s_waitcnt lgkmcnt(0)
	v_mfma_f32_16x16x32_bf16 v[124:127], v[154:157], v[186:189], v[124:127]
	v_mfma_f32_16x16x32_bf16 v[116:119], v[162:165], v[186:189], v[116:119]
	v_mfma_f32_16x16x32_bf16 v[108:111], v[154:157], v[194:197], v[108:111]
	v_mfma_f32_16x16x32_bf16 v[100:103], v[162:165], v[194:197], v[100:103]
	v_mfma_f32_16x16x32_bf16 v[92:95], v[154:157], v[202:205], v[92:95]
	v_mfma_f32_16x16x32_bf16 v[84:87], v[162:165], v[202:205], v[84:87]
	v_mfma_f32_16x16x32_bf16 v[76:79], v[154:157], v[210:213], v[76:79]
	v_mfma_f32_16x16x32_bf16 v[68:71], v[162:165], v[210:213], v[68:71]
	v_mfma_f32_16x16x32_bf16 v[124:127], v[158:161], v[190:193], v[124:127]
	v_mfma_f32_16x16x32_bf16 v[116:119], v[166:169], v[190:193], v[116:119]
	v_mfma_f32_16x16x32_bf16 v[108:111], v[158:161], v[198:201], v[108:111]
	v_mfma_f32_16x16x32_bf16 v[100:103], v[166:169], v[198:201], v[100:103]
	v_mfma_f32_16x16x32_bf16 v[92:95], v[158:161], v[206:209], v[92:95]
	v_mfma_f32_16x16x32_bf16 v[84:87], v[166:169], v[206:209], v[84:87]
	v_mfma_f32_16x16x32_bf16 v[76:79], v[158:161], v[214:217], v[76:79]
	v_mfma_f32_16x16x32_bf16 v[68:71], v[166:169], v[214:217], v[68:71]
	s_setprio 0
	s_setprio 1
	v_mfma_f32_16x16x32_bf16 v[120:123], v[170:173], v[186:189], v[120:123]
	v_mfma_f32_16x16x32_bf16 v[112:115], v[178:181], v[186:189], v[112:115]
	v_mfma_f32_16x16x32_bf16 v[104:107], v[170:173], v[194:197], v[104:107]
	v_mfma_f32_16x16x32_bf16 v[96:99], v[178:181], v[194:197], v[96:99]
	v_mfma_f32_16x16x32_bf16 v[88:91], v[170:173], v[202:205], v[88:91]
	v_mfma_f32_16x16x32_bf16 v[80:83], v[178:181], v[202:205], v[80:83]
	v_mfma_f32_16x16x32_bf16 v[72:75], v[170:173], v[210:213], v[72:75]
	v_mfma_f32_16x16x32_bf16 v[64:67], v[178:181], v[210:213], v[64:67]
	v_mfma_f32_16x16x32_bf16 v[120:123], v[174:177], v[190:193], v[120:123]
	v_mfma_f32_16x16x32_bf16 v[112:115], v[182:185], v[190:193], v[112:115]
	v_mfma_f32_16x16x32_bf16 v[104:107], v[174:177], v[198:201], v[104:107]
	v_mfma_f32_16x16x32_bf16 v[96:99], v[182:185], v[198:201], v[96:99]
	v_mfma_f32_16x16x32_bf16 v[88:91], v[174:177], v[206:209], v[88:91]
	v_mfma_f32_16x16x32_bf16 v[80:83], v[182:185], v[206:209], v[80:83]
	v_mfma_f32_16x16x32_bf16 v[72:75], v[174:177], v[214:217], v[72:75]
	v_mfma_f32_16x16x32_bf16 v[64:67], v[182:185], v[214:217], v[64:67]
	s_setprio 0
	s_barrier
	s_add_i32 s67, s57, s43
	v_lshl_add_u64 v[146:147], s[68:69], 0, v[132:133]
	s_mov_b32 m0, s67
	ds_read_b128 v[186:189], v153 offset:16384
	ds_read_b128 v[190:193], v153 offset:17408
	ds_read_b128 v[194:197], v153 offset:18432
	ds_read_b128 v[198:201], v153 offset:19456
	ds_read_b128 v[202:205], v153 offset:20480
	ds_read_b128 v[206:209], v153 offset:21504
	ds_read_b128 v[210:213], v153 offset:22528
	ds_read_b128 v[214:217], v153 offset:23552
	global_load_lds_dwordx4 v[146:147], off
	s_add_i32 m0, s67, 0x2000
	v_lshl_add_u64 v[218:219], s[68:69], 0, v[128:129]
	s_add_u32 s68, s68, s10
	s_addc_u32 s69, s69, s11
	s_add_i32 s67, s58, s43
	global_load_lds_dwordx4 v[218:219], off
	v_lshl_add_u64 v[220:221], s[68:69], 0, v[132:133]
	s_mov_b32 m0, s67
	v_lshl_add_u64 v[222:223], s[68:69], 0, v[128:129]
	global_load_lds_dwordx4 v[220:221], off
	s_add_i32 m0, s67, 0x2000
	v_lshl_add_u64 v[224:225], s[38:39], 0, v[134:135]
	global_load_lds_dwordx4 v[222:223], off
	s_mov_b32 m0, s46
	v_lshl_add_u64 v[226:227], s[38:39], 0, v[130:131]
	global_load_lds_dwordx4 v[224:225], off
	s_mov_b32 m0, s47
	s_nop 0
	global_load_lds_dwordx4 v[226:227], off
	s_waitcnt vmcnt(8)
	s_waitcnt lgkmcnt(0)
	s_barrier
; #define PG8_STAGE(bufoff, gbase, voff) do { _Pragma("unroll") for (int _i = 0; _i < 2; ++_i) \
;         __builtin_amdgcn_global_load_lds((const unsigned*)((const char*)(gbase) + (voff)[_i]), (PG8_LAS unsigned*)(lds + (bufoff) + ldsw + _i * 8192), 16, 0, 0); } while (0)
; #define PG8_LDA(dst, b, h) do { _Pragma("unroll") for (int m = 0; m < 4; ++m) _Pragma("unroll") for (int k = 0; k < 2; ++k) dst[m][k] = *(const PG8_LAS bf16x8*)(lds + PG8_SA(b, h) + aoff + m * 2048 + k * 1024); } while (0)
; #define PG8_LDB(dst, b, h) do { _Pragma("unroll") for (int n = 0; n < 2; ++n) _Pragma("unroll") for (int k = 0; k < 2; ++k) dst[n][k] = *(const PG8_LAS bf16x8*)(lds + PG8_SB(b, h) + boff + n * 2048 + k * 1024); } while (0)
; #define PG8_MMA(ai, bj, At, Bt) do { __builtin_amdgcn_s_setprio(1); _Pragma("unroll") for (int m = 0; m < 4; ++m) _Pragma("unroll") for (int n = 0; n < 2; ++n) _Pragma("unroll") for (int k = 0; k < 2; ++k) \
;         acc[ai][bj][m][n] = __builtin_amdgcn_mfma_f32_16x16x32_bf16(Bt[n][k], At[m][k], acc[ai][bj][m][n], 0, 0, 0); __builtin_amdgcn_s_setprio(0); } while (0)
; #define PG8_WAIT_V(n) asm volatile("s_waitcnt vmcnt(" #n ")" ::: "memory")
; #define PG8_WAIT_L(n) asm volatile("s_waitcnt lgkmcnt(" #n ")" ::: "memory")
; #define PG8_BAR __builtin_amdgcn_s_barrier()
; #define PG8_SCHED __builtin_amdgcn_sched_barrier(0)
; template <class Epi, class Sched, bool ALIGN_EPI = false, bool SP2 = false>
; __device__ __forceinline__ void gemm_phase(PG8_LAS unsigned char* lds, const Gemm g, const Sched& S, const Epi& E) {
;     ...
;             PG8_WAIT_V(8); PG8_WAIT_L(0); PG8_BAR; PG8_MMA(1, 0, At, B0); PG8_MMA(1, 1, At, B1); PG8_BAR; PG8_SCHED;
;             PG8_LDB(B0, 1, 0); PG8_LDB(B1, 1, 1); PG8_SCHED; PG8_LDA(At, 1, 0); PG8_STAGE(PG8_SA(0, 1), a2 + hstep, voffA);
;             PG8_WAIT_V(8); PG8_WAIT_L(0); PG8_BAR; PG8_MMA(0, 0, At, B0); PG8_MMA(0, 1, At, B1); PG8_BAR; PG8_SCHED;
	s_setprio 1
	s_waitcnt lgkmcnt(0)
	v_mfma_f32_16x16x32_bf16 v[60:63], v[154:157], v[186:189], v[60:63]
	v_mfma_f32_16x16x32_bf16 v[52:55], v[162:165], v[186:189], v[52:55]
	v_mfma_f32_16x16x32_bf16 v[44:47], v[154:157], v[194:197], v[44:47]
	v_mfma_f32_16x16x32_bf16 v[36:39], v[162:165], v[194:197], v[36:39]
	v_mfma_f32_16x16x32_bf16 v[28:31], v[154:157], v[202:205], v[28:31]
	v_mfma_f32_16x16x32_bf16 v[20:23], v[162:165], v[202:205], v[20:23]
	v_mfma_f32_16x16x32_bf16 v[12:15], v[154:157], v[210:213], v[12:15]
	v_mfma_f32_16x16x32_bf16 v[4:7], v[162:165], v[210:213], v[4:7]
	v_mfma_f32_16x16x32_bf16 v[60:63], v[158:161], v[190:193], v[60:63]
	v_mfma_f32_16x16x32_bf16 v[52:55], v[166:169], v[190:193], v[52:55]
	v_mfma_f32_16x16x32_bf16 v[44:47], v[158:161], v[198:201], v[44:47]
	v_mfma_f32_16x16x32_bf16 v[36:39], v[166:169], v[198:201], v[36:39]
	v_mfma_f32_16x16x32_bf16 v[28:31], v[158:161], v[206:209], v[28:31]
	v_mfma_f32_16x16x32_bf16 v[20:23], v[166:169], v[206:209], v[20:23]
	v_mfma_f32_16x16x32_bf16 v[12:15], v[158:161], v[214:217], v[12:15]
	v_mfma_f32_16x16x32_bf16 v[4:7], v[166:169], v[214:217], v[4:7]
	s_setprio 0
	s_setprio 1
	v_mfma_f32_16x16x32_bf16 v[56:59], v[170:173], v[186:189], v[56:59]
	v_mfma_f32_16x16x32_bf16 v[48:51], v[178:181], v[186:189], v[48:51]
	v_mfma_f32_16x16x32_bf16 v[40:43], v[170:173], v[194:197], v[40:43]
	v_mfma_f32_16x16x32_bf16 v[32:35], v[178:181], v[194:197], v[32:35]
	v_mfma_f32_16x16x32_bf16 v[24:27], v[170:173], v[202:205], v[24:27]
	v_mfma_f32_16x16x32_bf16 v[16:19], v[178:181], v[202:205], v[16:19]
	v_mfma_f32_16x16x32_bf16 v[8:11], v[170:173], v[210:213], v[8:11]
	v_mfma_f32_16x16x32_bf16 v[0:3], v[178:181], v[210:213], v[0:3]
	v_mfma_f32_16x16x32_bf16 v[56:59], v[174:177], v[190:193], v[56:59]
	v_mfma_f32_16x16x32_bf16 v[48:51], v[182:185], v[190:193], v[48:51]
	v_mfma_f32_16x16x32_bf16 v[40:43], v[174:177], v[198:201], v[40:43]
	v_mfma_f32_16x16x32_bf16 v[32:35], v[182:185], v[198:201], v[32:35]
	v_mfma_f32_16x16x32_bf16 v[24:27], v[174:177], v[206:209], v[24:27]
	v_mfma_f32_16x16x32_bf16 v[16:19], v[182:185], v[206:209], v[16:19]
	v_mfma_f32_16x16x32_bf16 v[8:11], v[174:177], v[214:217], v[8:11]
	v_mfma_f32_16x16x32_bf16 v[0:3], v[182:185], v[214:217], v[0:3]
	s_setprio 0
	s_barrier
	s_add_i32 s67, 0, 0x18000
	s_add_i32 s68, 0, 0x1c000
	v_add_u32_e32 v166, s67, v149
	v_add_u32_e32 v182, s68, v149
	ds_read_b128 v[154:157], v166
	ds_read_b128 v[158:161], v166 offset:1024
	ds_read_b128 v[162:165], v166 offset:2048
	ds_read_b128 v[166:169], v166 offset:3072
	ds_read_b128 v[170:173], v182
	ds_read_b128 v[174:177], v182 offset:1024
	ds_read_b128 v[178:181], v182 offset:2048
	ds_read_b128 v[182:185], v182 offset:3072
	s_add_u32 s38, s38, s10
	s_addc_u32 s39, s39, s11
	s_mov_b32 m0, s48
	v_lshl_add_u64 v[228:229], s[38:39], 0, v[134:135]
	ds_read_b128 v[186:189], v153 offset:32768
	ds_read_b128 v[190:193], v153 offset:33792
	ds_read_b128 v[194:197], v153 offset:34816
	ds_read_b128 v[198:201], v153 offset:35840
	ds_read_b128 v[202:205], v153 offset:36864
	ds_read_b128 v[206:209], v153 offset:37888
	ds_read_b128 v[210:213], v153 offset:38912
	ds_read_b128 v[214:217], v153 offset:39936
	global_load_lds_dwordx4 v[228:229], off
	v_lshl_add_u64 v[228:229], s[38:39], 0, v[130:131]
	s_mov_b32 m0, s49
	s_nop 0
	global_load_lds_dwordx4 v[228:229], off
	s_waitcnt vmcnt(8)
	s_waitcnt lgkmcnt(0)
	s_barrier
	s_setprio 1
	s_waitcnt lgkmcnt(0)
	v_mfma_f32_16x16x32_bf16 v[124:127], v[154:157], v[186:189], v[124:127]
	v_mfma_f32_16x16x32_bf16 v[116:119], v[162:165], v[186:189], v[116:119]
	v_mfma_f32_16x16x32_bf16 v[108:111], v[154:157], v[194:197], v[108:111]
	v_mfma_f32_16x16x32_bf16 v[100:103], v[162:165], v[194:197], v[100:103]
	v_mfma_f32_16x16x32_bf16 v[92:95], v[154:157], v[202:205], v[92:95]
	v_mfma_f32_16x16x32_bf16 v[84:87], v[162:165], v[202:205], v[84:87]
	v_mfma_f32_16x16x32_bf16 v[76:79], v[154:157], v[210:213], v[76:79]
	v_mfma_f32_16x16x32_bf16 v[68:71], v[162:165], v[210:213], v[68:71]
	v_mfma_f32_16x16x32_bf16 v[124:127], v[158:161], v[190:193], v[124:127]
	v_mfma_f32_16x16x32_bf16 v[116:119], v[166:169], v[190:193], v[116:119]
	v_mfma_f32_16x16x32_bf16 v[108:111], v[158:161], v[198:201], v[108:111]
	v_mfma_f32_16x16x32_bf16 v[100:103], v[166:169], v[198:201], v[100:103]
	v_mfma_f32_16x16x32_bf16 v[92:95], v[158:161], v[206:209], v[92:95]
	v_mfma_f32_16x16x32_bf16 v[84:87], v[166:169], v[206:209], v[84:87]
	v_mfma_f32_16x16x32_bf16 v[76:79], v[158:161], v[214:217], v[76:79]
	v_mfma_f32_16x16x32_bf16 v[68:71], v[166:169], v[214:217], v[68:71]
	s_setprio 0
	s_setprio 1
	v_mfma_f32_16x16x32_bf16 v[120:123], v[170:173], v[186:189], v[120:123]
	v_mfma_f32_16x16x32_bf16 v[112:115], v[178:181], v[186:189], v[112:115]
	v_mfma_f32_16x16x32_bf16 v[104:107], v[170:173], v[194:197], v[104:107]
	v_mfma_f32_16x16x32_bf16 v[96:99], v[178:181], v[194:197], v[96:99]
	v_mfma_f32_16x16x32_bf16 v[88:91], v[170:173], v[202:205], v[88:91]
	v_mfma_f32_16x16x32_bf16 v[80:83], v[178:181], v[202:205], v[80:83]
	v_mfma_f32_16x16x32_bf16 v[72:75], v[170:173], v[210:213], v[72:75]
	v_mfma_f32_16x16x32_bf16 v[64:67], v[178:181], v[210:213], v[64:67]
	v_mfma_f32_16x16x32_bf16 v[120:123], v[174:177], v[190:193], v[120:123]
	v_mfma_f32_16x16x32_bf16 v[112:115], v[182:185], v[190:193], v[112:115]
	v_mfma_f32_16x16x32_bf16 v[104:107], v[174:177], v[198:201], v[104:107]
	v_mfma_f32_16x16x32_bf16 v[96:99], v[182:185], v[198:201], v[96:99]
	v_mfma_f32_16x16x32_bf16 v[88:91], v[174:177], v[206:209], v[88:91]
	v_mfma_f32_16x16x32_bf16 v[80:83], v[182:185], v[206:209], v[80:83]
	v_mfma_f32_16x16x32_bf16 v[72:75], v[174:177], v[214:217], v[72:75]
	v_mfma_f32_16x16x32_bf16 v[64:67], v[182:185], v[214:217], v[64:67]
	s_setprio 0
	s_barrier
; #define PG8_STAGE(bufoff, gbase, voff) do { _Pragma("unroll") for (int _i = 0; _i < 2; ++_i) \
;         __builtin_amdgcn_global_load_lds((const unsigned*)((const char*)(gbase) + (voff)[_i]), (PG8_LAS unsigned*)(lds + (bufoff) + ldsw + _i * 8192), 16, 0, 0); } while (0)
; #define PG8_LDA(dst, b, h) do { _Pragma("unroll") for (int m = 0; m < 4; ++m) _Pragma("unroll") for (int k = 0; k < 2; ++k) dst[m][k] = *(const PG8_LAS bf16x8*)(lds + PG8_SA(b, h) + aoff + m * 2048 + k * 1024); } while (0)
; #define PG8_MMA(ai, bj, At, Bt) do { __builtin_amdgcn_s_setprio(1); _Pragma("unroll") for (int m = 0; m < 4; ++m) _Pragma("unroll") for (int n = 0; n < 2; ++n) _Pragma("unroll") for (int k = 0; k < 2; ++k) \
;         acc[ai][bj][m][n] = __builtin_amdgcn_mfma_f32_16x16x32_bf16(Bt[n][k], At[m][k], acc[ai][bj][m][n], 0, 0, 0); __builtin_amdgcn_s_setprio(0); } while (0)
; #define PG8_WAIT_V(n) asm volatile("s_waitcnt vmcnt(" #n ")" ::: "memory")
; #define PG8_WAIT_L(n) asm volatile("s_waitcnt lgkmcnt(" #n ")" ::: "memory")
; #define PG8_BAR __builtin_amdgcn_s_barrier()
; #define PG8_SCHED __builtin_amdgcn_sched_barrier(0)
; template <class Epi, class Sched, bool ALIGN_EPI = false, bool SP2 = false>
; __device__ __forceinline__ void gemm_phase(PG8_LAS unsigned char* lds, const Gemm g, const Sched& S, const Epi& E) {
;     ...
;             PG8_LDA(At, 1, 1); PG8_STAGE(PG8_SB(1, 0), b3, voffB); PG8_STAGE(PG8_SB(1, 1), b3 + hstep, voffB); PG8_STAGE(PG8_SA(1, 0), a3, voffA);
;             PG8_WAIT_V(8); PG8_WAIT_L(0); PG8_BAR; PG8_MMA(1, 0, At, B0); PG8_MMA(1, 1, At, B1); PG8_BAR; PG8_SCHED;
	s_add_i32 s38, s67, s43
	v_lshl_add_u64 v[146:147], v[146:147], 0, s[18:19]
	s_mov_b32 m0, s38
	ds_read_b128 v[186:189], v153 offset:49152
	ds_read_b128 v[190:193], v153 offset:50176
	ds_read_b128 v[194:197], v153 offset:51200
	ds_read_b128 v[198:201], v153 offset:52224
	ds_read_b128 v[202:205], v153 offset:53248
	ds_read_b128 v[206:209], v153 offset:54272
	ds_read_b128 v[210:213], v153 offset:55296
	ds_read_b128 v[214:217], v153 offset:56320
	global_load_lds_dwordx4 v[146:147], off
	v_lshl_add_u64 v[146:147], v[218:219], 0, s[18:19]
	s_add_i32 m0, s38, 0x2000
	s_add_i32 s38, s68, s43
	global_load_lds_dwordx4 v[146:147], off
	v_lshl_add_u64 v[146:147], v[220:221], 0, s[18:19]
	s_mov_b32 m0, s38
	s_nop 0
	global_load_lds_dwordx4 v[146:147], off
	v_lshl_add_u64 v[146:147], v[222:223], 0, s[18:19]
	s_add_i32 m0, s38, 0x2000
	s_nop 0
	global_load_lds_dwordx4 v[146:147], off
	v_lshl_add_u64 v[146:147], v[224:225], 0, s[18:19]
	s_mov_b32 m0, s51
	s_nop 0
	global_load_lds_dwordx4 v[146:147], off
	v_lshl_add_u64 v[146:147], v[226:227], 0, s[18:19]
	s_mov_b32 m0, s52
	s_nop 0
	global_load_lds_dwordx4 v[146:147], off
	s_waitcnt vmcnt(8)
	s_waitcnt lgkmcnt(0)
	s_barrier
	s_setprio 1
	s_waitcnt lgkmcnt(0)
	v_mfma_f32_16x16x32_bf16 v[60:63], v[154:157], v[186:189], v[60:63]
	v_mfma_f32_16x16x32_bf16 v[52:55], v[162:165], v[186:189], v[52:55]
	v_mfma_f32_16x16x32_bf16 v[44:47], v[154:157], v[194:197], v[44:47]
	v_mfma_f32_16x16x32_bf16 v[36:39], v[162:165], v[194:197], v[36:39]
	v_mfma_f32_16x16x32_bf16 v[28:31], v[154:157], v[202:205], v[28:31]
	v_mfma_f32_16x16x32_bf16 v[20:23], v[162:165], v[202:205], v[20:23]
	v_mfma_f32_16x16x32_bf16 v[12:15], v[154:157], v[210:213], v[12:15]
	v_mfma_f32_16x16x32_bf16 v[4:7], v[162:165], v[210:213], v[4:7]
	v_mfma_f32_16x16x32_bf16 v[60:63], v[158:161], v[190:193], v[60:63]
	v_mfma_f32_16x16x32_bf16 v[52:55], v[166:169], v[190:193], v[52:55]
	v_mfma_f32_16x16x32_bf16 v[44:47], v[158:161], v[198:201], v[44:47]
	v_mfma_f32_16x16x32_bf16 v[36:39], v[166:169], v[198:201], v[36:39]
	v_mfma_f32_16x16x32_bf16 v[28:31], v[158:161], v[206:209], v[28:31]
	v_mfma_f32_16x16x32_bf16 v[20:23], v[166:169], v[206:209], v[20:23]
	v_mfma_f32_16x16x32_bf16 v[12:15], v[158:161], v[214:217], v[12:15]
	v_mfma_f32_16x16x32_bf16 v[4:7], v[166:169], v[214:217], v[4:7]
	s_setprio 0
	s_setprio 1
	v_mfma_f32_16x16x32_bf16 v[56:59], v[170:173], v[186:189], v[56:59]
	v_mfma_f32_16x16x32_bf16 v[48:51], v[178:181], v[186:189], v[48:51]
	v_mfma_f32_16x16x32_bf16 v[40:43], v[170:173], v[194:197], v[40:43]
	v_mfma_f32_16x16x32_bf16 v[32:35], v[178:181], v[194:197], v[32:35]
	v_mfma_f32_16x16x32_bf16 v[24:27], v[170:173], v[202:205], v[24:27]
	v_mfma_f32_16x16x32_bf16 v[16:19], v[178:181], v[202:205], v[16:19]
	v_mfma_f32_16x16x32_bf16 v[8:11], v[170:173], v[210:213], v[8:11]
	v_mfma_f32_16x16x32_bf16 v[0:3], v[178:181], v[210:213], v[0:3]
	v_mfma_f32_16x16x32_bf16 v[56:59], v[174:177], v[190:193], v[56:59]
	v_mfma_f32_16x16x32_bf16 v[48:51], v[182:185], v[190:193], v[48:51]
	v_mfma_f32_16x16x32_bf16 v[40:43], v[174:177], v[198:201], v[40:43]
	v_mfma_f32_16x16x32_bf16 v[32:35], v[182:185], v[198:201], v[32:35]
	v_mfma_f32_16x16x32_bf16 v[24:27], v[174:177], v[206:209], v[24:27]
	v_mfma_f32_16x16x32_bf16 v[16:19], v[182:185], v[206:209], v[16:19]
	v_mfma_f32_16x16x32_bf16 v[8:11], v[174:177], v[214:217], v[8:11]
	v_mfma_f32_16x16x32_bf16 v[0:3], v[182:185], v[214:217], v[0:3]
	s_setprio 0
	s_add_u32 s64, s64, 0x100
	s_addc_u32 s65, s65, 0
	s_add_u32 s36, s36, 0x100
	s_addc_u32 s37, s37, 0
	s_cmp_ge_i32 s66, s53
	s_mov_b32 s38, s66
	s_barrier
	s_cbranch_scc0 .LBB0_1406

; #define PG8_STAGE(bufoff, gbase, voff) do { _Pragma("unroll") for (int _i = 0; _i < 2; ++_i) \
;         __builtin_amdgcn_global_load_lds((const unsigned*)((const char*)(gbase) + (voff)[_i]), (PG8_LAS unsigned*)(lds + (bufoff) + ldsw + _i * 8192), 16, 0, 0); } while (0)
; #define PG8_LDA(dst, b, h) do { _Pragma("unroll") for (int m = 0; m < 4; ++m) _Pragma("unroll") for (int k = 0; k < 2; ++k) dst[m][k] = *(const PG8_LAS bf16x8*)(lds + PG8_SA(b, h) + aoff + m * 2048 + k * 1024); } while (0)
; #define PG8_LDB(dst, b, h) do { _Pragma("unroll") for (int n = 0; n < 2; ++n) _Pragma("unroll") for (int k = 0; k < 2; ++k) dst[n][k] = *(const PG8_LAS bf16x8*)(lds + PG8_SB(b, h) + boff + n * 2048 + k * 1024); } while (0)
; #define PG8_MMA(ai, bj, At, Bt) do { __builtin_amdgcn_s_setprio(1); _Pragma("unroll") for (int m = 0; m < 4; ++m) _Pragma("unroll") for (int n = 0; n < 2; ++n) _Pragma("unroll") for (int k = 0; k < 2; ++k) \
;         acc[ai][bj][m][n] = __builtin_amdgcn_mfma_f32_16x16x32_bf16(Bt[n][k], At[m][k], acc[ai][bj][m][n], 0, 0, 0); __builtin_amdgcn_s_setprio(0); } while (0)
; #define PG8_WAIT_V(n) asm volatile("s_waitcnt vmcnt(" #n ")" ::: "memory")
; #define PG8_WAIT_L(n) asm volatile("s_waitcnt lgkmcnt(" #n ")" ::: "memory")
; #define PG8_BAR __builtin_amdgcn_s_barrier()
; #define PG8_SCHED __builtin_amdgcn_sched_barrier(0)
; template <class Epi, class Sched, bool ALIGN_EPI = false, bool SP2 = false>
; __device__ __forceinline__ void gemm_phase(PG8_LAS unsigned char* lds, const Gemm g, const Sched& S, const Epi& E) {
;     ...
;         for (int t = 0; t < nt; t += 2) {
;             const bool last = (t == nt - 2);
;             const char* a1 = cA + (size_t)(t + 1) * kstep;
;             const char* a2 = last ? nA : cA + (size_t)(t + 2) * kstep; const char* b2 = last ? nB : cB + (size_t)(t + 2) * kstep;
;             const char* a3 = a2 + kstep; const char* b3 = b2 + kstep;
;             if (last && has_next) S.a_ready(nxt);
;             if constexpr (SP2) {
;             PG8_LDB(B0, 0, 0); PG8_LDB(B1, 0, 1); PG8_SCHED; PG8_LDA(At, 0, 0); PG8_STAGE(PG8_SA(1, 1), a1 + hstep, voffA);
;             PG8_WAIT_V(8); PG8_WAIT_L(0); PG8_BAR; PG8_MMA(0, 0, At, B0); PG8_MMA(0, 1, At, B1); PG8_BAR; PG8_SCHED;
;             PG8_LDA(At, 0, 1); PG8_STAGE(PG8_SB(0, 0), b2, voffB); PG8_STAGE(PG8_SB(0, 1), b2 + hstep, voffB); PG8_STAGE(PG8_SA(0, 0), a2, voffA);
.LBB0_1486:
	v_add_u32_e32 v5, s58, v152
	ds_read_b128 v[154:157], v5
	ds_read_b128 v[158:161], v5 offset:1024
	ds_read_b128 v[164:167], v5 offset:2048
	ds_read_b128 v[168:171], v5 offset:3072
	v_add_u32_e32 v5, s59, v152
	ds_read_b128 v[172:175], v5
	ds_read_b128 v[176:179], v5 offset:1024
	ds_read_b128 v[180:183], v5 offset:2048
	ds_read_b128 v[184:187], v5 offset:3072
	s_add_i32 s66, s38, 2
	s_add_u32 s67, s36, 0x80
	s_addc_u32 s39, s37, 0
	s_cmp_eq_u32 s57, s38
	s_cselect_b32 s38, s6, s67
	s_cselect_b32 s39, s7, s39
	s_cselect_b32 s69, s35, s65
	s_cselect_b32 s68, s34, s64
	v_lshl_add_u64 v[6:7], s[36:37], 0, v[146:147]
	s_add_i32 m0, s49, 0xc000
	ds_read_b128 v[188:191], v153
	ds_read_b128 v[192:195], v153 offset:1024
	ds_read_b128 v[196:199], v153 offset:2048
	ds_read_b128 v[200:203], v153 offset:3072
	ds_read_b128 v[204:207], v153 offset:4096
	ds_read_b128 v[208:211], v153 offset:5120
	ds_read_b128 v[212:215], v153 offset:6144
	ds_read_b128 v[216:219], v153 offset:7168
	global_load_lds_dwordx4 v[6:7], off
	v_lshl_add_u64 v[6:7], s[36:37], 0, v[142:143]
	s_add_i32 m0, s49, 0xe000
	s_nop 0
	global_load_lds_dwordx4 v[6:7], off
	s_waitcnt vmcnt(8)
	s_waitcnt lgkmcnt(0)
	s_barrier
	s_setprio 1
	s_waitcnt lgkmcnt(0)
	v_mfma_f32_16x16x32_bf16 v[80:83], v[154:157], v[188:191], v[80:83]
	v_mfma_f32_16x16x32_bf16 v[44:47], v[164:167], v[188:191], v[44:47]
	v_mfma_f32_16x16x32_bf16 v[88:91], v[154:157], v[196:199], v[88:91]
	v_mfma_f32_16x16x32_bf16 v[56:59], v[164:167], v[196:199], v[56:59]
	v_mfma_f32_16x16x32_bf16 v[100:103], v[154:157], v[204:207], v[100:103]
	v_mfma_f32_16x16x32_bf16 v[68:71], v[164:167], v[204:207], v[68:71]
	v_mfma_f32_16x16x32_bf16 v[104:107], v[154:157], v[212:215], v[104:107]
	v_mfma_f32_16x16x32_bf16 v[72:75], v[164:167], v[212:215], v[72:75]
	v_mfma_f32_16x16x32_bf16 v[80:83], v[158:161], v[192:195], v[80:83]
	v_mfma_f32_16x16x32_bf16 v[44:47], v[168:171], v[192:195], v[44:47]
	v_mfma_f32_16x16x32_bf16 v[88:91], v[158:161], v[200:203], v[88:91]
	v_mfma_f32_16x16x32_bf16 v[56:59], v[168:171], v[200:203], v[56:59]
	v_mfma_f32_16x16x32_bf16 v[100:103], v[158:161], v[208:211], v[100:103]
	v_mfma_f32_16x16x32_bf16 v[68:71], v[168:171], v[208:211], v[68:71]
	v_mfma_f32_16x16x32_bf16 v[104:107], v[158:161], v[216:219], v[104:107]
	v_mfma_f32_16x16x32_bf16 v[72:75], v[168:171], v[216:219], v[72:75]
	s_setprio 0
	s_setprio 1
	v_mfma_f32_16x16x32_bf16 v[20:23], v[172:175], v[188:191], v[20:23]
	v_mfma_f32_16x16x32_bf16 v[132:135], v[180:183], v[188:191], v[132:135]
	v_mfma_f32_16x16x32_bf16 v[28:31], v[172:175], v[196:199], v[28:31]
	v_mfma_f32_16x16x32_bf16 v[6:9], v[180:183], v[196:199], v[8:11]
	v_mfma_f32_16x16x32_bf16 v[36:39], v[172:175], v[204:207], v[36:39]
	v_mfma_f32_16x16x32_bf16 v[10:13], v[180:183], v[204:207], v[12:15]
	v_mfma_f32_16x16x32_bf16 v[40:43], v[172:175], v[212:215], v[40:43]
	v_mfma_f32_16x16x32_bf16 v[16:19], v[180:183], v[212:215], v[16:19]
	v_mfma_f32_16x16x32_bf16 v[20:23], v[176:179], v[192:195], v[20:23]
	v_mfma_f32_16x16x32_bf16 v[132:135], v[184:187], v[192:195], v[132:135]
	v_mfma_f32_16x16x32_bf16 v[28:31], v[176:179], v[200:203], v[28:31]
	v_mfma_f32_16x16x32_bf16 v[6:9], v[184:187], v[200:203], v[6:9]
	v_mfma_f32_16x16x32_bf16 v[36:39], v[176:179], v[208:211], v[36:39]
	v_mfma_f32_16x16x32_bf16 v[12:15], v[184:187], v[208:211], v[10:13]
	v_mfma_f32_16x16x32_bf16 v[40:43], v[176:179], v[216:219], v[40:43]
	v_mfma_f32_16x16x32_bf16 v[16:19], v[184:187], v[216:219], v[16:19]
	s_setprio 0
	s_barrier
	s_add_i32 s67, s58, s48
	v_lshl_add_u64 v[220:221], s[68:69], 0, v[138:139]
	s_mov_b32 m0, s67
	ds_read_b128 v[188:191], v153 offset:16384
	ds_read_b128 v[192:195], v153 offset:17408
	ds_read_b128 v[196:199], v153 offset:18432
	ds_read_b128 v[200:203], v153 offset:19456
	ds_read_b128 v[204:207], v153 offset:20480
	ds_read_b128 v[208:211], v153 offset:21504
	ds_read_b128 v[212:215], v153 offset:22528
	ds_read_b128 v[216:219], v153 offset:23552
	global_load_lds_dwordx4 v[220:221], off
	s_add_i32 m0, s67, 0x2000
	v_lshl_add_u64 v[222:223], s[68:69], 0, v[140:141]
	s_add_u32 s68, s68, s12
	s_addc_u32 s69, s69, s13
	s_add_i32 s67, s59, s48
	global_load_lds_dwordx4 v[222:223], off
	v_lshl_add_u64 v[224:225], s[68:69], 0, v[138:139]
	s_mov_b32 m0, s67
	v_lshl_add_u64 v[226:227], s[68:69], 0, v[140:141]
	global_load_lds_dwordx4 v[224:225], off
	s_add_i32 m0, s67, 0x2000
	v_lshl_add_u64 v[228:229], s[38:39], 0, v[138:139]
	global_load_lds_dwordx4 v[226:227], off
	s_mov_b32 m0, s49
	v_lshl_add_u64 v[230:231], s[38:39], 0, v[140:141]
	global_load_lds_dwordx4 v[228:229], off
	s_mov_b32 m0, s50
	s_nop 0
	global_load_lds_dwordx4 v[230:231], off
	s_waitcnt vmcnt(8)
	s_waitcnt lgkmcnt(0)
	s_barrier
; #define PG8_STAGE(bufoff, gbase, voff) do { _Pragma("unroll") for (int _i = 0; _i < 2; ++_i) \
;         __builtin_amdgcn_global_load_lds((const unsigned*)((const char*)(gbase) + (voff)[_i]), (PG8_LAS unsigned*)(lds + (bufoff) + ldsw + _i * 8192), 16, 0, 0); } while (0)
; #define PG8_LDA(dst, b, h) do { _Pragma("unroll") for (int m = 0; m < 4; ++m) _Pragma("unroll") for (int k = 0; k < 2; ++k) dst[m][k] = *(const PG8_LAS bf16x8*)(lds + PG8_SA(b, h) + aoff + m * 2048 + k * 1024); } while (0)
; #define PG8_LDB(dst, b, h) do { _Pragma("unroll") for (int n = 0; n < 2; ++n) _Pragma("unroll") for (int k = 0; k < 2; ++k) dst[n][k] = *(const PG8_LAS bf16x8*)(lds + PG8_SB(b, h) + boff + n * 2048 + k * 1024); } while (0)
; #define PG8_MMA(ai, bj, At, Bt) do { __builtin_amdgcn_s_setprio(1); _Pragma("unroll") for (int m = 0; m < 4; ++m) _Pragma("unroll") for (int n = 0; n < 2; ++n) _Pragma("unroll") for (int k = 0; k < 2; ++k) \
;         acc[ai][bj][m][n] = __builtin_amdgcn_mfma_f32_16x16x32_bf16(Bt[n][k], At[m][k], acc[ai][bj][m][n], 0, 0, 0); __builtin_amdgcn_s_setprio(0); } while (0)
; #define PG8_WAIT_V(n) asm volatile("s_waitcnt vmcnt(" #n ")" ::: "memory")
; #define PG8_WAIT_L(n) asm volatile("s_waitcnt lgkmcnt(" #n ")" ::: "memory")
; #define PG8_BAR __builtin_amdgcn_s_barrier()
; #define PG8_SCHED __builtin_amdgcn_sched_barrier(0)
; template <class Epi, class Sched, bool ALIGN_EPI = false, bool SP2 = false>
; __device__ __forceinline__ void gemm_phase(PG8_LAS unsigned char* lds, const Gemm g, const Sched& S, const Epi& E) {
;     ...
;             PG8_WAIT_V(8); PG8_WAIT_L(0); PG8_BAR; PG8_MMA(1, 0, At, B0); PG8_MMA(1, 1, At, B1); PG8_BAR; PG8_SCHED;
;             PG8_LDB(B0, 1, 0); PG8_LDB(B1, 1, 1); PG8_SCHED; PG8_LDA(At, 1, 0); PG8_STAGE(PG8_SA(0, 1), a2 + hstep, voffA);
;             PG8_WAIT_V(8); PG8_WAIT_L(0); PG8_BAR; PG8_MMA(0, 0, At, B0); PG8_MMA(0, 1, At, B1); PG8_BAR; PG8_SCHED;
	s_setprio 1
	s_waitcnt lgkmcnt(0)
	v_mfma_f32_16x16x32_bf16 v[112:115], v[154:157], v[188:191], v[112:115]
	v_mfma_f32_16x16x32_bf16 v[84:87], v[164:167], v[188:191], v[84:87]
	v_mfma_f32_16x16x32_bf16 v[120:123], v[154:157], v[196:199], v[120:123]
	v_mfma_f32_16x16x32_bf16 v[96:99], v[164:167], v[196:199], v[96:99]
	v_mfma_f32_16x16x32_bf16 v[128:131], v[154:157], v[204:207], v[128:131]
	v_mfma_f32_16x16x32_bf16 v[108:111], v[164:167], v[204:207], v[108:111]
	v_mfma_f32_16x16x32_bf16 v[124:127], v[154:157], v[212:215], v[124:127]
	v_mfma_f32_16x16x32_bf16 v[116:119], v[164:167], v[212:215], v[116:119]
	v_mfma_f32_16x16x32_bf16 v[112:115], v[158:161], v[192:195], v[112:115]
	v_mfma_f32_16x16x32_bf16 v[84:87], v[168:171], v[192:195], v[84:87]
	v_mfma_f32_16x16x32_bf16 v[120:123], v[158:161], v[200:203], v[120:123]
	v_mfma_f32_16x16x32_bf16 v[96:99], v[168:171], v[200:203], v[96:99]
	v_mfma_f32_16x16x32_bf16 v[128:131], v[158:161], v[208:211], v[128:131]
	v_mfma_f32_16x16x32_bf16 v[108:111], v[168:171], v[208:211], v[108:111]
	v_mfma_f32_16x16x32_bf16 v[124:127], v[158:161], v[216:219], v[124:127]
	v_mfma_f32_16x16x32_bf16 v[116:119], v[168:171], v[216:219], v[116:119]
	s_setprio 0
	s_setprio 1
	v_mfma_f32_16x16x32_bf16 v[52:55], v[172:175], v[188:191], v[52:55]
	v_mfma_f32_16x16x32_bf16 v[24:27], v[180:183], v[188:191], v[24:27]
	v_mfma_f32_16x16x32_bf16 v[60:63], v[172:175], v[196:199], v[60:63]
	v_mfma_f32_16x16x32_bf16 v[32:35], v[180:183], v[196:199], v[32:35]
	v_mfma_f32_16x16x32_bf16 v[76:79], v[172:175], v[204:207], v[76:79]
	v_mfma_f32_16x16x32_bf16 v[48:51], v[180:183], v[204:207], v[48:51]
	v_mfma_f32_16x16x32_bf16 v[92:95], v[172:175], v[212:215], v[92:95]
	v_mfma_f32_16x16x32_bf16 v[64:67], v[180:183], v[212:215], v[64:67]
	v_mfma_f32_16x16x32_bf16 v[52:55], v[176:179], v[192:195], v[52:55]
	v_mfma_f32_16x16x32_bf16 v[24:27], v[184:187], v[192:195], v[24:27]
	v_mfma_f32_16x16x32_bf16 v[60:63], v[176:179], v[200:203], v[60:63]
	v_mfma_f32_16x16x32_bf16 v[32:35], v[184:187], v[200:203], v[32:35]
	v_mfma_f32_16x16x32_bf16 v[76:79], v[176:179], v[208:211], v[76:79]
	v_mfma_f32_16x16x32_bf16 v[48:51], v[184:187], v[208:211], v[48:51]
	v_mfma_f32_16x16x32_bf16 v[92:95], v[176:179], v[216:219], v[92:95]
	v_mfma_f32_16x16x32_bf16 v[64:67], v[184:187], v[216:219], v[64:67]
	s_setprio 0
	s_barrier
	s_add_i32 s67, 0, 0x18000
	v_add_u32_e32 v5, s67, v152
	s_add_i32 s68, 0, 0x1c000
	ds_read_b128 v[154:157], v5
	ds_read_b128 v[158:161], v5 offset:1024
	ds_read_b128 v[164:167], v5 offset:2048
	ds_read_b128 v[168:171], v5 offset:3072
	v_add_u32_e32 v5, s68, v152
	ds_read_b128 v[172:175], v5
	ds_read_b128 v[176:179], v5 offset:1024
	ds_read_b128 v[180:183], v5 offset:2048
	ds_read_b128 v[184:187], v5 offset:3072
	s_add_u32 s38, s38, s12
	s_addc_u32 s39, s39, s13
	s_mov_b32 m0, s51
	v_lshl_add_u64 v[10:11], s[38:39], 0, v[138:139]
	ds_read_b128 v[188:191], v153 offset:32768
	ds_read_b128 v[192:195], v153 offset:33792
	ds_read_b128 v[196:199], v153 offset:34816
	ds_read_b128 v[200:203], v153 offset:35840
	ds_read_b128 v[204:207], v153 offset:36864
	ds_read_b128 v[208:211], v153 offset:37888
	ds_read_b128 v[212:215], v153 offset:38912
	ds_read_b128 v[216:219], v153 offset:39936
	global_load_lds_dwordx4 v[10:11], off
	v_lshl_add_u64 v[10:11], s[38:39], 0, v[140:141]
	s_mov_b32 m0, s52
	s_nop 0
	global_load_lds_dwordx4 v[10:11], off
	s_waitcnt vmcnt(8)
	s_waitcnt lgkmcnt(0)
	s_barrier
	s_setprio 1
	s_waitcnt lgkmcnt(0)
	v_mfma_f32_16x16x32_bf16 v[80:83], v[154:157], v[188:191], v[80:83]
	v_mfma_f32_16x16x32_bf16 v[44:47], v[164:167], v[188:191], v[44:47]
	v_mfma_f32_16x16x32_bf16 v[88:91], v[154:157], v[196:199], v[88:91]
	v_mfma_f32_16x16x32_bf16 v[56:59], v[164:167], v[196:199], v[56:59]
	v_mfma_f32_16x16x32_bf16 v[100:103], v[154:157], v[204:207], v[100:103]
	v_mfma_f32_16x16x32_bf16 v[68:71], v[164:167], v[204:207], v[68:71]
	v_mfma_f32_16x16x32_bf16 v[104:107], v[154:157], v[212:215], v[104:107]
	v_mfma_f32_16x16x32_bf16 v[72:75], v[164:167], v[212:215], v[72:75]
	v_mfma_f32_16x16x32_bf16 v[80:83], v[158:161], v[192:195], v[80:83]
	v_mfma_f32_16x16x32_bf16 v[44:47], v[168:171], v[192:195], v[44:47]
	v_mfma_f32_16x16x32_bf16 v[88:91], v[158:161], v[200:203], v[88:91]
	v_mfma_f32_16x16x32_bf16 v[56:59], v[168:171], v[200:203], v[56:59]
	v_mfma_f32_16x16x32_bf16 v[100:103], v[158:161], v[208:211], v[100:103]
	v_mfma_f32_16x16x32_bf16 v[68:71], v[168:171], v[208:211], v[68:71]
	v_mfma_f32_16x16x32_bf16 v[104:107], v[158:161], v[216:219], v[104:107]
	v_mfma_f32_16x16x32_bf16 v[72:75], v[168:171], v[216:219], v[72:75]
	s_setprio 0
	s_setprio 1
	v_mfma_f32_16x16x32_bf16 v[20:23], v[172:175], v[188:191], v[20:23]
	v_mfma_f32_16x16x32_bf16 v[132:135], v[180:183], v[188:191], v[132:135]
	v_mfma_f32_16x16x32_bf16 v[28:31], v[172:175], v[196:199], v[28:31]
	v_mfma_f32_16x16x32_bf16 v[6:9], v[180:183], v[196:199], v[6:9]
	v_mfma_f32_16x16x32_bf16 v[36:39], v[172:175], v[204:207], v[36:39]
	v_mfma_f32_16x16x32_bf16 v[12:15], v[180:183], v[204:207], v[12:15]
	v_mfma_f32_16x16x32_bf16 v[40:43], v[172:175], v[212:215], v[40:43]
	v_mfma_f32_16x16x32_bf16 v[16:19], v[180:183], v[212:215], v[16:19]
	v_mfma_f32_16x16x32_bf16 v[20:23], v[176:179], v[192:195], v[20:23]
	v_mfma_f32_16x16x32_bf16 v[132:135], v[184:187], v[192:195], v[132:135]
	v_mfma_f32_16x16x32_bf16 v[28:31], v[176:179], v[200:203], v[28:31]
	v_mfma_f32_16x16x32_bf16 v[8:11], v[184:187], v[200:203], v[6:9]
	v_mfma_f32_16x16x32_bf16 v[36:39], v[176:179], v[208:211], v[36:39]
	v_mfma_f32_16x16x32_bf16 v[12:15], v[184:187], v[208:211], v[12:15]
	v_mfma_f32_16x16x32_bf16 v[40:43], v[176:179], v[216:219], v[40:43]
	v_mfma_f32_16x16x32_bf16 v[16:19], v[184:187], v[216:219], v[16:19]
	s_setprio 0
	s_barrier
; #define PG8_STAGE(bufoff, gbase, voff) do { _Pragma("unroll") for (int _i = 0; _i < 2; ++_i) \
;         __builtin_amdgcn_global_load_lds((const unsigned*)((const char*)(gbase) + (voff)[_i]), (PG8_LAS unsigned*)(lds + (bufoff) + ldsw + _i * 8192), 16, 0, 0); } while (0)
; #define PG8_LDA(dst, b, h) do { _Pragma("unroll") for (int m = 0; m < 4; ++m) _Pragma("unroll") for (int k = 0; k < 2; ++k) dst[m][k] = *(const PG8_LAS bf16x8*)(lds + PG8_SA(b, h) + aoff + m * 2048 + k * 1024); } while (0)
; #define PG8_MMA(ai, bj, At, Bt) do { __builtin_amdgcn_s_setprio(1); _Pragma("unroll") for (int m = 0; m < 4; ++m) _Pragma("unroll") for (int n = 0; n < 2; ++n) _Pragma("unroll") for (int k = 0; k < 2; ++k) \
;         acc[ai][bj][m][n] = __builtin_amdgcn_mfma_f32_16x16x32_bf16(Bt[n][k], At[m][k], acc[ai][bj][m][n], 0, 0, 0); __builtin_amdgcn_s_setprio(0); } while (0)
; #define PG8_WAIT_V(n) asm volatile("s_waitcnt vmcnt(" #n ")" ::: "memory")
; #define PG8_WAIT_L(n) asm volatile("s_waitcnt lgkmcnt(" #n ")" ::: "memory")
; #define PG8_BAR __builtin_amdgcn_s_barrier()
; #define PG8_SCHED __builtin_amdgcn_sched_barrier(0)
; template <class Epi, class Sched, bool ALIGN_EPI = false, bool SP2 = false>
; __device__ __forceinline__ void gemm_phase(PG8_LAS unsigned char* lds, const Gemm g, const Sched& S, const Epi& E) {
;     ...
;             PG8_LDA(At, 1, 1); PG8_STAGE(PG8_SB(1, 0), b3, voffB); PG8_STAGE(PG8_SB(1, 1), b3 + hstep, voffB); PG8_STAGE(PG8_SA(1, 0), a3, voffA);
;             PG8_WAIT_V(8); PG8_WAIT_L(0); PG8_BAR; PG8_MMA(1, 0, At, B0); PG8_MMA(1, 1, At, B1); PG8_BAR; PG8_SCHED;
	s_add_i32 s38, s67, s48
	v_lshl_add_u64 v[6:7], v[220:221], 0, s[20:21]
	s_mov_b32 m0, s38
	ds_read_b128 v[188:191], v153 offset:49152
	ds_read_b128 v[192:195], v153 offset:50176
	ds_read_b128 v[196:199], v153 offset:51200
	ds_read_b128 v[200:203], v153 offset:52224
	ds_read_b128 v[204:207], v153 offset:53248
	ds_read_b128 v[208:211], v153 offset:54272
	ds_read_b128 v[212:215], v153 offset:55296
	ds_read_b128 v[216:219], v153 offset:56320
	global_load_lds_dwordx4 v[6:7], off
	v_lshl_add_u64 v[6:7], v[222:223], 0, s[20:21]
	s_add_i32 m0, s38, 0x2000
	s_add_i32 s38, s68, s48
	global_load_lds_dwordx4 v[6:7], off
	v_lshl_add_u64 v[6:7], v[224:225], 0, s[20:21]
	s_mov_b32 m0, s38
	s_nop 0
	global_load_lds_dwordx4 v[6:7], off
	v_lshl_add_u64 v[6:7], v[226:227], 0, s[20:21]
	s_add_i32 m0, s38, 0x2000
	s_nop 0
	global_load_lds_dwordx4 v[6:7], off
	v_lshl_add_u64 v[6:7], v[228:229], 0, s[20:21]
	s_mov_b32 m0, s54
	s_nop 0
	global_load_lds_dwordx4 v[6:7], off
	v_lshl_add_u64 v[6:7], v[230:231], 0, s[20:21]
	s_mov_b32 m0, s55
	s_nop 0
	global_load_lds_dwordx4 v[6:7], off
	s_waitcnt vmcnt(8)
	s_waitcnt lgkmcnt(0)
	s_barrier
	s_setprio 1
	s_waitcnt lgkmcnt(0)
	v_mfma_f32_16x16x32_bf16 v[112:115], v[154:157], v[188:191], v[112:115]
	v_mfma_f32_16x16x32_bf16 v[84:87], v[164:167], v[188:191], v[84:87]
	v_mfma_f32_16x16x32_bf16 v[120:123], v[154:157], v[196:199], v[120:123]
	v_mfma_f32_16x16x32_bf16 v[96:99], v[164:167], v[196:199], v[96:99]
	v_mfma_f32_16x16x32_bf16 v[128:131], v[154:157], v[204:207], v[128:131]
	v_mfma_f32_16x16x32_bf16 v[108:111], v[164:167], v[204:207], v[108:111]
	v_mfma_f32_16x16x32_bf16 v[124:127], v[154:157], v[212:215], v[124:127]
	v_mfma_f32_16x16x32_bf16 v[116:119], v[164:167], v[212:215], v[116:119]
	v_mfma_f32_16x16x32_bf16 v[112:115], v[158:161], v[192:195], v[112:115]
	v_mfma_f32_16x16x32_bf16 v[84:87], v[168:171], v[192:195], v[84:87]
	v_mfma_f32_16x16x32_bf16 v[120:123], v[158:161], v[200:203], v[120:123]
	v_mfma_f32_16x16x32_bf16 v[96:99], v[168:171], v[200:203], v[96:99]
	v_mfma_f32_16x16x32_bf16 v[128:131], v[158:161], v[208:211], v[128:131]
	v_mfma_f32_16x16x32_bf16 v[108:111], v[168:171], v[208:211], v[108:111]
	v_mfma_f32_16x16x32_bf16 v[124:127], v[158:161], v[216:219], v[124:127]
	v_mfma_f32_16x16x32_bf16 v[116:119], v[168:171], v[216:219], v[116:119]
	s_setprio 0
	s_setprio 1
	v_mfma_f32_16x16x32_bf16 v[52:55], v[172:175], v[188:191], v[52:55]
	v_mfma_f32_16x16x32_bf16 v[24:27], v[180:183], v[188:191], v[24:27]
	v_mfma_f32_16x16x32_bf16 v[60:63], v[172:175], v[196:199], v[60:63]
	v_mfma_f32_16x16x32_bf16 v[32:35], v[180:183], v[196:199], v[32:35]
	v_mfma_f32_16x16x32_bf16 v[76:79], v[172:175], v[204:207], v[76:79]
	v_mfma_f32_16x16x32_bf16 v[48:51], v[180:183], v[204:207], v[48:51]
	v_mfma_f32_16x16x32_bf16 v[92:95], v[172:175], v[212:215], v[92:95]
	v_mfma_f32_16x16x32_bf16 v[64:67], v[180:183], v[212:215], v[64:67]
	v_mfma_f32_16x16x32_bf16 v[52:55], v[176:179], v[192:195], v[52:55]
	v_mfma_f32_16x16x32_bf16 v[24:27], v[184:187], v[192:195], v[24:27]
	v_mfma_f32_16x16x32_bf16 v[60:63], v[176:179], v[200:203], v[60:63]
	v_mfma_f32_16x16x32_bf16 v[32:35], v[184:187], v[200:203], v[32:35]
	v_mfma_f32_16x16x32_bf16 v[76:79], v[176:179], v[208:211], v[76:79]
	v_mfma_f32_16x16x32_bf16 v[48:51], v[184:187], v[208:211], v[48:51]
	v_mfma_f32_16x16x32_bf16 v[92:95], v[176:179], v[216:219], v[92:95]
	v_mfma_f32_16x16x32_bf16 v[64:67], v[184:187], v[216:219], v[64:67]
	s_setprio 0
	s_add_u32 s64, s64, 0x100
	s_addc_u32 s65, s65, 0
	s_add_u32 s36, s36, 0x100
	s_addc_u32 s37, s37, 0
	s_cmp_ge_i32 s66, s56
	s_mov_b32 s38, s66
	s_barrier
	s_cbranch_scc0 .LBB0_1486
